# hand-rewritten pipelined up-GEMM epilogue (packed f32, saddr stores) + nt (streaming) policy on in-proj/out-proj/down epilogue row stores
# speedup vs baseline: 1.0086x; 1.0086x over previous
; #define PG8_LAS __attribute__((address_space(3)))
;     __device__ __forceinline__ void operator()(const f32x4 (&acc)[2][2][4][2], const Unit& u, int wr, int wc, int fr, int fq, PG8_LAS float* stash, int par, PG8_LAS unsigned char* stg, const Unit& un) const {
;     ...
;                     for (int i = 0; i < 2; ++i) { const int c = fq * 16 + fr + 64 * i, rr = c >> 3, pc = c & 7;
;                         const u32x4 w = *(const PG8_LAS u32x4*)(stg + rr * 144 + pc * 16);
;                         const int rowc = row - fr + rr, posc = rowc & 4095;
;                         if (kind == 1 || kind == 2) {
;                             bf16_t* dst = (kind == 1) ? kd : vt;
;                             if (odd) *(u32x4*)(dst + (size_t)(b * 4 + wc) * (4096 * 64) + (size_t)((posc & 15) * 256 + (posc >> 4)) * 64 + pc * 8) = w;
;                             else     *(u32x4*)(dst + (size_t)(b * 2 + (wc & 1)) * (4096 * 64) + (size_t)posc * 64 + pc * 8) = w;
;                         } else {
;                             *(u32x4*)(proj + (size_t)rowc * ldp + u.pn * BM + wc * 64 + pc * 8) = w;
;                         }
.LBB0_160:
	v_lshlrev_b32_e32 v0, 1, v140
	v_lshl_add_u64 v[118:119], v[118:119], 0, v[0:1]
	s_waitcnt lgkmcnt(0)
	global_store_dwordx4 v[118:119], v[114:117], off nt
	ds_read_b128 v[114:117], v180 offset:1152
	v_or_b32_e32 v120, s19, v175
	s_andn2_b64 vcc, exec, s[68:69]
	s_mov_b64 s[68:69], -1
	s_cbranch_vccnz .LBB0_162
	v_mad_i64_i32 v[118:119], s[68:69], v120, s48, 0
	s_lshl_b32 s68, s18, 8
	v_lshl_add_u64 v[118:119], v[118:119], 1, s[78:79]
	s_ashr_i32 s69, s68, 31
	v_lshl_add_u64 v[118:119], s[68:69], 1, v[118:119]
	s_lshl_b32 s74, s15, 1
	v_lshl_add_u64 v[118:119], v[118:119], 0, s[74:75]
	s_mov_b64 s[68:69], 0

; #define PG8_LAS __attribute__((address_space(3)))
;     __device__ __forceinline__ void operator()(const f32x4 (&acc)[2][2][4][2], const Unit& u, int wr, int wc, int fr, int fq, PG8_LAS float* stash, int par, PG8_LAS unsigned char* stg, const Unit& un) const {
;     ...
;                     if (odd) kind = (u.pn < 6) ? 0 : (u.pn == 6 ? 1 : 2);
;                     else     kind = (u.pn < 2) ? 0 : (u.pn == 2 ? (wc < 2 ? 1 : 2) : 3);
; #pragma unroll
;                     for (int i = 0; i < 2; ++i) { const int c = fq * 16 + fr + 64 * i, rr = c >> 3, pc = c & 7;
;                         const u32x4 w = *(const PG8_LAS u32x4*)(stg + rr * 144 + pc * 16);
;                         const int rowc = row - fr + rr, posc = rowc & 4095;
;                         if (kind == 1 || kind == 2) {
;                             bf16_t* dst = (kind == 1) ? kd : vt;
;                             if (odd) *(u32x4*)(dst + (size_t)(b * 4 + wc) * (4096 * 64) + (size_t)((posc & 15) * 256 + (posc >> 4)) * 64 + pc * 8) = w;
;                             else     *(u32x4*)(dst + (size_t)(b * 2 + (wc & 1)) * (4096 * 64) + (size_t)posc * 64 + pc * 8) = w;
;                         } else {
;                             *(u32x4*)(proj + (size_t)rowc * ldp + u.pn * BM + wc * 64 + pc * 8) = w;
.LBB0_167:
	v_lshl_add_u64 v[118:119], v[118:119], 0, v[0:1]
	s_and_b64 vcc, exec, s[42:43]
	s_mov_b64 s[66:67], -1
	s_waitcnt lgkmcnt(0)
	global_store_dwordx4 v[118:119], v[114:117], off nt
	s_cbranch_vccnz .LBB0_169
	s_cmp_eq_u32 s18, 6
	s_cselect_b32 s53, 1, 2
	s_cmp_gt_i32 s18, 5
	s_cselect_b32 s65, s53, 0
	s_mov_b64 s[66:67], 0

; #define PG8_LAS __attribute__((address_space(3)))
;     __device__ __forceinline__ void operator()(const f32x4 (&acc)[2][2][4][2], const Unit& u, int wr, int wc, int fr, int fq, PG8_LAS float* stash, int par, PG8_LAS unsigned char* stg, const Unit& un) const {
;     ...
;                     for (int i = 0; i < 2; ++i) { const int c = fq * 16 + fr + 64 * i, rr = c >> 3, pc = c & 7;
;                         const u32x4 w = *(const PG8_LAS u32x4*)(stg + rr * 144 + pc * 16);
;                         const int rowc = row - fr + rr, posc = rowc & 4095;
;                         if (kind == 1 || kind == 2) {
;                             bf16_t* dst = (kind == 1) ? kd : vt;
;                             if (odd) *(u32x4*)(dst + (size_t)(b * 4 + wc) * (4096 * 64) + (size_t)((posc & 15) * 256 + (posc >> 4)) * 64 + pc * 8) = w;
;                             else     *(u32x4*)(dst + (size_t)(b * 2 + (wc & 1)) * (4096 * 64) + (size_t)posc * 64 + pc * 8) = w;
;                         } else {
;                             *(u32x4*)(proj + (size_t)rowc * ldp + u.pn * BM + wc * 64 + pc * 8) = w;
;                         }
.LBB0_186:
	v_lshl_add_u64 v[102:103], v[102:103], 0, v[0:1]
	s_waitcnt lgkmcnt(0)
	global_store_dwordx4 v[102:103], v[98:101], off nt
	ds_read_b128 v[98:101], v180 offset:1152
	v_or_b32_e32 v104, s53, v175
	s_andn2_b64 vcc, exec, s[68:69]
	s_mov_b64 s[68:69], -1
	s_cbranch_vccnz .LBB0_188
	v_mad_i64_i32 v[102:103], s[68:69], v104, s48, 0
	s_lshl_b32 s68, s18, 8
	v_lshl_add_u64 v[102:103], v[102:103], 1, s[78:79]
	s_ashr_i32 s69, s68, 31
	v_lshl_add_u64 v[102:103], s[68:69], 1, v[102:103]
	s_lshl_b32 s74, s15, 1
	v_lshl_add_u64 v[102:103], v[102:103], 0, s[74:75]
	s_mov_b64 s[68:69], 0

; #define PG8_LAS __attribute__((address_space(3)))
;     __device__ __forceinline__ void operator()(const f32x4 (&acc)[2][2][4][2], const Unit& u, int wr, int wc, int fr, int fq, PG8_LAS float* stash, int par, PG8_LAS unsigned char* stg, const Unit& un) const {
;     ...
;                     if (odd) kind = (u.pn < 6) ? 0 : (u.pn == 6 ? 1 : 2);
;                     else     kind = (u.pn < 2) ? 0 : (u.pn == 2 ? (wc < 2 ? 1 : 2) : 3);
; #pragma unroll
;                     for (int i = 0; i < 2; ++i) { const int c = fq * 16 + fr + 64 * i, rr = c >> 3, pc = c & 7;
;                         const u32x4 w = *(const PG8_LAS u32x4*)(stg + rr * 144 + pc * 16);
;                         const int rowc = row - fr + rr, posc = rowc & 4095;
;                         if (kind == 1 || kind == 2) {
;                             bf16_t* dst = (kind == 1) ? kd : vt;
;                             if (odd) *(u32x4*)(dst + (size_t)(b * 4 + wc) * (4096 * 64) + (size_t)((posc & 15) * 256 + (posc >> 4)) * 64 + pc * 8) = w;
;                             else     *(u32x4*)(dst + (size_t)(b * 2 + (wc & 1)) * (4096 * 64) + (size_t)posc * 64 + pc * 8) = w;
;                         } else {
;                             *(u32x4*)(proj + (size_t)rowc * ldp + u.pn * BM + wc * 64 + pc * 8) = w;
.LBB0_193:
	v_lshl_add_u64 v[102:103], v[102:103], 0, v[0:1]
	s_and_b64 vcc, exec, s[42:43]
	s_mov_b64 s[66:67], -1
	s_waitcnt lgkmcnt(0)
	global_store_dwordx4 v[102:103], v[98:101], off nt
	s_cbranch_vccnz .LBB0_195
	s_cmp_eq_u32 s18, 6
	s_cselect_b32 s53, 1, 2
	s_cmp_gt_i32 s18, 5
	s_cselect_b32 s65, s53, 0
	s_mov_b64 s[66:67], 0

; #define PG8_LAS __attribute__((address_space(3)))
;     __device__ __forceinline__ void operator()(const f32x4 (&acc)[2][2][4][2], const Unit& u, int wr, int wc, int fr, int fq, PG8_LAS float* stash, int par, PG8_LAS unsigned char* stg, const Unit& un) const {
;     ...
;                     for (int i = 0; i < 2; ++i) { const int c = fq * 16 + fr + 64 * i, rr = c >> 3, pc = c & 7;
;                         const u32x4 w = *(const PG8_LAS u32x4*)(stg + rr * 144 + pc * 16);
;                         const int rowc = row - fr + rr, posc = rowc & 4095;
;                         if (kind == 1 || kind == 2) {
;                             bf16_t* dst = (kind == 1) ? kd : vt;
;                             if (odd) *(u32x4*)(dst + (size_t)(b * 4 + wc) * (4096 * 64) + (size_t)((posc & 15) * 256 + (posc >> 4)) * 64 + pc * 8) = w;
;                             else     *(u32x4*)(dst + (size_t)(b * 2 + (wc & 1)) * (4096 * 64) + (size_t)posc * 64 + pc * 8) = w;
;                         } else {
;                             *(u32x4*)(proj + (size_t)rowc * ldp + u.pn * BM + wc * 64 + pc * 8) = w;
;                         }
.LBB0_212:
	v_lshl_add_u64 v[86:87], v[86:87], 0, v[0:1]
	s_waitcnt lgkmcnt(0)
	global_store_dwordx4 v[86:87], v[82:85], off nt
	ds_read_b128 v[82:85], v180 offset:1152
	v_or_b32_e32 v88, s53, v175
	s_andn2_b64 vcc, exec, s[68:69]
	s_mov_b64 s[68:69], -1
	s_cbranch_vccnz .LBB0_214
	v_mad_i64_i32 v[86:87], s[68:69], v88, s48, 0
	s_lshl_b32 s68, s18, 8
	v_lshl_add_u64 v[86:87], v[86:87], 1, s[78:79]
	s_ashr_i32 s69, s68, 31
	v_lshl_add_u64 v[86:87], s[68:69], 1, v[86:87]
	s_lshl_b32 s74, s15, 1
	v_lshl_add_u64 v[86:87], v[86:87], 0, s[74:75]
	s_mov_b64 s[68:69], 0

; #define PG8_LAS __attribute__((address_space(3)))
;     __device__ __forceinline__ void operator()(const f32x4 (&acc)[2][2][4][2], const Unit& u, int wr, int wc, int fr, int fq, PG8_LAS float* stash, int par, PG8_LAS unsigned char* stg, const Unit& un) const {
;     ...
;                     if (odd) kind = (u.pn < 6) ? 0 : (u.pn == 6 ? 1 : 2);
;                     else     kind = (u.pn < 2) ? 0 : (u.pn == 2 ? (wc < 2 ? 1 : 2) : 3);
; #pragma unroll
;                     for (int i = 0; i < 2; ++i) { const int c = fq * 16 + fr + 64 * i, rr = c >> 3, pc = c & 7;
;                         const u32x4 w = *(const PG8_LAS u32x4*)(stg + rr * 144 + pc * 16);
;                         const int rowc = row - fr + rr, posc = rowc & 4095;
;                         if (kind == 1 || kind == 2) {
;                             bf16_t* dst = (kind == 1) ? kd : vt;
;                             if (odd) *(u32x4*)(dst + (size_t)(b * 4 + wc) * (4096 * 64) + (size_t)((posc & 15) * 256 + (posc >> 4)) * 64 + pc * 8) = w;
;                             else     *(u32x4*)(dst + (size_t)(b * 2 + (wc & 1)) * (4096 * 64) + (size_t)posc * 64 + pc * 8) = w;
;                         } else {
;                             *(u32x4*)(proj + (size_t)rowc * ldp + u.pn * BM + wc * 64 + pc * 8) = w;
.LBB0_219:
	v_lshl_add_u64 v[86:87], v[86:87], 0, v[0:1]
	s_and_b64 vcc, exec, s[42:43]
	s_mov_b64 s[66:67], -1
	s_waitcnt lgkmcnt(0)
	global_store_dwordx4 v[86:87], v[82:85], off nt
	s_cbranch_vccnz .LBB0_221
	s_cmp_eq_u32 s18, 6
	s_cselect_b32 s53, 1, 2
	s_cmp_gt_i32 s18, 5
	s_cselect_b32 s65, s53, 0
	s_mov_b64 s[66:67], 0

; #define PG8_LAS __attribute__((address_space(3)))
;     __device__ __forceinline__ void operator()(const f32x4 (&acc)[2][2][4][2], const Unit& u, int wr, int wc, int fr, int fq, PG8_LAS float* stash, int par, PG8_LAS unsigned char* stg, const Unit& un) const {
;     ...
;                     for (int i = 0; i < 2; ++i) { const int c = fq * 16 + fr + 64 * i, rr = c >> 3, pc = c & 7;
;                         const u32x4 w = *(const PG8_LAS u32x4*)(stg + rr * 144 + pc * 16);
;                         const int rowc = row - fr + rr, posc = rowc & 4095;
;                         if (kind == 1 || kind == 2) {
;                             bf16_t* dst = (kind == 1) ? kd : vt;
;                             if (odd) *(u32x4*)(dst + (size_t)(b * 4 + wc) * (4096 * 64) + (size_t)((posc & 15) * 256 + (posc >> 4)) * 64 + pc * 8) = w;
;                             else     *(u32x4*)(dst + (size_t)(b * 2 + (wc & 1)) * (4096 * 64) + (size_t)posc * 64 + pc * 8) = w;
;                         } else {
;                             *(u32x4*)(proj + (size_t)rowc * ldp + u.pn * BM + wc * 64 + pc * 8) = w;
;                         }
.LBB0_238:
	v_lshl_add_u64 v[70:71], v[70:71], 0, v[0:1]
	s_waitcnt lgkmcnt(0)
	global_store_dwordx4 v[70:71], v[66:69], off nt
	ds_read_b128 v[66:69], v180 offset:1152
	v_or_b32_e32 v72, s53, v175
	s_andn2_b64 vcc, exec, s[68:69]
	s_mov_b64 s[68:69], -1
	s_cbranch_vccnz .LBB0_240
	v_mad_i64_i32 v[70:71], s[68:69], v72, s48, 0
	s_lshl_b32 s68, s18, 8
	v_lshl_add_u64 v[70:71], v[70:71], 1, s[78:79]
	s_ashr_i32 s69, s68, 31
	v_lshl_add_u64 v[70:71], s[68:69], 1, v[70:71]
	s_lshl_b32 s74, s15, 1
	v_lshl_add_u64 v[70:71], v[70:71], 0, s[74:75]
	s_mov_b64 s[68:69], 0

; #define PG8_LAS __attribute__((address_space(3)))
;     __device__ __forceinline__ void operator()(const f32x4 (&acc)[2][2][4][2], const Unit& u, int wr, int wc, int fr, int fq, PG8_LAS float* stash, int par, PG8_LAS unsigned char* stg, const Unit& un) const {
;     ...
;                     if (odd) kind = (u.pn < 6) ? 0 : (u.pn == 6 ? 1 : 2);
;                     else     kind = (u.pn < 2) ? 0 : (u.pn == 2 ? (wc < 2 ? 1 : 2) : 3);
; #pragma unroll
;                     for (int i = 0; i < 2; ++i) { const int c = fq * 16 + fr + 64 * i, rr = c >> 3, pc = c & 7;
;                         const u32x4 w = *(const PG8_LAS u32x4*)(stg + rr * 144 + pc * 16);
;                         const int rowc = row - fr + rr, posc = rowc & 4095;
;                         if (kind == 1 || kind == 2) {
;                             bf16_t* dst = (kind == 1) ? kd : vt;
;                             if (odd) *(u32x4*)(dst + (size_t)(b * 4 + wc) * (4096 * 64) + (size_t)((posc & 15) * 256 + (posc >> 4)) * 64 + pc * 8) = w;
;                             else     *(u32x4*)(dst + (size_t)(b * 2 + (wc & 1)) * (4096 * 64) + (size_t)posc * 64 + pc * 8) = w;
;                         } else {
;                             *(u32x4*)(proj + (size_t)rowc * ldp + u.pn * BM + wc * 64 + pc * 8) = w;
.LBB0_245:
	v_lshl_add_u64 v[70:71], v[70:71], 0, v[0:1]
	s_waitcnt lgkmcnt(0)
	global_store_dwordx4 v[70:71], v[66:69], off nt
	s_and_b64 vcc, exec, s[42:43]
	s_mov_b64 s[66:67], -1
	s_cbranch_vccnz .LBB0_247
	s_cmp_eq_u32 s18, 6
	s_cselect_b32 s53, 1, 2
	s_cmp_gt_i32 s18, 5
	s_cselect_b32 s53, s53, 0
	s_mov_b64 s[66:67], 0

; #define PG8_LAS __attribute__((address_space(3)))
;     __device__ __forceinline__ void operator()(const f32x4 (&acc)[2][2][4][2], const Unit& u, int wr, int wc, int fr, int fq, PG8_LAS float* stash, int par, PG8_LAS unsigned char* stg, const Unit& un) const {
;     ...
;                     for (int i = 0; i < 2; ++i) { const int c = fq * 16 + fr + 64 * i, rr = c >> 3, pc = c & 7;
;                         const u32x4 w = *(const PG8_LAS u32x4*)(stg + rr * 144 + pc * 16);
;                         const int rowc = row - fr + rr, posc = rowc & 4095;
;                         if (kind == 1 || kind == 2) {
;                             bf16_t* dst = (kind == 1) ? kd : vt;
;                             if (odd) *(u32x4*)(dst + (size_t)(b * 4 + wc) * (4096 * 64) + (size_t)((posc & 15) * 256 + (posc >> 4)) * 64 + pc * 8) = w;
;                             else     *(u32x4*)(dst + (size_t)(b * 2 + (wc & 1)) * (4096 * 64) + (size_t)posc * 64 + pc * 8) = w;
;                         } else {
;                             *(u32x4*)(proj + (size_t)rowc * ldp + u.pn * BM + wc * 64 + pc * 8) = w;
;                         }
.LBB0_264:
	v_lshl_add_u64 v[54:55], v[54:55], 0, v[0:1]
	s_waitcnt lgkmcnt(0)
	global_store_dwordx4 v[54:55], v[50:53], off nt
	ds_read_b128 v[50:53], v180 offset:1152
	v_or_b32_e32 v56, s19, v175
	s_andn2_b64 vcc, exec, s[68:69]
	s_mov_b64 s[68:69], -1
	s_cbranch_vccnz .LBB0_266
	v_mad_i64_i32 v[54:55], s[68:69], v56, s48, 0
	s_lshl_b32 s68, s18, 8
	v_lshl_add_u64 v[54:55], v[54:55], 1, s[78:79]
	s_ashr_i32 s69, s68, 31
	v_lshl_add_u64 v[54:55], s[68:69], 1, v[54:55]
	s_lshl_b32 s74, s15, 1
	v_lshl_add_u64 v[54:55], v[54:55], 0, s[74:75]
	s_mov_b64 s[68:69], 0

; #define PG8_LAS __attribute__((address_space(3)))
;     __device__ __forceinline__ void operator()(const f32x4 (&acc)[2][2][4][2], const Unit& u, int wr, int wc, int fr, int fq, PG8_LAS float* stash, int par, PG8_LAS unsigned char* stg, const Unit& un) const {
;     ...
;                     if (odd) kind = (u.pn < 6) ? 0 : (u.pn == 6 ? 1 : 2);
;                     else     kind = (u.pn < 2) ? 0 : (u.pn == 2 ? (wc < 2 ? 1 : 2) : 3);
; #pragma unroll
;                     for (int i = 0; i < 2; ++i) { const int c = fq * 16 + fr + 64 * i, rr = c >> 3, pc = c & 7;
;                         const u32x4 w = *(const PG8_LAS u32x4*)(stg + rr * 144 + pc * 16);
;                         const int rowc = row - fr + rr, posc = rowc & 4095;
;                         if (kind == 1 || kind == 2) {
;                             bf16_t* dst = (kind == 1) ? kd : vt;
;                             if (odd) *(u32x4*)(dst + (size_t)(b * 4 + wc) * (4096 * 64) + (size_t)((posc & 15) * 256 + (posc >> 4)) * 64 + pc * 8) = w;
;                             else     *(u32x4*)(dst + (size_t)(b * 2 + (wc & 1)) * (4096 * 64) + (size_t)posc * 64 + pc * 8) = w;
;                         } else {
;                             *(u32x4*)(proj + (size_t)rowc * ldp + u.pn * BM + wc * 64 + pc * 8) = w;
.LBB0_271:
	v_lshl_add_u64 v[54:55], v[54:55], 0, v[0:1]
	s_and_b64 vcc, exec, s[42:43]
	s_mov_b64 s[66:67], -1
	s_waitcnt lgkmcnt(0)
	global_store_dwordx4 v[54:55], v[50:53], off nt
	s_cbranch_vccnz .LBB0_273
	s_cmp_eq_u32 s18, 6
	s_cselect_b32 s53, 1, 2
	s_cmp_gt_i32 s18, 5
	s_cselect_b32 s65, s53, 0
	s_mov_b64 s[66:67], 0

; #define PG8_LAS __attribute__((address_space(3)))
;     __device__ __forceinline__ void operator()(const f32x4 (&acc)[2][2][4][2], const Unit& u, int wr, int wc, int fr, int fq, PG8_LAS float* stash, int par, PG8_LAS unsigned char* stg, const Unit& un) const {
;     ...
;                     for (int i = 0; i < 2; ++i) { const int c = fq * 16 + fr + 64 * i, rr = c >> 3, pc = c & 7;
;                         const u32x4 w = *(const PG8_LAS u32x4*)(stg + rr * 144 + pc * 16);
;                         const int rowc = row - fr + rr, posc = rowc & 4095;
;                         if (kind == 1 || kind == 2) {
;                             bf16_t* dst = (kind == 1) ? kd : vt;
;                             if (odd) *(u32x4*)(dst + (size_t)(b * 4 + wc) * (4096 * 64) + (size_t)((posc & 15) * 256 + (posc >> 4)) * 64 + pc * 8) = w;
;                             else     *(u32x4*)(dst + (size_t)(b * 2 + (wc & 1)) * (4096 * 64) + (size_t)posc * 64 + pc * 8) = w;
;                         } else {
;                             *(u32x4*)(proj + (size_t)rowc * ldp + u.pn * BM + wc * 64 + pc * 8) = w;
;                         }
.LBB0_290:
	v_lshl_add_u64 v[38:39], v[38:39], 0, v[0:1]
	s_waitcnt lgkmcnt(0)
	global_store_dwordx4 v[38:39], v[34:37], off nt
	ds_read_b128 v[34:37], v180 offset:1152
	v_or_b32_e32 v40, s53, v175
	s_andn2_b64 vcc, exec, s[68:69]
	s_mov_b64 s[68:69], -1
	s_cbranch_vccnz .LBB0_292
	v_mad_i64_i32 v[38:39], s[68:69], v40, s48, 0
	s_lshl_b32 s68, s18, 8
	v_lshl_add_u64 v[38:39], v[38:39], 1, s[78:79]
	s_ashr_i32 s69, s68, 31
	v_lshl_add_u64 v[38:39], s[68:69], 1, v[38:39]
	s_lshl_b32 s74, s15, 1
	v_lshl_add_u64 v[38:39], v[38:39], 0, s[74:75]
	s_mov_b64 s[68:69], 0

; #define PG8_LAS __attribute__((address_space(3)))
;     __device__ __forceinline__ void operator()(const f32x4 (&acc)[2][2][4][2], const Unit& u, int wr, int wc, int fr, int fq, PG8_LAS float* stash, int par, PG8_LAS unsigned char* stg, const Unit& un) const {
;     ...
;                     if (odd) kind = (u.pn < 6) ? 0 : (u.pn == 6 ? 1 : 2);
;                     else     kind = (u.pn < 2) ? 0 : (u.pn == 2 ? (wc < 2 ? 1 : 2) : 3);
; #pragma unroll
;                     for (int i = 0; i < 2; ++i) { const int c = fq * 16 + fr + 64 * i, rr = c >> 3, pc = c & 7;
;                         const u32x4 w = *(const PG8_LAS u32x4*)(stg + rr * 144 + pc * 16);
;                         const int rowc = row - fr + rr, posc = rowc & 4095;
;                         if (kind == 1 || kind == 2) {
;                             bf16_t* dst = (kind == 1) ? kd : vt;
;                             if (odd) *(u32x4*)(dst + (size_t)(b * 4 + wc) * (4096 * 64) + (size_t)((posc & 15) * 256 + (posc >> 4)) * 64 + pc * 8) = w;
;                             else     *(u32x4*)(dst + (size_t)(b * 2 + (wc & 1)) * (4096 * 64) + (size_t)posc * 64 + pc * 8) = w;
;                         } else {
;                             *(u32x4*)(proj + (size_t)rowc * ldp + u.pn * BM + wc * 64 + pc * 8) = w;
.LBB0_297:
	v_lshl_add_u64 v[38:39], v[38:39], 0, v[0:1]
	s_and_b64 vcc, exec, s[42:43]
	s_mov_b64 s[66:67], -1
	s_waitcnt lgkmcnt(0)
	global_store_dwordx4 v[38:39], v[34:37], off nt
	s_cbranch_vccnz .LBB0_299
	s_cmp_eq_u32 s18, 6
	s_cselect_b32 s53, 1, 2
	s_cmp_gt_i32 s18, 5
	s_cselect_b32 s65, s53, 0
	s_mov_b64 s[66:67], 0

; #define PG8_LAS __attribute__((address_space(3)))
;     __device__ __forceinline__ void operator()(const f32x4 (&acc)[2][2][4][2], const Unit& u, int wr, int wc, int fr, int fq, PG8_LAS float* stash, int par, PG8_LAS unsigned char* stg, const Unit& un) const {
;     ...
;                     for (int i = 0; i < 2; ++i) { const int c = fq * 16 + fr + 64 * i, rr = c >> 3, pc = c & 7;
;                         const u32x4 w = *(const PG8_LAS u32x4*)(stg + rr * 144 + pc * 16);
;                         const int rowc = row - fr + rr, posc = rowc & 4095;
;                         if (kind == 1 || kind == 2) {
;                             bf16_t* dst = (kind == 1) ? kd : vt;
;                             if (odd) *(u32x4*)(dst + (size_t)(b * 4 + wc) * (4096 * 64) + (size_t)((posc & 15) * 256 + (posc >> 4)) * 64 + pc * 8) = w;
;                             else     *(u32x4*)(dst + (size_t)(b * 2 + (wc & 1)) * (4096 * 64) + (size_t)posc * 64 + pc * 8) = w;
;                         } else {
;                             *(u32x4*)(proj + (size_t)rowc * ldp + u.pn * BM + wc * 64 + pc * 8) = w;
;                         }
.LBB0_316:
	v_lshl_add_u64 v[22:23], v[22:23], 0, v[0:1]
	s_waitcnt lgkmcnt(0)
	global_store_dwordx4 v[22:23], v[18:21], off nt
	ds_read_b128 v[18:21], v180 offset:1152
	v_or_b32_e32 v24, s53, v175
	s_andn2_b64 vcc, exec, s[68:69]
	s_mov_b64 s[68:69], -1
	s_mov_b64 s[84:85], s[54:55]
	s_cbranch_vccnz .LBB0_318
	v_mad_i64_i32 v[22:23], s[68:69], v24, s48, 0
	s_lshl_b32 s68, s18, 8
	v_lshl_add_u64 v[22:23], v[22:23], 1, s[78:79]
	s_ashr_i32 s69, s68, 31
	v_lshl_add_u64 v[22:23], s[68:69], 1, v[22:23]
	s_lshl_b32 s74, s15, 1
	v_lshl_add_u64 v[22:23], v[22:23], 0, s[74:75]
	s_mov_b64 s[68:69], 0

; #define PG8_LAS __attribute__((address_space(3)))
;     __device__ __forceinline__ void operator()(const f32x4 (&acc)[2][2][4][2], const Unit& u, int wr, int wc, int fr, int fq, PG8_LAS float* stash, int par, PG8_LAS unsigned char* stg, const Unit& un) const {
;     ...
;                     if (odd) kind = (u.pn < 6) ? 0 : (u.pn == 6 ? 1 : 2);
;                     else     kind = (u.pn < 2) ? 0 : (u.pn == 2 ? (wc < 2 ? 1 : 2) : 3);
; #pragma unroll
;                     for (int i = 0; i < 2; ++i) { const int c = fq * 16 + fr + 64 * i, rr = c >> 3, pc = c & 7;
;                         const u32x4 w = *(const PG8_LAS u32x4*)(stg + rr * 144 + pc * 16);
;                         const int rowc = row - fr + rr, posc = rowc & 4095;
;                         if (kind == 1 || kind == 2) {
;                             bf16_t* dst = (kind == 1) ? kd : vt;
;                             if (odd) *(u32x4*)(dst + (size_t)(b * 4 + wc) * (4096 * 64) + (size_t)((posc & 15) * 256 + (posc >> 4)) * 64 + pc * 8) = w;
;                             else     *(u32x4*)(dst + (size_t)(b * 2 + (wc & 1)) * (4096 * 64) + (size_t)posc * 64 + pc * 8) = w;
;                         } else {
;                             *(u32x4*)(proj + (size_t)rowc * ldp + u.pn * BM + wc * 64 + pc * 8) = w;
.LBB0_323:
	v_lshl_add_u64 v[22:23], v[22:23], 0, v[0:1]
	s_and_b64 vcc, exec, s[42:43]
	s_mov_b64 s[66:67], -1
	s_waitcnt lgkmcnt(0)
	global_store_dwordx4 v[22:23], v[18:21], off nt
	s_cbranch_vccnz .LBB0_325
	s_cmp_eq_u32 s18, 6
	s_cselect_b32 s53, 1, 2
	s_cmp_gt_i32 s18, 5
	s_cselect_b32 s53, s53, 0
	s_mov_b64 s[66:67], 0

; #define PG8_LAS __attribute__((address_space(3)))
;     __device__ __forceinline__ void operator()(const f32x4 (&acc)[2][2][4][2], const Unit& u, int wr, int wc, int fr, int fq, PG8_LAS float* stash, int par, PG8_LAS unsigned char* stg, const Unit& un) const {
;     ...
;                     for (int i = 0; i < 2; ++i) { const int c = fq * 16 + fr + 64 * i, rr = c >> 3, pc = c & 7;
;                         const u32x4 w = *(const PG8_LAS u32x4*)(stg + rr * 144 + pc * 16);
;                         const int rowc = row - fr + rr, posc = rowc & 4095;
;                         if (kind == 1 || kind == 2) {
;                             bf16_t* dst = (kind == 1) ? kd : vt;
;                             if (odd) *(u32x4*)(dst + (size_t)(b * 4 + wc) * (4096 * 64) + (size_t)((posc & 15) * 256 + (posc >> 4)) * 64 + pc * 8) = w;
;                             else     *(u32x4*)(dst + (size_t)(b * 2 + (wc & 1)) * (4096 * 64) + (size_t)posc * 64 + pc * 8) = w;
;                         } else {
;                             *(u32x4*)(proj + (size_t)rowc * ldp + u.pn * BM + wc * 64 + pc * 8) = w;
;                         }
.LBB0_342:
	v_lshl_add_u64 v[6:7], v[6:7], 0, v[0:1]
	s_waitcnt lgkmcnt(0)
	global_store_dwordx4 v[6:7], v[2:5], off nt
	ds_read_b128 v[2:5], v180 offset:1152
	v_or_b32_e32 v8, s19, v175
	s_andn2_b64 vcc, exec, s[66:67]
	s_mov_b64 s[66:67], -1
	s_cbranch_vccnz .LBB0_344
	v_mad_i64_i32 v[6:7], s[66:67], v8, s48, 0
	s_lshl_b32 s18, s18, 8
	v_lshl_add_u64 v[6:7], v[6:7], 1, s[78:79]
	s_ashr_i32 s19, s18, 31
	v_lshl_add_u64 v[6:7], s[18:19], 1, v[6:7]
	s_lshl_b32 s74, s15, 1
	v_lshl_add_u64 v[6:7], v[6:7], 0, s[74:75]
	s_mov_b64 s[66:67], 0

; __device__ __forceinline__ float sum_x16(float s) { auto r = __builtin_amdgcn_permlane16_swap(__float_as_uint(s), __float_as_uint(s), false, false); return __uint_as_float(r[0]) + __uint_as_float(r[1]); }
; __device__ __forceinline__ float sum_x32(float s) { auto r = __builtin_amdgcn_permlane32_swap(__float_as_uint(s), __float_as_uint(s), false, false); return __uint_as_float(r[0]) + __uint_as_float(r[1]); }
; __device__ __forceinline__ void rows_part_reduce(const f32x4 (&pl)[2][4], float (&rs)[2][4]) {
; #pragma unroll
;     for (int ai = 0; ai < 2; ++ai)
; #pragma unroll
;         for (int m = 0; m < 4; ++m) { float s = (pl[ai][m][0] + pl[ai][m][1]) + (pl[ai][m][2] + pl[ai][m][3]); s = sum_x16(s); s = sum_x32(s); rs[ai][m] = __builtin_amdgcn_rsqf(s * (1.0f / 1024.0f) + 1e-6f); }
; }
;     __device__ __forceinline__ void operator()(const f32x4 (&acc)[2][2][4][2], const Unit& u, int wr, int wc, int fr, int fq, PG8_LAS float* stash, int par, PG8_LAS unsigned char* stg, const Unit& un) const {
;     ...
;         if (newpm) { float rsn[2][4]; rows_part_reduce(pln, rsn);
;           if (fq == 0) {
; #pragma unroll
;               for (int ai = 0; ai < 2; ++ai)
; #pragma unroll
;                   for (int m = 0; m < 4; ++m) stash[(par ^ 1) * 256 + ai * HALF + wr * 64 + m * 16 + fr] = rsn[ai][m]; } }
.LBB0_349:
	v_lshl_add_u64 v[6:7], v[6:7], 0, v[0:1]
	s_andn2_b64 vcc, exec, s[20:21]
	s_mov_b64 s[86:87], s[88:89]
	s_mov_b32 s88, s17
	s_mov_b32 s89, s91
	s_mov_b32 s91, s50
	s_waitcnt lgkmcnt(0)
	global_store_dwordx4 v[6:7], v[2:5], off nt
	s_cbranch_vccnz .LBB0_353
	s_waitcnt vmcnt(0)
	v_add_f32_e32 v0, v207, v214
	v_add_f32_e32 v2, v216, v217
	v_add_f32_e32 v3, v198, v211
	v_add_f32_e32 v4, v213, v215
	v_add_f32_e32 v5, v195, v208
	v_add_f32_e32 v6, v210, v212
	v_add_f32_e32 v7, v192, v199
	v_add_f32_e32 v8, v206, v209
	v_add_f32_e32 v9, v189, v194
	v_add_f32_e32 v10, v197, v205
	v_add_f32_e32 v11, v185, v190
	v_add_f32_e32 v12, v193, v196
	v_add_f32_e32 v13, v183, v186
	v_add_f32_e32 v14, v188, v191
	v_add_f32_e32 v15, v181, v182
	v_add_f32_e32 v16, v184, v187
	v_add_f32_e32 v0, v0, v2
	v_add_f32_e32 v3, v3, v4
	v_add_f32_e32 v5, v5, v6
	v_add_f32_e32 v7, v7, v8
	v_add_f32_e32 v9, v9, v10
	v_add_f32_e32 v11, v11, v12
	v_add_f32_e32 v13, v13, v14
	v_add_f32_e32 v15, v15, v16
	v_mov_b32_e32 v2, v0
	v_mov_b32_e32 v4, v3
	v_mov_b32_e32 v6, v5
	v_mov_b32_e32 v8, v7
	v_mov_b32_e32 v10, v9
	v_mov_b32_e32 v12, v11
	v_mov_b32_e32 v14, v13
	v_mov_b32_e32 v16, v15
	v_permlane16_swap_b32_e32 v0, v2
	v_permlane16_swap_b32_e32 v3, v4
	v_permlane16_swap_b32_e32 v5, v6
	v_permlane16_swap_b32_e32 v7, v8
	v_permlane16_swap_b32_e32 v9, v10
	v_permlane16_swap_b32_e32 v11, v12
	v_permlane16_swap_b32_e32 v13, v14
	v_permlane16_swap_b32_e32 v15, v16
	v_add_f32_e32 v0, v0, v2
	v_add_f32_e32 v3, v3, v4
	v_add_f32_e32 v5, v5, v6
	v_add_f32_e32 v7, v7, v8
	v_add_f32_e32 v9, v9, v10
	v_add_f32_e32 v11, v11, v12
	v_add_f32_e32 v13, v13, v14
	v_add_f32_e32 v15, v15, v16
	v_mov_b32_e32 v2, v0
	v_mov_b32_e32 v4, v3
	v_mov_b32_e32 v6, v5
	v_mov_b32_e32 v8, v7
	v_mov_b32_e32 v10, v9
	v_mov_b32_e32 v12, v11
	v_mov_b32_e32 v14, v13
	v_mov_b32_e32 v16, v15
	v_permlane32_swap_b32_e32 v0, v2
	v_permlane32_swap_b32_e32 v3, v4
	v_permlane32_swap_b32_e32 v5, v6
	v_permlane32_swap_b32_e32 v7, v8
	v_permlane32_swap_b32_e32 v9, v10
	v_permlane32_swap_b32_e32 v11, v12
	v_permlane32_swap_b32_e32 v13, v14
	v_permlane32_swap_b32_e32 v15, v16
	s_and_saveexec_b64 s[18:19], s[34:35]
	s_cbranch_execz .LBB0_352
	v_add_f32_e32 v15, v15, v16
	v_mov_b32_e32 v16, 0x358637bd
	v_add_f32_e32 v3, v3, v4
	v_add_f32_e32 v0, v0, v2
	v_add_f32_e32 v7, v7, v8
	v_add_f32_e32 v5, v5, v6
	v_fmamk_f32 v3, v3, 0x3a800000, v16
	v_fmamk_f32 v0, v0, 0x3a800000, v16
	v_add_f32_e32 v11, v11, v12
	v_add_f32_e32 v9, v9, v10
	v_fmamk_f32 v7, v7, 0x3a800000, v16
	v_fmamk_f32 v5, v5, 0x3a800000, v16
	v_rsq_f32_e32 v3, v3
	v_rsq_f32_e32 v0, v0
	v_add_f32_e32 v13, v13, v14
	v_fmamk_f32 v11, v11, 0x3a800000, v16
	v_fmamk_f32 v9, v9, 0x3a800000, v16
	v_rsq_f32_e32 v7, v7
	v_rsq_f32_e32 v5, v5
	v_lshlrev_b32_e32 v2, 10, v179
	v_fmamk_f32 v15, v15, 0x3a800000, v16
	v_fmamk_f32 v13, v13, 0x3a800000, v16
	v_rsq_f32_e32 v11, v11
	v_rsq_f32_e32 v9, v9
	v_xor_b32_e32 v2, 0x400, v2
	v_rsq_f32_e32 v15, v15
	v_rsq_f32_e32 v13, v13
	v_add_u32_e32 v2, v172, v2
	ds_write2_b32 v2, v0, v3 offset1:16
	ds_write2_b32 v2, v5, v7 offset0:32 offset1:48
	ds_write2_b32 v2, v9, v11 offset0:128 offset1:144
	ds_write2_b32 v2, v13, v15 offset0:160 offset1:176

; #define PG8_LAS __attribute__((address_space(3)))
; __device__ __forceinline__ unsigned cvt_pk_bf16(float lo, float hi) { unsigned r; asm volatile("v_cvt_pk_bf16_f32 %0, %1, %2" : "=v"(r) : "v"(lo), "v"(hi)); return r; }
;     __device__ __forceinline__ void operator()(const f32x4 (&acc)[2][2][4][2], const Unit& u, int wr, int wc, int fr, int fq, PG8_LAS unsigned char* stg) const {
;     ...
;         for (int ai = 0; ai < 2; ++ai) {
;         asm volatile("" ::: "memory");
;         u32x4 xin[4][2];
; #pragma unroll
;         for (int m = 0; m < 4; ++m)
; #pragma unroll
;             for (int i = 0; i < 2; ++i) { const int c = lane + 64 * i; xin[m][i] = *(const u32x4*)(xb + (size_t)(rowb + ai * HALF + m * 16 + (c >> 3)) * 1024 + colw + (c & 7) * 8); }
; #pragma unroll
;         for (int m = 0; m < 4; ++m) {
;             const int row = rowb + ai * HALF + m * 16 + fr;
; #pragma unroll
;             for (int i = 0; i < 2; ++i) { const int c = lane + 64 * i; *(PG8_LAS u32x4*)(stg + (c >> 3) * 144 + (c & 7) * 16) = xin[m][i]; }
;             float ss = 0.f;
; #pragma unroll
;             for (int bj = 0; bj < 2; ++bj) {
;                 const u32x4 xo = *(const PG8_LAS u32x4*)(st + bj * 64);
;                 float v[8];
; #pragma unroll
;                 for (int i = 0; i < 4; ++i) { v[2 * i] = __uint_as_float(xo[i] << 16) + acc[ai][bj][m][i >> 1][(2 * i) & 3]; v[2 * i + 1] = __uint_as_float(xo[i] & 0xffff0000u) + acc[ai][bj][m][i >> 1][(2 * i + 1) & 3]; }
;                 u32x4 w; w.x = cvt_pk_bf16(v[0], v[1]); w.y = cvt_pk_bf16(v[2], v[3]); w.z = cvt_pk_bf16(v[4], v[5]); w.w = cvt_pk_bf16(v[6], v[7]);
;                 *(PG8_LAS u32x4*)(st + bj * 64) = w;
;                 ss += ((v[0] * v[0] + v[1] * v[1]) + (v[2] * v[2] + v[3] * v[3])) + ((v[4] * v[4] + v[5] * v[5]) + (v[6] * v[6] + v[7] * v[7]));
;             }
; #pragma unroll
;             for (int i = 0; i < 2; ++i) { const int c = lane + 64 * i; const u32x4 w = *(const PG8_LAS u32x4*)(stg + (c >> 3) * 144 + (c & 7) * 16);
;                 *(u32x4*)(xo_ + (size_t)(row - fr + (c >> 3)) * 1024 + colw + (c & 7) * 8) = w; }
;             ss = sum_x16(ss); ss = sum_x32(ss);
;             if (fq == 0) po_[(size_t)(u.pn * 4 + wc) * 65536 + row] = ss;
.LBB0_756:
	s_ashr_i32 s47, s46, 31
	s_lshl_b64 s[44:45], s[46:47], 8
	s_lshl_b32 s29, s50, 8
	s_or_b64 s[48:49], s[44:45], s[22:23]
	s_add_i32 s44, s29, s15
	v_or_b32_e32 v130, s44, v206
	s_lshl_b64 s[48:49], s[48:49], 1
	v_ashrrev_i32_e32 v131, 31, v130
	v_lshl_add_u64 v[182:183], v[176:177], 0, s[48:49]
	v_lshlrev_b64 v[198:199], 11, v[130:131]
	v_lshl_add_u64 v[130:131], v[182:183], 0, v[198:199]
	global_load_dwordx4 v[154:157], v[130:131], off
	v_or_b32_e32 v130, s44, v207
	v_ashrrev_i32_e32 v131, 31, v130
	v_lshlrev_b64 v[196:197], 11, v[130:131]
	v_lshl_add_u64 v[130:131], v[182:183], 0, v[196:197]
	global_load_dwordx4 v[160:163], v[130:131], off
	s_lshl_b32 s29, s46, 2
	s_or_b32 s46, s29, s13
	s_or_b32 s29, s44, 16
	v_or_b32_e32 v130, s29, v206
	v_ashrrev_i32_e32 v131, 31, v130
	v_lshlrev_b64 v[194:195], 11, v[130:131]
	v_lshl_add_u64 v[130:131], v[182:183], 0, v[194:195]
	global_load_dwordx4 v[146:149], v[130:131], off
	v_or_b32_e32 v130, s29, v207
	v_ashrrev_i32_e32 v131, 31, v130
	v_lshlrev_b64 v[192:193], 11, v[130:131]
	v_lshl_add_u64 v[130:131], v[182:183], 0, v[192:193]
	s_or_b32 s29, s44, 32
	global_load_dwordx4 v[150:153], v[130:131], off
	v_or_b32_e32 v130, s29, v206
	v_ashrrev_i32_e32 v131, 31, v130
	v_lshlrev_b64 v[188:189], 11, v[130:131]
	v_lshl_add_u64 v[130:131], v[182:183], 0, v[188:189]
	global_load_dwordx4 v[134:137], v[130:131], off
	v_or_b32_e32 v130, s29, v207
	v_ashrrev_i32_e32 v131, 31, v130
	v_lshlrev_b64 v[186:187], 11, v[130:131]
	v_lshl_add_u64 v[130:131], v[182:183], 0, v[186:187]
	s_or_b32 s29, s44, 48
	global_load_dwordx4 v[138:141], v[130:131], off
	v_or_b32_e32 v130, s29, v206
	v_or_b32_e32 v142, s29, v207
	v_ashrrev_i32_e32 v131, 31, v130
	v_ashrrev_i32_e32 v143, 31, v142
	v_lshlrev_b64 v[184:185], 11, v[130:131]
	v_lshlrev_b64 v[190:191], 11, v[142:143]
	v_lshl_add_u64 v[130:131], v[182:183], 0, v[184:185]
	v_lshl_add_u64 v[142:143], v[182:183], 0, v[190:191]
	global_load_dwordx4 v[130:133], v[130:131], off
	s_ashr_i32 s47, s46, 31
	global_load_dwordx4 v[142:145], v[142:143], off
	s_lshl_b64 s[46:47], s[46:47], 18
	s_waitcnt vmcnt(0)
	ds_write_b128 v209, v[154:157]
	ds_write_b128 v209, v[160:163] offset:1152
	ds_read_b128 v[154:157], v210
	s_waitcnt lgkmcnt(0)
	v_lshlrev_b32_e32 v160, 16, v154
	v_and_b32_e32 v154, 0xffff0000, v154
	v_add_f32_e32 v127, v127, v154
	v_lshlrev_b32_e32 v154, 16, v155
	v_add_f32_e32 v128, v128, v154
	v_and_b32_e32 v154, 0xffff0000, v155
	v_add_f32_e32 v129, v129, v154
	v_lshlrev_b32_e32 v154, 16, v156
	v_add_f32_e32 v154, v122, v154
	v_and_b32_e32 v122, 0xffff0000, v156
	v_add_f32_e32 v155, v123, v122
	v_lshlrev_b32_e32 v122, 16, v157
	v_add_f32_e32 v156, v124, v122
	v_and_b32_e32 v122, 0xffff0000, v157
	v_add_f32_e32 v126, v126, v160
	v_add_f32_e32 v157, v125, v122
	v_cvt_pk_bf16_f32 v122, v126, v127
	v_cvt_pk_bf16_f32 v123, v128, v129
	v_cvt_pk_bf16_f32 v124, v154, v155
	v_cvt_pk_bf16_f32 v125, v156, v157
	ds_write_b128 v210, v[122:125]
	v_mul_f32_e32 v122, v127, v127
	v_mul_f32_e32 v123, v129, v129
	v_fmac_f32_e32 v122, v126, v126
	v_fmac_f32_e32 v123, v128, v128
	v_add_f32_e32 v122, v122, v123
	v_mul_f32_e32 v123, v155, v155
	v_mul_f32_e32 v124, v157, v157
	v_fmac_f32_e32 v123, v154, v154
	v_fmac_f32_e32 v124, v156, v156
	v_add_f32_e32 v123, v123, v124
	v_add_f32_e32 v126, v122, v123
	ds_read_b128 v[122:125], v210 offset:64
	s_waitcnt lgkmcnt(0)
	v_lshlrev_b32_e32 v127, 16, v122
	v_and_b32_e32 v122, 0xffff0000, v122
	v_add_f32_e32 v119, v119, v122
	v_lshlrev_b32_e32 v122, 16, v123
	v_add_f32_e32 v120, v120, v122
	v_and_b32_e32 v122, 0xffff0000, v123
	v_add_f32_e32 v121, v121, v122
	v_lshlrev_b32_e32 v122, 16, v124
	v_add_f32_e32 v122, v114, v122
	v_and_b32_e32 v114, 0xffff0000, v124
	v_add_f32_e32 v123, v115, v114
	v_lshlrev_b32_e32 v114, 16, v125
	v_add_f32_e32 v124, v116, v114
	v_and_b32_e32 v114, 0xffff0000, v125
	v_add_f32_e32 v118, v118, v127
	v_add_f32_e32 v125, v117, v114
	v_cvt_pk_bf16_f32 v114, v118, v119
	v_cvt_pk_bf16_f32 v115, v120, v121
	v_cvt_pk_bf16_f32 v116, v122, v123
	v_cvt_pk_bf16_f32 v117, v124, v125
	ds_write_b128 v210, v[114:117] offset:64
	v_mul_f32_e32 v114, v119, v119
	v_mul_f32_e32 v115, v121, v121
	v_fmac_f32_e32 v114, v118, v118
	v_fmac_f32_e32 v115, v120, v120
	v_add_f32_e32 v114, v114, v115
	v_mul_f32_e32 v115, v123, v123
	v_mul_f32_e32 v116, v125, v125
	v_fmac_f32_e32 v115, v122, v122
	v_fmac_f32_e32 v116, v124, v124
	v_add_f32_e32 v115, v115, v116
	v_add_f32_e32 v114, v114, v115
	v_add_f32_e32 v120, v126, v114
	ds_read_b128 v[114:117], v211
	v_lshl_add_u64 v[118:119], s[76:77], 0, v[198:199]
	v_lshl_add_u64 v[118:119], v[118:119], 0, s[48:49]
	v_lshl_add_u64 v[118:119], v[118:119], 0, v[0:1]
	s_waitcnt lgkmcnt(0)
	global_store_dwordx4 v[118:119], v[114:117], off nt
	ds_read_b128 v[114:117], v211 offset:1152
	v_lshl_add_u64 v[118:119], s[76:77], 0, v[196:197]
	v_lshl_add_u64 v[118:119], v[118:119], 0, s[48:49]
	v_lshl_add_u64 v[118:119], v[118:119], 0, v[0:1]
	s_waitcnt lgkmcnt(0)
	global_store_dwordx4 v[118:119], v[114:117], off nt
	s_nop 1
	v_mov_b32_e32 v114, v120
	s_nop 1
	v_permlane16_swap_b32_e32 v120, v114
	v_add_f32_e32 v114, v120, v114
	v_mov_b32_e32 v115, v114
	s_nop 1
	v_permlane32_swap_b32_e32 v114, v115
	s_and_saveexec_b64 s[52:53], s[34:35]
	s_cbranch_execz .LBB0_758
	s_add_u32 s50, s82, s46
	v_or_b32_e32 v116, s44, v174
	s_addc_u32 s51, s83, s47
	v_ashrrev_i32_e32 v117, 31, v116
	v_lshl_add_u64 v[116:117], v[116:117], 2, s[50:51]
	v_add_f32_e32 v114, v114, v115
	global_store_dword v[116:117], v114, off
; #define PG8_LAS __attribute__((address_space(3)))
; __device__ __forceinline__ unsigned cvt_pk_bf16(float lo, float hi) { unsigned r; asm volatile("v_cvt_pk_bf16_f32 %0, %1, %2" : "=v"(r) : "v"(lo), "v"(hi)); return r; }
; __device__ __forceinline__ float sum_x16(float s) { auto r = __builtin_amdgcn_permlane16_swap(__float_as_uint(s), __float_as_uint(s), false, false); return __uint_as_float(r[0]) + __uint_as_float(r[1]); }
; __device__ __forceinline__ float sum_x32(float s) { auto r = __builtin_amdgcn_permlane32_swap(__float_as_uint(s), __float_as_uint(s), false, false); return __uint_as_float(r[0]) + __uint_as_float(r[1]); }
;     __device__ __forceinline__ void operator()(const f32x4 (&acc)[2][2][4][2], const Unit& u, int wr, int wc, int fr, int fq, PG8_LAS unsigned char* stg) const {
;     ...
;         for (int m = 0; m < 4; ++m) {
;             const int row = rowb + ai * HALF + m * 16 + fr;
; #pragma unroll
;             for (int i = 0; i < 2; ++i) { const int c = lane + 64 * i; *(PG8_LAS u32x4*)(stg + (c >> 3) * 144 + (c & 7) * 16) = xin[m][i]; }
;             float ss = 0.f;
; #pragma unroll
;             for (int bj = 0; bj < 2; ++bj) {
;                 const u32x4 xo = *(const PG8_LAS u32x4*)(st + bj * 64);
;                 float v[8];
; #pragma unroll
;                 for (int i = 0; i < 4; ++i) { v[2 * i] = __uint_as_float(xo[i] << 16) + acc[ai][bj][m][i >> 1][(2 * i) & 3]; v[2 * i + 1] = __uint_as_float(xo[i] & 0xffff0000u) + acc[ai][bj][m][i >> 1][(2 * i + 1) & 3]; }
;                 u32x4 w; w.x = cvt_pk_bf16(v[0], v[1]); w.y = cvt_pk_bf16(v[2], v[3]); w.z = cvt_pk_bf16(v[4], v[5]); w.w = cvt_pk_bf16(v[6], v[7]);
;                 *(PG8_LAS u32x4*)(st + bj * 64) = w;
;                 ss += ((v[0] * v[0] + v[1] * v[1]) + (v[2] * v[2] + v[3] * v[3])) + ((v[4] * v[4] + v[5] * v[5]) + (v[6] * v[6] + v[7] * v[7]));
;             }
; #pragma unroll
;             for (int i = 0; i < 2; ++i) { const int c = lane + 64 * i; const u32x4 w = *(const PG8_LAS u32x4*)(stg + (c >> 3) * 144 + (c & 7) * 16);
;                 *(u32x4*)(xo_ + (size_t)(row - fr + (c >> 3)) * 1024 + colw + (c & 7) * 8) = w; }
;             ss = sum_x16(ss); ss = sum_x32(ss);
;             if (fq == 0) po_[(size_t)(u.pn * 4 + wc) * 65536 + row] = ss;
.LBB0_758:
	s_or_b64 exec, exec, s[52:53]
	ds_write_b128 v209, v[146:149]
	ds_write_b128 v209, v[150:153] offset:1152
	ds_read_b128 v[114:117], v210
	s_waitcnt lgkmcnt(0)
	v_lshlrev_b32_e32 v118, 16, v114
	v_and_b32_e32 v114, 0xffff0000, v114
	v_add_f32_e32 v111, v111, v114
	v_and_b32_e32 v114, 0xffff0000, v115
	v_add_f32_e32 v113, v113, v114
	v_lshlrev_b32_e32 v114, 16, v116
	v_add_f32_e32 v114, v106, v114
	v_and_b32_e32 v106, 0xffff0000, v116
	v_lshlrev_b32_e32 v119, 16, v115
	v_add_f32_e32 v115, v107, v106
	v_lshlrev_b32_e32 v106, 16, v117
	v_add_f32_e32 v116, v108, v106
	v_and_b32_e32 v106, 0xffff0000, v117
	v_add_f32_e32 v110, v110, v118
	v_add_f32_e32 v112, v112, v119
	v_add_f32_e32 v117, v109, v106
	v_cvt_pk_bf16_f32 v106, v110, v111
	v_cvt_pk_bf16_f32 v107, v112, v113
	v_cvt_pk_bf16_f32 v108, v114, v115
	v_cvt_pk_bf16_f32 v109, v116, v117
	ds_write_b128 v210, v[106:109]
	v_mul_f32_e32 v106, v111, v111
	v_mul_f32_e32 v107, v113, v113
	v_fmac_f32_e32 v106, v110, v110
	v_fmac_f32_e32 v107, v112, v112
	v_add_f32_e32 v110, v106, v107
	ds_read_b128 v[106:109], v210 offset:64
	v_mul_f32_e32 v111, v115, v115
	v_mul_f32_e32 v112, v117, v117
	v_fmac_f32_e32 v111, v114, v114
	v_fmac_f32_e32 v112, v116, v116
	v_add_f32_e32 v111, v111, v112
	v_add_f32_e32 v110, v110, v111
	s_waitcnt lgkmcnt(0)
	v_lshlrev_b32_e32 v111, 16, v106
	v_and_b32_e32 v106, 0xffff0000, v106
	v_add_f32_e32 v103, v103, v106
	v_lshlrev_b32_e32 v106, 16, v107
	v_add_f32_e32 v104, v104, v106
	v_and_b32_e32 v106, 0xffff0000, v107
	v_add_f32_e32 v105, v105, v106
	v_lshlrev_b32_e32 v106, 16, v108
	v_add_f32_e32 v106, v98, v106
	v_and_b32_e32 v98, 0xffff0000, v108
	v_add_f32_e32 v107, v99, v98
	v_lshlrev_b32_e32 v98, 16, v109
	v_add_f32_e32 v108, v100, v98
	v_and_b32_e32 v98, 0xffff0000, v109
	v_add_f32_e32 v102, v102, v111
	v_add_f32_e32 v109, v101, v98
	v_cvt_pk_bf16_f32 v98, v102, v103
	v_cvt_pk_bf16_f32 v99, v104, v105
	v_cvt_pk_bf16_f32 v100, v106, v107
	v_cvt_pk_bf16_f32 v101, v108, v109
	ds_write_b128 v210, v[98:101] offset:64
	v_mul_f32_e32 v98, v103, v103
	v_mul_f32_e32 v99, v105, v105
	v_fmac_f32_e32 v98, v102, v102
	v_fmac_f32_e32 v99, v104, v104
	v_add_f32_e32 v98, v98, v99
	v_mul_f32_e32 v99, v107, v107
	v_mul_f32_e32 v100, v109, v109
	v_fmac_f32_e32 v99, v106, v106
	v_fmac_f32_e32 v100, v108, v108
	v_add_f32_e32 v99, v99, v100
	v_add_f32_e32 v98, v98, v99
	v_add_f32_e32 v108, v110, v98
	ds_read_b128 v[98:101], v211
	v_lshl_add_u64 v[102:103], s[76:77], 0, v[194:195]
	v_lshl_add_u64 v[102:103], v[102:103], 0, s[48:49]
	v_lshl_add_u64 v[106:107], v[102:103], 0, v[0:1]
	ds_read_b128 v[102:105], v211 offset:1152
	s_waitcnt lgkmcnt(1)
	global_store_dwordx4 v[106:107], v[98:101], off nt
	s_nop 1
	v_lshl_add_u64 v[98:99], s[76:77], 0, v[192:193]
	v_lshl_add_u64 v[98:99], v[98:99], 0, s[48:49]
	v_lshl_add_u64 v[98:99], v[98:99], 0, v[0:1]
	s_waitcnt lgkmcnt(0)
	global_store_dwordx4 v[98:99], v[102:105], off nt
	v_mov_b32_e32 v98, v108
	s_nop 1
	v_permlane16_swap_b32_e32 v108, v98
	v_add_f32_e32 v98, v108, v98
	v_mov_b32_e32 v99, v98
	s_nop 1
	v_permlane32_swap_b32_e32 v98, v99
	s_and_saveexec_b64 s[52:53], s[34:35]
	s_cbranch_execz .LBB0_760
	s_add_u32 s50, s82, s46
	s_addc_u32 s51, s83, s47
	s_ashr_i32 s45, s44, 31
	v_lshl_add_u64 v[100:101], s[44:45], 0, v[174:175]
	v_lshl_add_u64 v[100:101], v[100:101], 2, s[50:51]
	v_add_f32_e32 v98, v98, v99
	global_store_dword v[100:101], v98, off offset:64
.LBB0_760:
	s_or_b64 exec, exec, s[52:53]
	ds_write_b128 v209, v[134:137]
	ds_write_b128 v209, v[138:141] offset:1152
	ds_read_b128 v[98:101], v210
	s_waitcnt lgkmcnt(0)
	v_lshlrev_b32_e32 v102, 16, v98
	v_and_b32_e32 v98, 0xffff0000, v98
	v_add_f32_e32 v95, v95, v98
	v_and_b32_e32 v98, 0xffff0000, v99
	v_add_f32_e32 v97, v97, v98
	v_lshlrev_b32_e32 v98, 16, v100
	v_add_f32_e32 v98, v90, v98
	v_and_b32_e32 v90, 0xffff0000, v100
	v_lshlrev_b32_e32 v103, 16, v99
	v_add_f32_e32 v99, v91, v90
	v_lshlrev_b32_e32 v90, 16, v101
	v_add_f32_e32 v100, v92, v90
	v_and_b32_e32 v90, 0xffff0000, v101
	v_add_f32_e32 v94, v94, v102
	v_add_f32_e32 v96, v96, v103
	v_add_f32_e32 v101, v93, v90
	v_cvt_pk_bf16_f32 v90, v94, v95
	v_cvt_pk_bf16_f32 v91, v96, v97
	v_cvt_pk_bf16_f32 v92, v98, v99
	v_cvt_pk_bf16_f32 v93, v100, v101
	ds_write_b128 v210, v[90:93]
	v_mul_f32_e32 v90, v95, v95
	v_mul_f32_e32 v91, v97, v97
	v_fmac_f32_e32 v90, v94, v94
	v_fmac_f32_e32 v91, v96, v96
	v_add_f32_e32 v94, v90, v91
	ds_read_b128 v[90:93], v210 offset:64
	v_mul_f32_e32 v95, v99, v99
	v_mul_f32_e32 v96, v101, v101
	v_fmac_f32_e32 v95, v98, v98
	v_fmac_f32_e32 v96, v100, v100
	v_add_f32_e32 v95, v95, v96
	v_add_f32_e32 v94, v94, v95
	s_waitcnt lgkmcnt(0)
	v_lshlrev_b32_e32 v95, 16, v90
	v_and_b32_e32 v90, 0xffff0000, v90
	v_add_f32_e32 v87, v87, v90
	v_lshlrev_b32_e32 v90, 16, v91
	v_add_f32_e32 v88, v88, v90
	v_and_b32_e32 v90, 0xffff0000, v91
	v_add_f32_e32 v89, v89, v90
	v_lshlrev_b32_e32 v90, 16, v92
	v_add_f32_e32 v90, v82, v90
	v_and_b32_e32 v82, 0xffff0000, v92
	v_add_f32_e32 v91, v83, v82
	v_lshlrev_b32_e32 v82, 16, v93
	v_add_f32_e32 v92, v84, v82
	v_and_b32_e32 v82, 0xffff0000, v93
	v_add_f32_e32 v86, v86, v95
	v_add_f32_e32 v93, v85, v82
	v_cvt_pk_bf16_f32 v82, v86, v87
	v_cvt_pk_bf16_f32 v83, v88, v89
	v_cvt_pk_bf16_f32 v84, v90, v91
	v_cvt_pk_bf16_f32 v85, v92, v93
	ds_write_b128 v210, v[82:85] offset:64
	v_mul_f32_e32 v82, v87, v87
	v_mul_f32_e32 v83, v89, v89
	v_fmac_f32_e32 v82, v86, v86
	v_fmac_f32_e32 v83, v88, v88
	v_add_f32_e32 v82, v82, v83
	v_mul_f32_e32 v83, v91, v91
	v_mul_f32_e32 v84, v93, v93
	v_fmac_f32_e32 v83, v90, v90
	v_fmac_f32_e32 v84, v92, v92
	v_add_f32_e32 v83, v83, v84
	v_add_f32_e32 v82, v82, v83
	v_add_f32_e32 v92, v94, v82
	ds_read_b128 v[82:85], v211
	v_lshl_add_u64 v[86:87], s[76:77], 0, v[188:189]
	v_lshl_add_u64 v[86:87], v[86:87], 0, s[48:49]
	v_lshl_add_u64 v[90:91], v[86:87], 0, v[0:1]
	ds_read_b128 v[86:89], v211 offset:1152
	s_waitcnt lgkmcnt(1)
	global_store_dwordx4 v[90:91], v[82:85], off nt
	s_nop 1
	v_lshl_add_u64 v[82:83], s[76:77], 0, v[186:187]
	v_lshl_add_u64 v[82:83], v[82:83], 0, s[48:49]
	v_lshl_add_u64 v[82:83], v[82:83], 0, v[0:1]
	s_waitcnt lgkmcnt(0)
	global_store_dwordx4 v[82:83], v[86:89], off nt
	v_mov_b32_e32 v82, v92
	s_nop 1
	v_permlane16_swap_b32_e32 v92, v82
	v_add_f32_e32 v82, v92, v82
	v_mov_b32_e32 v83, v82
	s_nop 1
	v_permlane32_swap_b32_e32 v82, v83
	s_and_saveexec_b64 s[52:53], s[34:35]
	v_readlane_b32 s55, v254, 41
	s_cbranch_execz .LBB0_762
	s_add_u32 s50, s82, s46
	s_addc_u32 s51, s83, s47
	s_ashr_i32 s45, s44, 31
	v_lshl_add_u64 v[84:85], s[44:45], 0, v[174:175]
	v_lshl_add_u64 v[84:85], v[84:85], 2, s[50:51]
	v_add_f32_e32 v82, v82, v83
	global_store_dword v[84:85], v82, off offset:128
; #define PG8_LAS __attribute__((address_space(3)))
; __device__ __forceinline__ unsigned cvt_pk_bf16(float lo, float hi) { unsigned r; asm volatile("v_cvt_pk_bf16_f32 %0, %1, %2" : "=v"(r) : "v"(lo), "v"(hi)); return r; }
; __device__ __forceinline__ float sum_x16(float s) { auto r = __builtin_amdgcn_permlane16_swap(__float_as_uint(s), __float_as_uint(s), false, false); return __uint_as_float(r[0]) + __uint_as_float(r[1]); }
;     __device__ __forceinline__ void operator()(const f32x4 (&acc)[2][2][4][2], const Unit& u, int wr, int wc, int fr, int fq, PG8_LAS unsigned char* stg) const {
;     ...
;         for (int m = 0; m < 4; ++m)
; #pragma unroll
;             for (int i = 0; i < 2; ++i) { const int c = lane + 64 * i; xin[m][i] = *(const u32x4*)(xb + (size_t)(rowb + ai * HALF + m * 16 + (c >> 3)) * 1024 + colw + (c & 7) * 8); }
; #pragma unroll
;         for (int m = 0; m < 4; ++m) {
;             const int row = rowb + ai * HALF + m * 16 + fr;
; #pragma unroll
;             for (int i = 0; i < 2; ++i) { const int c = lane + 64 * i; *(PG8_LAS u32x4*)(stg + (c >> 3) * 144 + (c & 7) * 16) = xin[m][i]; }
;             float ss = 0.f;
; #pragma unroll
;             for (int bj = 0; bj < 2; ++bj) {
;                 const u32x4 xo = *(const PG8_LAS u32x4*)(st + bj * 64);
;                 float v[8];
; #pragma unroll
;                 for (int i = 0; i < 4; ++i) { v[2 * i] = __uint_as_float(xo[i] << 16) + acc[ai][bj][m][i >> 1][(2 * i) & 3]; v[2 * i + 1] = __uint_as_float(xo[i] & 0xffff0000u) + acc[ai][bj][m][i >> 1][(2 * i + 1) & 3]; }
;                 u32x4 w; w.x = cvt_pk_bf16(v[0], v[1]); w.y = cvt_pk_bf16(v[2], v[3]); w.z = cvt_pk_bf16(v[4], v[5]); w.w = cvt_pk_bf16(v[6], v[7]);
;                 *(PG8_LAS u32x4*)(st + bj * 64) = w;
;                 ss += ((v[0] * v[0] + v[1] * v[1]) + (v[2] * v[2] + v[3] * v[3])) + ((v[4] * v[4] + v[5] * v[5]) + (v[6] * v[6] + v[7] * v[7]));
;             }
; #pragma unroll
;             for (int i = 0; i < 2; ++i) { const int c = lane + 64 * i; const u32x4 w = *(const PG8_LAS u32x4*)(stg + (c >> 3) * 144 + (c & 7) * 16);
;                 *(u32x4*)(xo_ + (size_t)(row - fr + (c >> 3)) * 1024 + colw + (c & 7) * 8) = w; }
;             ss = sum_x16(ss); ss = sum_x32(ss);
;             if (fq == 0) po_[(size_t)(u.pn * 4 + wc) * 65536 + row] = ss;
.LBB0_762:
	s_or_b64 exec, exec, s[52:53]
	ds_write_b128 v209, v[130:133]
	ds_write_b128 v209, v[142:145] offset:1152
	ds_read_b128 v[82:85], v210
	s_waitcnt lgkmcnt(0)
	v_lshlrev_b32_e32 v86, 16, v82
	v_and_b32_e32 v82, 0xffff0000, v82
	v_add_f32_e32 v79, v79, v82
	v_and_b32_e32 v82, 0xffff0000, v83
	v_add_f32_e32 v81, v81, v82
	v_lshlrev_b32_e32 v82, 16, v84
	v_add_f32_e32 v82, v74, v82
	v_and_b32_e32 v74, 0xffff0000, v84
	v_lshlrev_b32_e32 v87, 16, v83
	v_add_f32_e32 v83, v75, v74
	v_lshlrev_b32_e32 v74, 16, v85
	v_add_f32_e32 v84, v76, v74
	v_and_b32_e32 v74, 0xffff0000, v85
	v_add_f32_e32 v78, v78, v86
	v_add_f32_e32 v80, v80, v87
	v_add_f32_e32 v85, v77, v74
	v_cvt_pk_bf16_f32 v74, v78, v79
	v_cvt_pk_bf16_f32 v75, v80, v81
	v_cvt_pk_bf16_f32 v76, v82, v83
	v_cvt_pk_bf16_f32 v77, v84, v85
	ds_write_b128 v210, v[74:77]
	v_mul_f32_e32 v74, v79, v79
	v_mul_f32_e32 v75, v81, v81
	v_fmac_f32_e32 v74, v78, v78
	v_fmac_f32_e32 v75, v80, v80
	v_add_f32_e32 v78, v74, v75
	ds_read_b128 v[74:77], v210 offset:64
	v_mul_f32_e32 v79, v83, v83
	v_mul_f32_e32 v80, v85, v85
	v_fmac_f32_e32 v79, v82, v82
	v_fmac_f32_e32 v80, v84, v84
	v_add_f32_e32 v79, v79, v80
	v_add_f32_e32 v78, v78, v79
	s_waitcnt lgkmcnt(0)
	v_lshlrev_b32_e32 v79, 16, v74
	v_and_b32_e32 v74, 0xffff0000, v74
	v_add_f32_e32 v71, v71, v74
	v_lshlrev_b32_e32 v74, 16, v75
	v_add_f32_e32 v72, v72, v74
	v_and_b32_e32 v74, 0xffff0000, v75
	v_add_f32_e32 v73, v73, v74
	v_lshlrev_b32_e32 v74, 16, v76
	v_add_f32_e32 v74, v66, v74
	v_and_b32_e32 v66, 0xffff0000, v76
	v_add_f32_e32 v75, v67, v66
	v_lshlrev_b32_e32 v66, 16, v77
	v_add_f32_e32 v76, v68, v66
	v_and_b32_e32 v66, 0xffff0000, v77
	v_add_f32_e32 v70, v70, v79
	v_add_f32_e32 v77, v69, v66
	v_cvt_pk_bf16_f32 v66, v70, v71
	v_cvt_pk_bf16_f32 v67, v72, v73
	v_cvt_pk_bf16_f32 v68, v74, v75
	v_cvt_pk_bf16_f32 v69, v76, v77
	ds_write_b128 v210, v[66:69] offset:64
	v_mul_f32_e32 v66, v71, v71
	v_mul_f32_e32 v67, v73, v73
	v_fmac_f32_e32 v66, v70, v70
	v_fmac_f32_e32 v67, v72, v72
	v_add_f32_e32 v66, v66, v67
	v_mul_f32_e32 v67, v75, v75
	v_mul_f32_e32 v68, v77, v77
	v_fmac_f32_e32 v67, v74, v74
	v_fmac_f32_e32 v68, v76, v76
	v_add_f32_e32 v67, v67, v68
	v_add_f32_e32 v66, v66, v67
	v_add_f32_e32 v76, v78, v66
	ds_read_b128 v[66:69], v211
	v_lshl_add_u64 v[70:71], s[76:77], 0, v[184:185]
	v_lshl_add_u64 v[70:71], v[70:71], 0, s[48:49]
	v_lshl_add_u64 v[74:75], v[70:71], 0, v[0:1]
	ds_read_b128 v[70:73], v211 offset:1152
	s_waitcnt lgkmcnt(1)
	global_store_dwordx4 v[74:75], v[66:69], off nt
	s_nop 1
	v_lshl_add_u64 v[66:67], s[76:77], 0, v[190:191]
	v_lshl_add_u64 v[66:67], v[66:67], 0, s[48:49]
	v_lshl_add_u64 v[66:67], v[66:67], 0, v[0:1]
	s_waitcnt lgkmcnt(0)
	global_store_dwordx4 v[66:67], v[70:73], off nt
	v_mov_b32_e32 v66, v76
	s_nop 1
	v_permlane16_swap_b32_e32 v76, v66
	v_add_f32_e32 v66, v76, v66
	v_mov_b32_e32 v67, v66
	s_nop 1
	v_permlane32_swap_b32_e32 v66, v67
	s_and_saveexec_b64 s[52:53], s[34:35]
	s_cbranch_execz .LBB0_764
	s_add_u32 s50, s82, s46
	s_addc_u32 s51, s83, s47
	s_ashr_i32 s45, s44, 31
	v_lshl_add_u64 v[68:69], s[44:45], 0, v[174:175]
	v_lshl_add_u64 v[68:69], v[68:69], 2, s[50:51]
	v_add_f32_e32 v66, v66, v67
	global_store_dword v[68:69], v66, off offset:192
.LBB0_764:
	s_or_b64 exec, exec, s[52:53]
	s_add_i32 s29, s44, 0x80
	v_or_b32_e32 v66, s29, v206
	v_ashrrev_i32_e32 v67, 31, v66
	v_lshlrev_b64 v[104:105], 11, v[66:67]
	v_lshl_add_u64 v[66:67], v[182:183], 0, v[104:105]
	global_load_dwordx4 v[106:109], v[66:67], off
	v_or_b32_e32 v66, s29, v207
	v_ashrrev_i32_e32 v67, 31, v66
	v_lshlrev_b64 v[102:103], 11, v[66:67]
	v_lshl_add_u64 v[66:67], v[182:183], 0, v[102:103]
	global_load_dwordx4 v[110:113], v[66:67], off
	s_add_i32 s29, s44, 0x90
	v_or_b32_e32 v66, s29, v206
	v_ashrrev_i32_e32 v67, 31, v66
	v_lshlrev_b64 v[100:101], 11, v[66:67]
	v_lshl_add_u64 v[66:67], v[182:183], 0, v[100:101]
	global_load_dwordx4 v[82:85], v[66:67], off
	v_or_b32_e32 v66, s29, v207
	v_ashrrev_i32_e32 v67, 31, v66
	v_lshlrev_b64 v[98:99], 11, v[66:67]
	v_lshl_add_u64 v[66:67], v[182:183], 0, v[98:99]
	s_add_i32 s29, s44, 0xa0
	global_load_dwordx4 v[86:89], v[66:67], off
	v_or_b32_e32 v66, s29, v206
	v_ashrrev_i32_e32 v67, 31, v66
	v_lshlrev_b64 v[94:95], 11, v[66:67]
	v_lshl_add_u64 v[66:67], v[182:183], 0, v[94:95]
	global_load_dwordx4 v[70:73], v[66:67], off
	v_or_b32_e32 v66, s29, v207
	v_ashrrev_i32_e32 v67, 31, v66
	v_lshlrev_b64 v[92:93], 11, v[66:67]
	v_lshl_add_u64 v[66:67], v[182:183], 0, v[92:93]
	s_add_i32 s29, s44, 0xb0
	global_load_dwordx4 v[74:77], v[66:67], off
	v_or_b32_e32 v66, s29, v206
	v_or_b32_e32 v78, s29, v207
	v_ashrrev_i32_e32 v67, 31, v66
	v_ashrrev_i32_e32 v79, 31, v78
	v_lshlrev_b64 v[90:91], 11, v[66:67]
	v_lshlrev_b64 v[96:97], 11, v[78:79]
	v_lshl_add_u64 v[66:67], v[182:183], 0, v[90:91]
	v_lshl_add_u64 v[78:79], v[182:183], 0, v[96:97]
	global_load_dwordx4 v[66:69], v[66:67], off
	s_nop 0
	global_load_dwordx4 v[78:81], v[78:79], off
	s_waitcnt vmcnt(7)
	ds_write_b128 v209, v[106:109]
	s_waitcnt vmcnt(6)
	ds_write_b128 v209, v[110:113] offset:1152
	ds_read_b128 v[106:109], v210
	s_waitcnt lgkmcnt(0)
; #define PG8_LAS __attribute__((address_space(3)))
; __device__ __forceinline__ unsigned cvt_pk_bf16(float lo, float hi) { unsigned r; asm volatile("v_cvt_pk_bf16_f32 %0, %1, %2" : "=v"(r) : "v"(lo), "v"(hi)); return r; }
; __device__ __forceinline__ float sum_x16(float s) { auto r = __builtin_amdgcn_permlane16_swap(__float_as_uint(s), __float_as_uint(s), false, false); return __uint_as_float(r[0]) + __uint_as_float(r[1]); }
; __device__ __forceinline__ float sum_x32(float s) { auto r = __builtin_amdgcn_permlane32_swap(__float_as_uint(s), __float_as_uint(s), false, false); return __uint_as_float(r[0]) + __uint_as_float(r[1]); }
;     __device__ __forceinline__ void operator()(const f32x4 (&acc)[2][2][4][2], const Unit& u, int wr, int wc, int fr, int fq, PG8_LAS unsigned char* stg) const {
;     ...
;         for (int m = 0; m < 4; ++m) {
;             const int row = rowb + ai * HALF + m * 16 + fr;
; #pragma unroll
;             for (int i = 0; i < 2; ++i) { const int c = lane + 64 * i; *(PG8_LAS u32x4*)(stg + (c >> 3) * 144 + (c & 7) * 16) = xin[m][i]; }
;             float ss = 0.f;
; #pragma unroll
;             for (int bj = 0; bj < 2; ++bj) {
;                 const u32x4 xo = *(const PG8_LAS u32x4*)(st + bj * 64);
;                 float v[8];
; #pragma unroll
;                 for (int i = 0; i < 4; ++i) { v[2 * i] = __uint_as_float(xo[i] << 16) + acc[ai][bj][m][i >> 1][(2 * i) & 3]; v[2 * i + 1] = __uint_as_float(xo[i] & 0xffff0000u) + acc[ai][bj][m][i >> 1][(2 * i + 1) & 3]; }
;                 u32x4 w; w.x = cvt_pk_bf16(v[0], v[1]); w.y = cvt_pk_bf16(v[2], v[3]); w.z = cvt_pk_bf16(v[4], v[5]); w.w = cvt_pk_bf16(v[6], v[7]);
;                 *(PG8_LAS u32x4*)(st + bj * 64) = w;
;                 ss += ((v[0] * v[0] + v[1] * v[1]) + (v[2] * v[2] + v[3] * v[3])) + ((v[4] * v[4] + v[5] * v[5]) + (v[6] * v[6] + v[7] * v[7]));
;             }
; #pragma unroll
;             for (int i = 0; i < 2; ++i) { const int c = lane + 64 * i; const u32x4 w = *(const PG8_LAS u32x4*)(stg + (c >> 3) * 144 + (c & 7) * 16);
;                 *(u32x4*)(xo_ + (size_t)(row - fr + (c >> 3)) * 1024 + colw + (c & 7) * 8) = w; }
;             ss = sum_x16(ss); ss = sum_x32(ss);
;             if (fq == 0) po_[(size_t)(u.pn * 4 + wc) * 65536 + row] = ss;
	v_lshlrev_b32_e32 v110, 16, v106
	v_and_b32_e32 v106, 0xffff0000, v106
	v_add_f32_e32 v63, v63, v106
	v_lshlrev_b32_e32 v106, 16, v107
	v_add_f32_e32 v64, v64, v106
	v_and_b32_e32 v106, 0xffff0000, v107
	v_add_f32_e32 v65, v65, v106
	v_lshlrev_b32_e32 v106, 16, v108
	v_add_f32_e32 v106, v58, v106
	v_and_b32_e32 v58, 0xffff0000, v108
	v_add_f32_e32 v107, v59, v58
	v_lshlrev_b32_e32 v58, 16, v109
	v_add_f32_e32 v108, v60, v58
	v_and_b32_e32 v58, 0xffff0000, v109
	v_add_f32_e32 v62, v62, v110
	v_add_f32_e32 v109, v61, v58
	v_cvt_pk_bf16_f32 v58, v62, v63
	v_cvt_pk_bf16_f32 v59, v64, v65
	v_cvt_pk_bf16_f32 v60, v106, v107
	v_cvt_pk_bf16_f32 v61, v108, v109
	ds_write_b128 v210, v[58:61]
	v_mul_f32_e32 v58, v63, v63
	v_mul_f32_e32 v59, v65, v65
	v_fmac_f32_e32 v58, v62, v62
	v_fmac_f32_e32 v59, v64, v64
	v_add_f32_e32 v58, v58, v59
	v_mul_f32_e32 v59, v107, v107
	v_mul_f32_e32 v60, v109, v109
	v_fmac_f32_e32 v59, v106, v106
	v_fmac_f32_e32 v60, v108, v108
	v_add_f32_e32 v59, v59, v60
	v_add_f32_e32 v62, v58, v59
	ds_read_b128 v[58:61], v210 offset:64
	s_waitcnt lgkmcnt(0)
	v_lshlrev_b32_e32 v63, 16, v58
	v_and_b32_e32 v58, 0xffff0000, v58
	v_add_f32_e32 v55, v55, v58
	v_lshlrev_b32_e32 v58, 16, v59
	v_add_f32_e32 v56, v56, v58
	v_and_b32_e32 v58, 0xffff0000, v59
	v_add_f32_e32 v57, v57, v58
	v_lshlrev_b32_e32 v58, 16, v60
	v_add_f32_e32 v58, v50, v58
	v_and_b32_e32 v50, 0xffff0000, v60
	v_add_f32_e32 v59, v51, v50
	v_lshlrev_b32_e32 v50, 16, v61
	v_add_f32_e32 v60, v52, v50
	v_and_b32_e32 v50, 0xffff0000, v61
	v_add_f32_e32 v54, v54, v63
	v_add_f32_e32 v61, v53, v50
	v_cvt_pk_bf16_f32 v50, v54, v55
	v_cvt_pk_bf16_f32 v51, v56, v57
	v_cvt_pk_bf16_f32 v52, v58, v59
	v_cvt_pk_bf16_f32 v53, v60, v61
	ds_write_b128 v210, v[50:53] offset:64
	v_mul_f32_e32 v50, v55, v55
	v_mul_f32_e32 v51, v57, v57
	v_fmac_f32_e32 v50, v54, v54
	v_fmac_f32_e32 v51, v56, v56
	v_add_f32_e32 v50, v50, v51
	v_mul_f32_e32 v51, v59, v59
	v_mul_f32_e32 v52, v61, v61
	v_fmac_f32_e32 v51, v58, v58
	v_fmac_f32_e32 v52, v60, v60
	v_add_f32_e32 v51, v51, v52
	v_add_f32_e32 v50, v50, v51
	v_add_f32_e32 v56, v62, v50
	ds_read_b128 v[50:53], v211
	v_lshl_add_u64 v[54:55], s[76:77], 0, v[104:105]
	v_lshl_add_u64 v[54:55], v[54:55], 0, s[48:49]
	v_lshl_add_u64 v[54:55], v[54:55], 0, v[0:1]
	s_waitcnt lgkmcnt(0)
	global_store_dwordx4 v[54:55], v[50:53], off nt
	ds_read_b128 v[50:53], v211 offset:1152
	v_lshl_add_u64 v[54:55], s[76:77], 0, v[102:103]
	v_lshl_add_u64 v[54:55], v[54:55], 0, s[48:49]
	v_lshl_add_u64 v[54:55], v[54:55], 0, v[0:1]
	s_waitcnt lgkmcnt(0)
	global_store_dwordx4 v[54:55], v[50:53], off nt
	s_nop 1
	v_mov_b32_e32 v50, v56
	s_nop 1
	v_permlane16_swap_b32_e32 v56, v50
	v_add_f32_e32 v50, v56, v50
	v_mov_b32_e32 v51, v50
	s_nop 1
	v_permlane32_swap_b32_e32 v50, v51
	s_and_saveexec_b64 s[52:53], s[34:35]
	s_cbranch_execz .LBB0_766
	s_add_u32 s50, s82, s46
	s_addc_u32 s51, s83, s47
	s_ashr_i32 s45, s44, 31
	v_lshl_add_u64 v[52:53], s[44:45], 0, v[174:175]
	v_lshl_add_u64 v[52:53], v[52:53], 2, s[50:51]
	v_add_f32_e32 v50, v50, v51
	global_store_dword v[52:53], v50, off offset:512
.LBB0_766:
	s_or_b64 exec, exec, s[52:53]
	s_waitcnt vmcnt(7)
	ds_write_b128 v209, v[82:85]
	s_waitcnt vmcnt(6)
	ds_write_b128 v209, v[86:89] offset:1152
	ds_read_b128 v[50:53], v210
	s_waitcnt lgkmcnt(0)
	v_lshlrev_b32_e32 v54, 16, v50
	v_and_b32_e32 v50, 0xffff0000, v50
	v_add_f32_e32 v47, v47, v50
	v_and_b32_e32 v50, 0xffff0000, v51
	v_add_f32_e32 v49, v49, v50
	v_lshlrev_b32_e32 v50, 16, v52
	v_add_f32_e32 v50, v42, v50
	v_and_b32_e32 v42, 0xffff0000, v52
	v_lshlrev_b32_e32 v55, 16, v51
	v_add_f32_e32 v51, v43, v42
	v_lshlrev_b32_e32 v42, 16, v53
	v_add_f32_e32 v52, v44, v42
	v_and_b32_e32 v42, 0xffff0000, v53
	v_add_f32_e32 v46, v46, v54
	v_add_f32_e32 v48, v48, v55
	v_add_f32_e32 v53, v45, v42
	v_cvt_pk_bf16_f32 v42, v46, v47
	v_cvt_pk_bf16_f32 v43, v48, v49
	v_cvt_pk_bf16_f32 v44, v50, v51
	v_cvt_pk_bf16_f32 v45, v52, v53
	ds_write_b128 v210, v[42:45]
	v_mul_f32_e32 v42, v47, v47
	v_mul_f32_e32 v43, v49, v49
	v_fmac_f32_e32 v42, v46, v46
	v_fmac_f32_e32 v43, v48, v48
	v_add_f32_e32 v46, v42, v43
	ds_read_b128 v[42:45], v210 offset:64
	v_mul_f32_e32 v47, v51, v51
	v_mul_f32_e32 v48, v53, v53
	v_fmac_f32_e32 v47, v50, v50
	v_fmac_f32_e32 v48, v52, v52
	v_add_f32_e32 v47, v47, v48
	v_add_f32_e32 v46, v46, v47
	s_waitcnt lgkmcnt(0)
	v_lshlrev_b32_e32 v47, 16, v42
	v_and_b32_e32 v42, 0xffff0000, v42
	v_add_f32_e32 v39, v39, v42
	v_lshlrev_b32_e32 v42, 16, v43
	v_add_f32_e32 v40, v40, v42
	v_and_b32_e32 v42, 0xffff0000, v43
	v_add_f32_e32 v41, v41, v42
	v_lshlrev_b32_e32 v42, 16, v44
	v_add_f32_e32 v42, v34, v42
	v_and_b32_e32 v34, 0xffff0000, v44
	v_add_f32_e32 v43, v35, v34
	v_lshlrev_b32_e32 v34, 16, v45
	v_add_f32_e32 v44, v36, v34
	v_and_b32_e32 v34, 0xffff0000, v45
	v_add_f32_e32 v38, v38, v47
	v_add_f32_e32 v45, v37, v34
	v_cvt_pk_bf16_f32 v34, v38, v39
	v_cvt_pk_bf16_f32 v35, v40, v41
	v_cvt_pk_bf16_f32 v36, v42, v43
	v_cvt_pk_bf16_f32 v37, v44, v45
	ds_write_b128 v210, v[34:37] offset:64
	v_mul_f32_e32 v34, v39, v39
	v_mul_f32_e32 v35, v41, v41
	v_fmac_f32_e32 v34, v38, v38
	v_fmac_f32_e32 v35, v40, v40
	v_add_f32_e32 v34, v34, v35
	v_mul_f32_e32 v35, v43, v43
	v_mul_f32_e32 v36, v45, v45
	v_fmac_f32_e32 v35, v42, v42
	v_fmac_f32_e32 v36, v44, v44
	v_add_f32_e32 v35, v35, v36
	v_add_f32_e32 v34, v34, v35
	v_add_f32_e32 v44, v46, v34
	ds_read_b128 v[34:37], v211
	v_lshl_add_u64 v[38:39], s[76:77], 0, v[100:101]
	v_lshl_add_u64 v[38:39], v[38:39], 0, s[48:49]
	v_lshl_add_u64 v[42:43], v[38:39], 0, v[0:1]
	ds_read_b128 v[38:41], v211 offset:1152
	s_waitcnt lgkmcnt(1)
	global_store_dwordx4 v[42:43], v[34:37], off nt
	s_nop 1
	v_lshl_add_u64 v[34:35], s[76:77], 0, v[98:99]
	v_lshl_add_u64 v[34:35], v[34:35], 0, s[48:49]
	v_lshl_add_u64 v[34:35], v[34:35], 0, v[0:1]
	s_waitcnt lgkmcnt(0)
	global_store_dwordx4 v[34:35], v[38:41], off nt
	v_mov_b32_e32 v34, v44
	s_nop 1
	v_permlane16_swap_b32_e32 v44, v34
	v_add_f32_e32 v34, v44, v34
	v_mov_b32_e32 v35, v34
	s_nop 1
	v_permlane32_swap_b32_e32 v34, v35
	s_and_saveexec_b64 s[52:53], s[34:35]
	s_cbranch_execz .LBB0_768
	s_add_u32 s50, s82, s46
	s_addc_u32 s51, s83, s47
	s_ashr_i32 s45, s44, 31
	v_lshl_add_u64 v[36:37], s[44:45], 0, v[174:175]
	v_lshl_add_u64 v[36:37], v[36:37], 2, s[50:51]
	v_add_f32_e32 v34, v34, v35
	global_store_dword v[36:37], v34, off offset:576
; #define PG8_LAS __attribute__((address_space(3)))
; __device__ __forceinline__ unsigned cvt_pk_bf16(float lo, float hi) { unsigned r; asm volatile("v_cvt_pk_bf16_f32 %0, %1, %2" : "=v"(r) : "v"(lo), "v"(hi)); return r; }
; __device__ __forceinline__ float sum_x16(float s) { auto r = __builtin_amdgcn_permlane16_swap(__float_as_uint(s), __float_as_uint(s), false, false); return __uint_as_float(r[0]) + __uint_as_float(r[1]); }
; __device__ __forceinline__ float sum_x32(float s) { auto r = __builtin_amdgcn_permlane32_swap(__float_as_uint(s), __float_as_uint(s), false, false); return __uint_as_float(r[0]) + __uint_as_float(r[1]); }
;     __device__ __forceinline__ void operator()(const f32x4 (&acc)[2][2][4][2], const Unit& u, int wr, int wc, int fr, int fq, PG8_LAS unsigned char* stg) const {
;     ...
;         for (int m = 0; m < 4; ++m) {
;             const int row = rowb + ai * HALF + m * 16 + fr;
; #pragma unroll
;             for (int i = 0; i < 2; ++i) { const int c = lane + 64 * i; *(PG8_LAS u32x4*)(stg + (c >> 3) * 144 + (c & 7) * 16) = xin[m][i]; }
;             float ss = 0.f;
; #pragma unroll
;             for (int bj = 0; bj < 2; ++bj) {
;                 const u32x4 xo = *(const PG8_LAS u32x4*)(st + bj * 64);
;                 float v[8];
; #pragma unroll
;                 for (int i = 0; i < 4; ++i) { v[2 * i] = __uint_as_float(xo[i] << 16) + acc[ai][bj][m][i >> 1][(2 * i) & 3]; v[2 * i + 1] = __uint_as_float(xo[i] & 0xffff0000u) + acc[ai][bj][m][i >> 1][(2 * i + 1) & 3]; }
;                 u32x4 w; w.x = cvt_pk_bf16(v[0], v[1]); w.y = cvt_pk_bf16(v[2], v[3]); w.z = cvt_pk_bf16(v[4], v[5]); w.w = cvt_pk_bf16(v[6], v[7]);
;                 *(PG8_LAS u32x4*)(st + bj * 64) = w;
;                 ss += ((v[0] * v[0] + v[1] * v[1]) + (v[2] * v[2] + v[3] * v[3])) + ((v[4] * v[4] + v[5] * v[5]) + (v[6] * v[6] + v[7] * v[7]));
;             }
; #pragma unroll
;             for (int i = 0; i < 2; ++i) { const int c = lane + 64 * i; const u32x4 w = *(const PG8_LAS u32x4*)(stg + (c >> 3) * 144 + (c & 7) * 16);
;                 *(u32x4*)(xo_ + (size_t)(row - fr + (c >> 3)) * 1024 + colw + (c & 7) * 8) = w; }
;             ss = sum_x16(ss); ss = sum_x32(ss);
;             if (fq == 0) po_[(size_t)(u.pn * 4 + wc) * 65536 + row] = ss;
.LBB0_768:
	s_or_b64 exec, exec, s[52:53]
	s_waitcnt vmcnt(7)
	ds_write_b128 v209, v[70:73]
	s_waitcnt vmcnt(6)
	ds_write_b128 v209, v[74:77] offset:1152
	ds_read_b128 v[34:37], v210
	s_waitcnt lgkmcnt(0)
	v_lshlrev_b32_e32 v38, 16, v34
	v_and_b32_e32 v34, 0xffff0000, v34
	v_add_f32_e32 v31, v31, v34
	v_and_b32_e32 v34, 0xffff0000, v35
	v_add_f32_e32 v33, v33, v34
	v_lshlrev_b32_e32 v34, 16, v36
	v_add_f32_e32 v34, v26, v34
	v_and_b32_e32 v26, 0xffff0000, v36
	v_lshlrev_b32_e32 v39, 16, v35
	v_add_f32_e32 v35, v27, v26
	v_lshlrev_b32_e32 v26, 16, v37
	v_add_f32_e32 v36, v28, v26
	v_and_b32_e32 v26, 0xffff0000, v37
	v_add_f32_e32 v30, v30, v38
	v_add_f32_e32 v32, v32, v39
	v_add_f32_e32 v37, v29, v26
	v_cvt_pk_bf16_f32 v26, v30, v31
	v_cvt_pk_bf16_f32 v27, v32, v33
	v_cvt_pk_bf16_f32 v28, v34, v35
	v_cvt_pk_bf16_f32 v29, v36, v37
	ds_write_b128 v210, v[26:29]
	v_mul_f32_e32 v26, v31, v31
	v_mul_f32_e32 v27, v33, v33
	v_fmac_f32_e32 v26, v30, v30
	v_fmac_f32_e32 v27, v32, v32
	v_add_f32_e32 v30, v26, v27
	ds_read_b128 v[26:29], v210 offset:64
	v_mul_f32_e32 v31, v35, v35
	v_mul_f32_e32 v32, v37, v37
	v_fmac_f32_e32 v31, v34, v34
	v_fmac_f32_e32 v32, v36, v36
	v_add_f32_e32 v31, v31, v32
	v_add_f32_e32 v30, v30, v31
	s_waitcnt lgkmcnt(0)
	v_lshlrev_b32_e32 v31, 16, v26
	v_and_b32_e32 v26, 0xffff0000, v26
	v_add_f32_e32 v23, v23, v26
	v_lshlrev_b32_e32 v26, 16, v27
	v_add_f32_e32 v24, v24, v26
	v_and_b32_e32 v26, 0xffff0000, v27
	v_add_f32_e32 v25, v25, v26
	v_lshlrev_b32_e32 v26, 16, v28
	v_add_f32_e32 v26, v18, v26
	v_and_b32_e32 v18, 0xffff0000, v28
	v_add_f32_e32 v27, v19, v18
	v_lshlrev_b32_e32 v18, 16, v29
	v_add_f32_e32 v28, v20, v18
	v_and_b32_e32 v18, 0xffff0000, v29
	v_add_f32_e32 v22, v22, v31
	v_add_f32_e32 v29, v21, v18
	v_cvt_pk_bf16_f32 v18, v22, v23
	v_cvt_pk_bf16_f32 v19, v24, v25
	v_cvt_pk_bf16_f32 v20, v26, v27
	v_cvt_pk_bf16_f32 v21, v28, v29
	ds_write_b128 v210, v[18:21] offset:64
	v_mul_f32_e32 v18, v23, v23
	v_mul_f32_e32 v19, v25, v25
	v_fmac_f32_e32 v18, v22, v22
	v_fmac_f32_e32 v19, v24, v24
	v_add_f32_e32 v18, v18, v19
	v_mul_f32_e32 v19, v27, v27
	v_mul_f32_e32 v20, v29, v29
	v_fmac_f32_e32 v19, v26, v26
	v_fmac_f32_e32 v20, v28, v28
	v_add_f32_e32 v19, v19, v20
	v_add_f32_e32 v18, v18, v19
	v_add_f32_e32 v28, v30, v18
	ds_read_b128 v[18:21], v211
	v_lshl_add_u64 v[22:23], s[76:77], 0, v[94:95]
	v_lshl_add_u64 v[22:23], v[22:23], 0, s[48:49]
	v_lshl_add_u64 v[26:27], v[22:23], 0, v[0:1]
	ds_read_b128 v[22:25], v211 offset:1152
	s_waitcnt lgkmcnt(1)
	global_store_dwordx4 v[26:27], v[18:21], off nt
	s_nop 1
	v_lshl_add_u64 v[18:19], s[76:77], 0, v[92:93]
	v_lshl_add_u64 v[18:19], v[18:19], 0, s[48:49]
	v_lshl_add_u64 v[18:19], v[18:19], 0, v[0:1]
	s_waitcnt lgkmcnt(0)
	global_store_dwordx4 v[18:19], v[22:25], off nt
	v_mov_b32_e32 v18, v28
	s_nop 1
	v_permlane16_swap_b32_e32 v28, v18
	v_add_f32_e32 v18, v28, v18
	v_mov_b32_e32 v19, v18
	s_nop 1
	v_permlane32_swap_b32_e32 v18, v19
	s_and_saveexec_b64 s[52:53], s[34:35]
	s_cbranch_execz .LBB0_770
	s_add_u32 s50, s82, s46
	s_addc_u32 s51, s83, s47
	s_ashr_i32 s45, s44, 31
	v_lshl_add_u64 v[20:21], s[44:45], 0, v[174:175]
	v_lshl_add_u64 v[20:21], v[20:21], 2, s[50:51]
	v_add_f32_e32 v18, v18, v19
	global_store_dword v[20:21], v18, off offset:640
.LBB0_770:
	s_or_b64 exec, exec, s[52:53]
	s_waitcnt vmcnt(7)
	ds_write_b128 v209, v[66:69]
	s_waitcnt vmcnt(6)
	ds_write_b128 v209, v[78:81] offset:1152
	ds_read_b128 v[18:21], v210
	s_waitcnt lgkmcnt(0)
	v_lshlrev_b32_e32 v22, 16, v18
	v_and_b32_e32 v18, 0xffff0000, v18
	v_add_f32_e32 v15, v15, v18
	v_and_b32_e32 v18, 0xffff0000, v19
	v_add_f32_e32 v17, v17, v18
	v_lshlrev_b32_e32 v18, 16, v20
	v_add_f32_e32 v18, v10, v18
	v_and_b32_e32 v10, 0xffff0000, v20
	v_lshlrev_b32_e32 v23, 16, v19
	v_add_f32_e32 v19, v11, v10
	v_lshlrev_b32_e32 v10, 16, v21
	v_add_f32_e32 v20, v12, v10
	v_and_b32_e32 v10, 0xffff0000, v21
	v_add_f32_e32 v14, v14, v22
	v_add_f32_e32 v16, v16, v23
	v_add_f32_e32 v21, v13, v10
	v_cvt_pk_bf16_f32 v10, v14, v15
	v_cvt_pk_bf16_f32 v11, v16, v17
	v_cvt_pk_bf16_f32 v12, v18, v19
	v_cvt_pk_bf16_f32 v13, v20, v21
	ds_write_b128 v210, v[10:13]
	v_mul_f32_e32 v10, v15, v15
	v_mul_f32_e32 v11, v17, v17
	v_fmac_f32_e32 v10, v14, v14
	v_fmac_f32_e32 v11, v16, v16
	v_add_f32_e32 v14, v10, v11
	ds_read_b128 v[10:13], v210 offset:64
	v_mul_f32_e32 v15, v19, v19
	v_mul_f32_e32 v16, v21, v21
	v_fmac_f32_e32 v15, v18, v18
	v_fmac_f32_e32 v16, v20, v20
	v_add_f32_e32 v15, v15, v16
	v_add_f32_e32 v14, v14, v15
	s_waitcnt lgkmcnt(0)
	v_lshlrev_b32_e32 v15, 16, v10
	v_and_b32_e32 v10, 0xffff0000, v10
	v_add_f32_e32 v7, v7, v10
	v_lshlrev_b32_e32 v10, 16, v11
	v_add_f32_e32 v8, v8, v10
	v_and_b32_e32 v10, 0xffff0000, v11
	v_add_f32_e32 v9, v9, v10
	v_lshlrev_b32_e32 v10, 16, v12
	v_add_f32_e32 v10, v2, v10
	v_and_b32_e32 v2, 0xffff0000, v12
	v_add_f32_e32 v11, v3, v2
	v_lshlrev_b32_e32 v2, 16, v13
	v_add_f32_e32 v12, v4, v2
	v_and_b32_e32 v2, 0xffff0000, v13
	v_add_f32_e32 v6, v6, v15
	v_add_f32_e32 v13, v5, v2
	v_cvt_pk_bf16_f32 v2, v6, v7
	v_cvt_pk_bf16_f32 v3, v8, v9
	v_cvt_pk_bf16_f32 v4, v10, v11
	v_cvt_pk_bf16_f32 v5, v12, v13
	ds_write_b128 v210, v[2:5] offset:64
	v_mul_f32_e32 v2, v7, v7
	v_mul_f32_e32 v3, v9, v9
	v_fmac_f32_e32 v2, v6, v6
	v_fmac_f32_e32 v3, v8, v8
	v_add_f32_e32 v2, v2, v3
	v_mul_f32_e32 v3, v11, v11
	v_mul_f32_e32 v4, v13, v13
	v_fmac_f32_e32 v3, v10, v10
	v_fmac_f32_e32 v4, v12, v12
	v_add_f32_e32 v3, v3, v4
	v_add_f32_e32 v2, v2, v3
	v_add_f32_e32 v12, v14, v2
	ds_read_b128 v[2:5], v211
	v_lshl_add_u64 v[6:7], s[76:77], 0, v[90:91]
	v_lshl_add_u64 v[6:7], v[6:7], 0, s[48:49]
	v_lshl_add_u64 v[10:11], v[6:7], 0, v[0:1]
	ds_read_b128 v[6:9], v211 offset:1152
	s_waitcnt lgkmcnt(1)
	global_store_dwordx4 v[10:11], v[2:5], off nt
	s_nop 1
	v_lshl_add_u64 v[2:3], s[76:77], 0, v[96:97]
	v_lshl_add_u64 v[2:3], v[2:3], 0, s[48:49]
	v_lshl_add_u64 v[2:3], v[2:3], 0, v[0:1]
	s_waitcnt lgkmcnt(0)
	global_store_dwordx4 v[2:3], v[6:9], off nt
	v_mov_b32_e32 v2, v12
	s_nop 1
	v_permlane16_swap_b32_e32 v12, v2
	v_add_f32_e32 v2, v12, v2
	v_mov_b32_e32 v3, v2
	s_nop 1
	v_permlane32_swap_b32_e32 v2, v3
	s_and_saveexec_b64 s[48:49], s[34:35]
	s_cbranch_execz .LBB0_772
	s_add_u32 s46, s82, s46
	s_addc_u32 s47, s83, s47
	s_ashr_i32 s45, s44, 31
	v_lshl_add_u64 v[4:5], s[44:45], 0, v[174:175]
	v_lshl_add_u64 v[4:5], v[4:5], 2, s[46:47]
	v_add_f32_e32 v2, v2, v3
	global_store_dword v[4:5], v2, off offset:704

; #define PG8_LAS __attribute__((address_space(3)))
; __device__ __forceinline__ unsigned cvt_pk_bf16(float lo, float hi) { unsigned r; asm volatile("v_cvt_pk_bf16_f32 %0, %1, %2" : "=v"(r) : "v"(lo), "v"(hi)); return r; }
;     __device__ __forceinline__ void operator()(const f32x4 (&acc)[2][2][4][2], const Unit& u, int wr, int wc, int fr, int fq, PG8_LAS float* stash, int par, PG8_LAS unsigned char* stg, const Unit& un) const {
;     ...
;         float rsa[2][4];
; #pragma unroll
;         for (int ai = 0; ai < 2; ++ai)
; #pragma unroll
;             for (int m = 0; m < 4; ++m) rsa[ai][m] = stash[par * 256 + ai * HALF + wr * 64 + m * 16 + fr];
; #pragma unroll
;         for (int ai = 0; ai < 2; ++ai)
; #pragma unroll
;             for (int m = 0; m < 4; ++m) {
;                 const int row = u.pm * BM + ai * HALF + wr * 64 + m * 16 + fr;
;                 const float rs = rsa[ai][m];
;                 PG8_LAS unsigned char* st = stg + fr * 144 + fq * 16;
; #pragma unroll
;                 for (int bj = 0; bj < 2; ++bj) {
;                     float v[8];
; #pragma unroll
;                     for (int i = 0; i < 4; ++i) { v[i] = acc[ai][bj][m][0][i] * rs; v[4 + i] = acc[ai][bj][m][1][i] * rs; }
; #pragma unroll
;                     for (int i = 0; i < 8; ++i) { const float r = fmaxf(v[i], 0.f); v[i] = r * r; }
;                     u32x4 w; w.x = cvt_pk_bf16(v[0], v[1]); w.y = cvt_pk_bf16(v[2], v[3]); w.z = cvt_pk_bf16(v[4], v[5]); w.w = cvt_pk_bf16(v[6], v[7]);
;                     *(PG8_LAS u32x4*)(st + bj * 64) = w;
;                 }
; #pragma unroll
;                 for (int i = 0; i < 2; ++i) { const int c = fq * 16 + fr + 64 * i, rr = c >> 3, pc = c & 7;
;                     const u32x4 w = *(const PG8_LAS u32x4*)(stg + rr * 144 + pc * 16);
;                     __builtin_nontemporal_store(w, (u32x4*)(uo + (size_t)(row - fr + rr) * 4096 + u.pn * BM + wc * 64 + pc * 8)); }
;             }
.LBB0_848:
	v_lshl_add_u32 v144, v157, 10, v152
	ds_read2_b32 v[160:161], v144 offset1:16
	ds_read2_b32 v[148:149], v144 offset0:32 offset1:48
	ds_read2_b32 v[146:147], v144 offset0:128 offset1:144
	ds_read2_b32 v[144:145], v144 offset0:160 offset1:176
	s_lshl_b32 s16, s14, 8
	s_add_i32 s16, s16, s1
	s_lshl_b32 s100, s16, 13
	s_add_u32 s98, s78, s100
	s_addc_u32 s99, s79, 0
	s_lshl_b32 s100, s15, 9
	s_add_u32 s98, s98, s100
	s_addc_u32 s99, s99, 0
	s_add_u32 s98, s98, s74
	s_addc_u32 s99, s99, s75
	v_lshl_add_u32 v200, v153, 13, v0
	v_add_u32_e32 v201, 0x10000, v200
	s_waitcnt lgkmcnt(0)
	v_pk_mul_f32 v[126:127], v[126:127], v[160:161] op_sel_hi:[1,0]
	v_pk_mul_f32 v[128:129], v[128:129], v[160:161] op_sel_hi:[1,0]
	v_pk_mul_f32 v[122:123], v[122:123], v[160:161] op_sel_hi:[1,0]
	v_pk_mul_f32 v[124:125], v[124:125], v[160:161] op_sel_hi:[1,0]
	v_max_f32_e32 v126, 0, v126
	v_max_f32_e32 v127, 0, v127
	v_max_f32_e32 v128, 0, v128
	v_max_f32_e32 v129, 0, v129
	v_max_f32_e32 v122, 0, v122
	v_max_f32_e32 v123, 0, v123
	v_max_f32_e32 v124, 0, v124
	v_max_f32_e32 v125, 0, v125
	v_pk_mul_f32 v[126:127], v[126:127], v[126:127]
	v_pk_mul_f32 v[128:129], v[128:129], v[128:129]
	v_pk_mul_f32 v[122:123], v[122:123], v[122:123]
	v_pk_mul_f32 v[124:125], v[124:125], v[124:125]
	v_cvt_pk_bf16_f32 v126, v126, v127
	v_cvt_pk_bf16_f32 v127, v128, v129
	v_cvt_pk_bf16_f32 v128, v122, v123
	v_cvt_pk_bf16_f32 v129, v124, v125
	v_pk_mul_f32 v[118:119], v[118:119], v[160:161] op_sel_hi:[1,0]
	v_pk_mul_f32 v[120:121], v[120:121], v[160:161] op_sel_hi:[1,0]
	v_pk_mul_f32 v[114:115], v[114:115], v[160:161] op_sel_hi:[1,0]
	v_pk_mul_f32 v[116:117], v[116:117], v[160:161] op_sel_hi:[1,0]
	v_max_f32_e32 v118, 0, v118
	v_max_f32_e32 v119, 0, v119
	v_max_f32_e32 v120, 0, v120
	v_max_f32_e32 v121, 0, v121
	v_max_f32_e32 v114, 0, v114
	v_max_f32_e32 v115, 0, v115
	v_max_f32_e32 v116, 0, v116
	v_max_f32_e32 v117, 0, v117
	v_pk_mul_f32 v[118:119], v[118:119], v[118:119]
	v_pk_mul_f32 v[120:121], v[120:121], v[120:121]
	v_pk_mul_f32 v[114:115], v[114:115], v[114:115]
	v_pk_mul_f32 v[116:117], v[116:117], v[116:117]
	v_cvt_pk_bf16_f32 v118, v118, v119
	v_cvt_pk_bf16_f32 v119, v120, v121
	v_cvt_pk_bf16_f32 v120, v114, v115
	v_cvt_pk_bf16_f32 v121, v116, v117
	ds_write_b128 v156, v[126:129]
	ds_write_b128 v156, v[118:121] offset:64
	ds_read_b128 v[204:207], v158
	ds_read_b128 v[208:211], v158 offset:1152
	v_pk_mul_f32 v[110:111], v[110:111], v[160:161] op_sel:[0,1]
	v_pk_mul_f32 v[112:113], v[112:113], v[160:161] op_sel:[0,1]
	v_pk_mul_f32 v[106:107], v[106:107], v[160:161] op_sel:[0,1]
	v_pk_mul_f32 v[108:109], v[108:109], v[160:161] op_sel:[0,1]
	v_max_f32_e32 v110, 0, v110
	v_max_f32_e32 v111, 0, v111
	v_max_f32_e32 v112, 0, v112
	v_max_f32_e32 v113, 0, v113
	v_max_f32_e32 v106, 0, v106
	v_max_f32_e32 v107, 0, v107
	v_max_f32_e32 v108, 0, v108
	v_max_f32_e32 v109, 0, v109
	v_pk_mul_f32 v[110:111], v[110:111], v[110:111]
	v_pk_mul_f32 v[112:113], v[112:113], v[112:113]
	v_pk_mul_f32 v[106:107], v[106:107], v[106:107]
	v_pk_mul_f32 v[108:109], v[108:109], v[108:109]
	v_cvt_pk_bf16_f32 v110, v110, v111
	v_cvt_pk_bf16_f32 v111, v112, v113
	v_cvt_pk_bf16_f32 v112, v106, v107
	v_cvt_pk_bf16_f32 v113, v108, v109
	v_pk_mul_f32 v[102:103], v[102:103], v[160:161] op_sel:[0,1]
	v_pk_mul_f32 v[104:105], v[104:105], v[160:161] op_sel:[0,1]
	v_pk_mul_f32 v[98:99], v[98:99], v[160:161] op_sel:[0,1]
	v_pk_mul_f32 v[100:101], v[100:101], v[160:161] op_sel:[0,1]
	v_max_f32_e32 v102, 0, v102
	v_max_f32_e32 v103, 0, v103
	v_max_f32_e32 v104, 0, v104
	v_max_f32_e32 v105, 0, v105
	v_max_f32_e32 v98, 0, v98
	v_max_f32_e32 v99, 0, v99
	v_max_f32_e32 v100, 0, v100
	v_max_f32_e32 v101, 0, v101
	v_pk_mul_f32 v[102:103], v[102:103], v[102:103]
	v_pk_mul_f32 v[104:105], v[104:105], v[104:105]
	v_pk_mul_f32 v[98:99], v[98:99], v[98:99]
	v_pk_mul_f32 v[100:101], v[100:101], v[100:101]
	v_cvt_pk_bf16_f32 v102, v102, v103
	v_cvt_pk_bf16_f32 v103, v104, v105
	v_cvt_pk_bf16_f32 v104, v98, v99
	v_cvt_pk_bf16_f32 v105, v100, v101
	s_waitcnt lgkmcnt(0)
	global_store_dwordx4 v200, v[204:207], s[98:99] nt
	global_store_dwordx4 v201, v[208:211], s[98:99] nt
	ds_write_b128 v156, v[110:113]
	ds_write_b128 v156, v[102:105] offset:64
	ds_read_b128 v[212:215], v158
	ds_read_b128 v[216:219], v158 offset:1152
	v_pk_mul_f32 v[94:95], v[94:95], v[148:149] op_sel_hi:[1,0]
	v_pk_mul_f32 v[96:97], v[96:97], v[148:149] op_sel_hi:[1,0]
	v_pk_mul_f32 v[90:91], v[90:91], v[148:149] op_sel_hi:[1,0]
	v_pk_mul_f32 v[92:93], v[92:93], v[148:149] op_sel_hi:[1,0]
	v_max_f32_e32 v94, 0, v94
	v_max_f32_e32 v95, 0, v95
	v_max_f32_e32 v96, 0, v96
	v_max_f32_e32 v97, 0, v97
	v_max_f32_e32 v90, 0, v90
	v_max_f32_e32 v91, 0, v91
	v_max_f32_e32 v92, 0, v92
	v_max_f32_e32 v93, 0, v93
	v_pk_mul_f32 v[94:95], v[94:95], v[94:95]
	v_pk_mul_f32 v[96:97], v[96:97], v[96:97]
	v_pk_mul_f32 v[90:91], v[90:91], v[90:91]
	v_pk_mul_f32 v[92:93], v[92:93], v[92:93]
	v_cvt_pk_bf16_f32 v94, v94, v95
	v_cvt_pk_bf16_f32 v95, v96, v97
	v_cvt_pk_bf16_f32 v96, v90, v91
	v_cvt_pk_bf16_f32 v97, v92, v93
	v_pk_mul_f32 v[86:87], v[86:87], v[148:149] op_sel_hi:[1,0]
	v_pk_mul_f32 v[88:89], v[88:89], v[148:149] op_sel_hi:[1,0]
	v_pk_mul_f32 v[82:83], v[82:83], v[148:149] op_sel_hi:[1,0]
	v_pk_mul_f32 v[84:85], v[84:85], v[148:149] op_sel_hi:[1,0]
	v_max_f32_e32 v86, 0, v86
	v_max_f32_e32 v87, 0, v87
	v_max_f32_e32 v88, 0, v88
	v_max_f32_e32 v89, 0, v89
	v_max_f32_e32 v82, 0, v82
	v_max_f32_e32 v83, 0, v83
	v_max_f32_e32 v84, 0, v84
	v_max_f32_e32 v85, 0, v85
	v_pk_mul_f32 v[86:87], v[86:87], v[86:87]
	v_pk_mul_f32 v[88:89], v[88:89], v[88:89]
	v_pk_mul_f32 v[82:83], v[82:83], v[82:83]
	v_pk_mul_f32 v[84:85], v[84:85], v[84:85]
	v_cvt_pk_bf16_f32 v86, v86, v87
	v_cvt_pk_bf16_f32 v87, v88, v89
	v_cvt_pk_bf16_f32 v88, v82, v83
	v_cvt_pk_bf16_f32 v89, v84, v85
	s_waitcnt lgkmcnt(0)
; #define PG8_LAS __attribute__((address_space(3)))
; __device__ __forceinline__ unsigned cvt_pk_bf16(float lo, float hi) { unsigned r; asm volatile("v_cvt_pk_bf16_f32 %0, %1, %2" : "=v"(r) : "v"(lo), "v"(hi)); return r; }
;     __device__ __forceinline__ void operator()(const f32x4 (&acc)[2][2][4][2], const Unit& u, int wr, int wc, int fr, int fq, PG8_LAS float* stash, int par, PG8_LAS unsigned char* stg, const Unit& un) const {
;     ...
;         for (int ai = 0; ai < 2; ++ai)
; #pragma unroll
;             for (int m = 0; m < 4; ++m) {
;                 const int row = u.pm * BM + ai * HALF + wr * 64 + m * 16 + fr;
;                 const float rs = rsa[ai][m];
;                 PG8_LAS unsigned char* st = stg + fr * 144 + fq * 16;
; #pragma unroll
;                 for (int bj = 0; bj < 2; ++bj) {
;                     float v[8];
; #pragma unroll
;                     for (int i = 0; i < 4; ++i) { v[i] = acc[ai][bj][m][0][i] * rs; v[4 + i] = acc[ai][bj][m][1][i] * rs; }
; #pragma unroll
;                     for (int i = 0; i < 8; ++i) { const float r = fmaxf(v[i], 0.f); v[i] = r * r; }
;                     u32x4 w; w.x = cvt_pk_bf16(v[0], v[1]); w.y = cvt_pk_bf16(v[2], v[3]); w.z = cvt_pk_bf16(v[4], v[5]); w.w = cvt_pk_bf16(v[6], v[7]);
;                     *(PG8_LAS u32x4*)(st + bj * 64) = w;
;                 }
; #pragma unroll
;                 for (int i = 0; i < 2; ++i) { const int c = fq * 16 + fr + 64 * i, rr = c >> 3, pc = c & 7;
;                     const u32x4 w = *(const PG8_LAS u32x4*)(stg + rr * 144 + pc * 16);
;                     __builtin_nontemporal_store(w, (u32x4*)(uo + (size_t)(row - fr + rr) * 4096 + u.pn * BM + wc * 64 + pc * 8)); }
	s_add_u32 s100, s98, 0x20000
	s_addc_u32 s101, s99, 0
	global_store_dwordx4 v200, v[212:215], s[100:101] nt
	global_store_dwordx4 v201, v[216:219], s[100:101] nt
	ds_write_b128 v156, v[94:97]
	ds_write_b128 v156, v[86:89] offset:64
	ds_read_b128 v[204:207], v158
	ds_read_b128 v[208:211], v158 offset:1152
	v_pk_mul_f32 v[78:79], v[78:79], v[148:149] op_sel:[0,1]
	v_pk_mul_f32 v[80:81], v[80:81], v[148:149] op_sel:[0,1]
	v_pk_mul_f32 v[74:75], v[74:75], v[148:149] op_sel:[0,1]
	v_pk_mul_f32 v[76:77], v[76:77], v[148:149] op_sel:[0,1]
	v_max_f32_e32 v78, 0, v78
	v_max_f32_e32 v79, 0, v79
	v_max_f32_e32 v80, 0, v80
	v_max_f32_e32 v81, 0, v81
	v_max_f32_e32 v74, 0, v74
	v_max_f32_e32 v75, 0, v75
	v_max_f32_e32 v76, 0, v76
	v_max_f32_e32 v77, 0, v77
	v_pk_mul_f32 v[78:79], v[78:79], v[78:79]
	v_pk_mul_f32 v[80:81], v[80:81], v[80:81]
	v_pk_mul_f32 v[74:75], v[74:75], v[74:75]
	v_pk_mul_f32 v[76:77], v[76:77], v[76:77]
	v_cvt_pk_bf16_f32 v78, v78, v79
	v_cvt_pk_bf16_f32 v79, v80, v81
	v_cvt_pk_bf16_f32 v80, v74, v75
	v_cvt_pk_bf16_f32 v81, v76, v77
	v_pk_mul_f32 v[70:71], v[70:71], v[148:149] op_sel:[0,1]
	v_pk_mul_f32 v[72:73], v[72:73], v[148:149] op_sel:[0,1]
	v_pk_mul_f32 v[66:67], v[66:67], v[148:149] op_sel:[0,1]
	v_pk_mul_f32 v[68:69], v[68:69], v[148:149] op_sel:[0,1]
	v_max_f32_e32 v70, 0, v70
	v_max_f32_e32 v71, 0, v71
	v_max_f32_e32 v72, 0, v72
	v_max_f32_e32 v73, 0, v73
	v_max_f32_e32 v66, 0, v66
	v_max_f32_e32 v67, 0, v67
	v_max_f32_e32 v68, 0, v68
	v_max_f32_e32 v69, 0, v69
	v_pk_mul_f32 v[70:71], v[70:71], v[70:71]
	v_pk_mul_f32 v[72:73], v[72:73], v[72:73]
	v_pk_mul_f32 v[66:67], v[66:67], v[66:67]
	v_pk_mul_f32 v[68:69], v[68:69], v[68:69]
	v_cvt_pk_bf16_f32 v70, v70, v71
	v_cvt_pk_bf16_f32 v71, v72, v73
	v_cvt_pk_bf16_f32 v72, v66, v67
	v_cvt_pk_bf16_f32 v73, v68, v69
	s_waitcnt lgkmcnt(0)
	s_add_u32 s100, s98, 0x40000
	s_addc_u32 s101, s99, 0
	global_store_dwordx4 v200, v[204:207], s[100:101] nt
	global_store_dwordx4 v201, v[208:211], s[100:101] nt
	ds_write_b128 v156, v[78:81]
	ds_write_b128 v156, v[70:73] offset:64
	ds_read_b128 v[212:215], v158
	ds_read_b128 v[216:219], v158 offset:1152
	v_pk_mul_f32 v[62:63], v[62:63], v[146:147] op_sel_hi:[1,0]
	v_pk_mul_f32 v[64:65], v[64:65], v[146:147] op_sel_hi:[1,0]
	v_pk_mul_f32 v[58:59], v[58:59], v[146:147] op_sel_hi:[1,0]
	v_pk_mul_f32 v[60:61], v[60:61], v[146:147] op_sel_hi:[1,0]
	v_max_f32_e32 v62, 0, v62
	v_max_f32_e32 v63, 0, v63
	v_max_f32_e32 v64, 0, v64
	v_max_f32_e32 v65, 0, v65
	v_max_f32_e32 v58, 0, v58
	v_max_f32_e32 v59, 0, v59
	v_max_f32_e32 v60, 0, v60
	v_max_f32_e32 v61, 0, v61
	v_pk_mul_f32 v[62:63], v[62:63], v[62:63]
	v_pk_mul_f32 v[64:65], v[64:65], v[64:65]
	v_pk_mul_f32 v[58:59], v[58:59], v[58:59]
	v_pk_mul_f32 v[60:61], v[60:61], v[60:61]
	v_cvt_pk_bf16_f32 v62, v62, v63
	v_cvt_pk_bf16_f32 v63, v64, v65
	v_cvt_pk_bf16_f32 v64, v58, v59
	v_cvt_pk_bf16_f32 v65, v60, v61
	v_pk_mul_f32 v[54:55], v[54:55], v[146:147] op_sel_hi:[1,0]
	v_pk_mul_f32 v[56:57], v[56:57], v[146:147] op_sel_hi:[1,0]
	v_pk_mul_f32 v[50:51], v[50:51], v[146:147] op_sel_hi:[1,0]
	v_pk_mul_f32 v[52:53], v[52:53], v[146:147] op_sel_hi:[1,0]
	v_max_f32_e32 v54, 0, v54
	v_max_f32_e32 v55, 0, v55
	v_max_f32_e32 v56, 0, v56
	v_max_f32_e32 v57, 0, v57
	v_max_f32_e32 v50, 0, v50
	v_max_f32_e32 v51, 0, v51
	v_max_f32_e32 v52, 0, v52
	v_max_f32_e32 v53, 0, v53
	v_pk_mul_f32 v[54:55], v[54:55], v[54:55]
	v_pk_mul_f32 v[56:57], v[56:57], v[56:57]
	v_pk_mul_f32 v[50:51], v[50:51], v[50:51]
	v_pk_mul_f32 v[52:53], v[52:53], v[52:53]
	v_cvt_pk_bf16_f32 v54, v54, v55
	v_cvt_pk_bf16_f32 v55, v56, v57
	v_cvt_pk_bf16_f32 v56, v50, v51
	v_cvt_pk_bf16_f32 v57, v52, v53
	s_waitcnt lgkmcnt(0)
	s_add_u32 s100, s98, 0x60000
	s_addc_u32 s101, s99, 0
	global_store_dwordx4 v200, v[212:215], s[100:101] nt
	global_store_dwordx4 v201, v[216:219], s[100:101] nt
	ds_write_b128 v156, v[62:65]
	ds_write_b128 v156, v[54:57] offset:64
	ds_read_b128 v[204:207], v158
	ds_read_b128 v[208:211], v158 offset:1152
	v_pk_mul_f32 v[46:47], v[46:47], v[146:147] op_sel:[0,1]
	v_pk_mul_f32 v[48:49], v[48:49], v[146:147] op_sel:[0,1]
	v_pk_mul_f32 v[42:43], v[42:43], v[146:147] op_sel:[0,1]
	v_pk_mul_f32 v[44:45], v[44:45], v[146:147] op_sel:[0,1]
	v_max_f32_e32 v46, 0, v46
	v_max_f32_e32 v47, 0, v47
	v_max_f32_e32 v48, 0, v48
	v_max_f32_e32 v49, 0, v49
	v_max_f32_e32 v42, 0, v42
	v_max_f32_e32 v43, 0, v43
	v_max_f32_e32 v44, 0, v44
	v_max_f32_e32 v45, 0, v45
	v_pk_mul_f32 v[46:47], v[46:47], v[46:47]
	v_pk_mul_f32 v[48:49], v[48:49], v[48:49]
	v_pk_mul_f32 v[42:43], v[42:43], v[42:43]
	v_pk_mul_f32 v[44:45], v[44:45], v[44:45]
	v_cvt_pk_bf16_f32 v46, v46, v47
	v_cvt_pk_bf16_f32 v47, v48, v49
	v_cvt_pk_bf16_f32 v48, v42, v43
	v_cvt_pk_bf16_f32 v49, v44, v45
	v_pk_mul_f32 v[38:39], v[38:39], v[146:147] op_sel:[0,1]
	v_pk_mul_f32 v[40:41], v[40:41], v[146:147] op_sel:[0,1]
	v_pk_mul_f32 v[34:35], v[34:35], v[146:147] op_sel:[0,1]
	v_pk_mul_f32 v[36:37], v[36:37], v[146:147] op_sel:[0,1]
	v_max_f32_e32 v38, 0, v38
	v_max_f32_e32 v39, 0, v39
	v_max_f32_e32 v40, 0, v40
	v_max_f32_e32 v41, 0, v41
	v_max_f32_e32 v34, 0, v34
	v_max_f32_e32 v35, 0, v35
	v_max_f32_e32 v36, 0, v36
	v_max_f32_e32 v37, 0, v37
	v_pk_mul_f32 v[38:39], v[38:39], v[38:39]
	v_pk_mul_f32 v[40:41], v[40:41], v[40:41]
	v_pk_mul_f32 v[34:35], v[34:35], v[34:35]
	v_pk_mul_f32 v[36:37], v[36:37], v[36:37]
	v_cvt_pk_bf16_f32 v38, v38, v39
	v_cvt_pk_bf16_f32 v39, v40, v41
	v_cvt_pk_bf16_f32 v40, v34, v35
	v_cvt_pk_bf16_f32 v41, v36, v37
	s_waitcnt lgkmcnt(0)
; #define PG8_LAS __attribute__((address_space(3)))
; __device__ __forceinline__ unsigned cvt_pk_bf16(float lo, float hi) { unsigned r; asm volatile("v_cvt_pk_bf16_f32 %0, %1, %2" : "=v"(r) : "v"(lo), "v"(hi)); return r; }
;     __device__ __forceinline__ void operator()(const f32x4 (&acc)[2][2][4][2], const Unit& u, int wr, int wc, int fr, int fq, PG8_LAS float* stash, int par, PG8_LAS unsigned char* stg, const Unit& un) const {
;     ...
;         for (int ai = 0; ai < 2; ++ai)
; #pragma unroll
;             for (int m = 0; m < 4; ++m) {
;                 const int row = u.pm * BM + ai * HALF + wr * 64 + m * 16 + fr;
;                 const float rs = rsa[ai][m];
;                 PG8_LAS unsigned char* st = stg + fr * 144 + fq * 16;
; #pragma unroll
;                 for (int bj = 0; bj < 2; ++bj) {
;                     float v[8];
; #pragma unroll
;                     for (int i = 0; i < 4; ++i) { v[i] = acc[ai][bj][m][0][i] * rs; v[4 + i] = acc[ai][bj][m][1][i] * rs; }
; #pragma unroll
;                     for (int i = 0; i < 8; ++i) { const float r = fmaxf(v[i], 0.f); v[i] = r * r; }
;                     u32x4 w; w.x = cvt_pk_bf16(v[0], v[1]); w.y = cvt_pk_bf16(v[2], v[3]); w.z = cvt_pk_bf16(v[4], v[5]); w.w = cvt_pk_bf16(v[6], v[7]);
;                     *(PG8_LAS u32x4*)(st + bj * 64) = w;
;                 }
; #pragma unroll
;                 for (int i = 0; i < 2; ++i) { const int c = fq * 16 + fr + 64 * i, rr = c >> 3, pc = c & 7;
;                     const u32x4 w = *(const PG8_LAS u32x4*)(stg + rr * 144 + pc * 16);
;                     __builtin_nontemporal_store(w, (u32x4*)(uo + (size_t)(row - fr + rr) * 4096 + u.pn * BM + wc * 64 + pc * 8)); }
	s_add_u32 s100, s98, 0x100000
	s_addc_u32 s101, s99, 0
	global_store_dwordx4 v200, v[204:207], s[100:101] nt
	global_store_dwordx4 v201, v[208:211], s[100:101] nt
	ds_write_b128 v156, v[46:49]
	ds_write_b128 v156, v[38:41] offset:64
	ds_read_b128 v[212:215], v158
	ds_read_b128 v[216:219], v158 offset:1152
	v_pk_mul_f32 v[30:31], v[30:31], v[144:145] op_sel_hi:[1,0]
	v_pk_mul_f32 v[32:33], v[32:33], v[144:145] op_sel_hi:[1,0]
	v_pk_mul_f32 v[26:27], v[26:27], v[144:145] op_sel_hi:[1,0]
	v_pk_mul_f32 v[28:29], v[28:29], v[144:145] op_sel_hi:[1,0]
	v_max_f32_e32 v30, 0, v30
	v_max_f32_e32 v31, 0, v31
	v_max_f32_e32 v32, 0, v32
	v_max_f32_e32 v33, 0, v33
	v_max_f32_e32 v26, 0, v26
	v_max_f32_e32 v27, 0, v27
	v_max_f32_e32 v28, 0, v28
	v_max_f32_e32 v29, 0, v29
	v_pk_mul_f32 v[30:31], v[30:31], v[30:31]
	v_pk_mul_f32 v[32:33], v[32:33], v[32:33]
	v_pk_mul_f32 v[26:27], v[26:27], v[26:27]
	v_pk_mul_f32 v[28:29], v[28:29], v[28:29]
	v_cvt_pk_bf16_f32 v30, v30, v31
	v_cvt_pk_bf16_f32 v31, v32, v33
	v_cvt_pk_bf16_f32 v32, v26, v27
	v_cvt_pk_bf16_f32 v33, v28, v29
	v_pk_mul_f32 v[22:23], v[22:23], v[144:145] op_sel_hi:[1,0]
	v_pk_mul_f32 v[24:25], v[24:25], v[144:145] op_sel_hi:[1,0]
	v_pk_mul_f32 v[18:19], v[18:19], v[144:145] op_sel_hi:[1,0]
	v_pk_mul_f32 v[20:21], v[20:21], v[144:145] op_sel_hi:[1,0]
	v_max_f32_e32 v22, 0, v22
	v_max_f32_e32 v23, 0, v23
	v_max_f32_e32 v24, 0, v24
	v_max_f32_e32 v25, 0, v25
	v_max_f32_e32 v18, 0, v18
	v_max_f32_e32 v19, 0, v19
	v_max_f32_e32 v20, 0, v20
	v_max_f32_e32 v21, 0, v21
	v_pk_mul_f32 v[22:23], v[22:23], v[22:23]
	v_pk_mul_f32 v[24:25], v[24:25], v[24:25]
	v_pk_mul_f32 v[18:19], v[18:19], v[18:19]
	v_pk_mul_f32 v[20:21], v[20:21], v[20:21]
	v_cvt_pk_bf16_f32 v22, v22, v23
	v_cvt_pk_bf16_f32 v23, v24, v25
	v_cvt_pk_bf16_f32 v24, v18, v19
	v_cvt_pk_bf16_f32 v25, v20, v21
	s_waitcnt lgkmcnt(0)
	s_add_u32 s100, s98, 0x120000
	s_addc_u32 s101, s99, 0
	global_store_dwordx4 v200, v[212:215], s[100:101] nt
	global_store_dwordx4 v201, v[216:219], s[100:101] nt
	ds_write_b128 v156, v[30:33]
	ds_write_b128 v156, v[22:25] offset:64
	ds_read_b128 v[204:207], v158
	ds_read_b128 v[208:211], v158 offset:1152
	v_pk_mul_f32 v[14:15], v[14:15], v[144:145] op_sel:[0,1]
	v_pk_mul_f32 v[16:17], v[16:17], v[144:145] op_sel:[0,1]
	v_pk_mul_f32 v[10:11], v[10:11], v[144:145] op_sel:[0,1]
	v_pk_mul_f32 v[12:13], v[12:13], v[144:145] op_sel:[0,1]
	v_max_f32_e32 v14, 0, v14
	v_max_f32_e32 v15, 0, v15
	v_max_f32_e32 v16, 0, v16
	v_max_f32_e32 v17, 0, v17
	v_max_f32_e32 v10, 0, v10
	v_max_f32_e32 v11, 0, v11
	v_max_f32_e32 v12, 0, v12
	v_max_f32_e32 v13, 0, v13
	v_pk_mul_f32 v[14:15], v[14:15], v[14:15]
	v_pk_mul_f32 v[16:17], v[16:17], v[16:17]
	v_pk_mul_f32 v[10:11], v[10:11], v[10:11]
	v_pk_mul_f32 v[12:13], v[12:13], v[12:13]
	v_cvt_pk_bf16_f32 v14, v14, v15
	v_cvt_pk_bf16_f32 v15, v16, v17
	v_cvt_pk_bf16_f32 v16, v10, v11
	v_cvt_pk_bf16_f32 v17, v12, v13
	v_pk_mul_f32 v[6:7], v[6:7], v[144:145] op_sel:[0,1]
	v_pk_mul_f32 v[8:9], v[8:9], v[144:145] op_sel:[0,1]
	v_pk_mul_f32 v[2:3], v[2:3], v[144:145] op_sel:[0,1]
	v_pk_mul_f32 v[4:5], v[4:5], v[144:145] op_sel:[0,1]
	v_max_f32_e32 v6, 0, v6
	v_max_f32_e32 v7, 0, v7
	v_max_f32_e32 v8, 0, v8
	v_max_f32_e32 v9, 0, v9
	v_max_f32_e32 v2, 0, v2
	v_max_f32_e32 v3, 0, v3
	v_max_f32_e32 v4, 0, v4
	v_max_f32_e32 v5, 0, v5
	v_pk_mul_f32 v[6:7], v[6:7], v[6:7]
	v_pk_mul_f32 v[8:9], v[8:9], v[8:9]
	v_pk_mul_f32 v[2:3], v[2:3], v[2:3]
	v_pk_mul_f32 v[4:5], v[4:5], v[4:5]
	v_cvt_pk_bf16_f32 v6, v6, v7
	v_cvt_pk_bf16_f32 v7, v8, v9
	v_cvt_pk_bf16_f32 v8, v2, v3
	v_cvt_pk_bf16_f32 v9, v4, v5
	s_waitcnt lgkmcnt(0)
	s_add_u32 s100, s98, 0x140000
	s_addc_u32 s101, s99, 0
	global_store_dwordx4 v200, v[204:207], s[100:101] nt
	global_store_dwordx4 v201, v[208:211], s[100:101] nt
	ds_write_b128 v156, v[14:17]
	ds_write_b128 v156, v[6:9] offset:64
	ds_read_b128 v[212:215], v158
	ds_read_b128 v[216:219], v158 offset:1152
	s_waitcnt lgkmcnt(0)
	s_add_u32 s100, s98, 0x160000
	s_addc_u32 s101, s99, 0
	global_store_dwordx4 v200, v[212:215], s[100:101] nt
	global_store_dwordx4 v201, v[216:219], s[100:101] nt
	s_andn2_b64 vcc, exec, s[42:43]
	s_cbranch_vccnz .LBB0_852
; __device__ __forceinline__ float sum_x16(float s) { auto r = __builtin_amdgcn_permlane16_swap(__float_as_uint(s), __float_as_uint(s), false, false); return __uint_as_float(r[0]) + __uint_as_float(r[1]); }
; __device__ __forceinline__ float sum_x32(float s) { auto r = __builtin_amdgcn_permlane32_swap(__float_as_uint(s), __float_as_uint(s), false, false); return __uint_as_float(r[0]) + __uint_as_float(r[1]); }
; __device__ __forceinline__ void rows_part_reduce(const f32x4 (&pl)[2][4], float (&rs)[2][4]) {
; #pragma unroll
;     for (int ai = 0; ai < 2; ++ai)
; #pragma unroll
;         for (int m = 0; m < 4; ++m) { float s = (pl[ai][m][0] + pl[ai][m][1]) + (pl[ai][m][2] + pl[ai][m][3]); s = sum_x16(s); s = sum_x32(s); rs[ai][m] = __builtin_amdgcn_rsqf(s * (1.0f / 1024.0f) + 1e-6f); }
; }
;     __device__ __forceinline__ void operator()(const f32x4 (&acc)[2][2][4][2], const Unit& u, int wr, int wc, int fr, int fq, PG8_LAS float* stash, int par, PG8_LAS unsigned char* stg, const Unit& un) const {
;     ...
;         if (newpm) { float rsn[2][4]; rows_part_reduce(pln, rsn);
;           if (fq == 0) {
; #pragma unroll
;               for (int ai = 0; ai < 2; ++ai)
; #pragma unroll
;                   for (int m = 0; m < 4; ++m) stash[(par ^ 1) * 256 + ai * HALF + wr * 64 + m * 16 + fr] = rsn[ai][m]; } }
	s_waitcnt vmcnt(0)
	v_add_f32_e32 v2, v188, v195
	v_add_f32_e32 v3, v197, v198
	v_add_f32_e32 v4, v184, v192
	v_add_f32_e32 v5, v194, v196
	v_add_f32_e32 v6, v181, v189
	v_add_f32_e32 v7, v191, v193
	v_add_f32_e32 v8, v178, v185
	v_add_f32_e32 v9, v187, v190
	v_add_f32_e32 v10, v175, v180
	v_add_f32_e32 v11, v183, v186
	v_add_f32_e32 v12, v171, v176
	v_add_f32_e32 v13, v179, v182
	v_add_f32_e32 v14, v169, v172
	v_add_f32_e32 v15, v174, v177
	v_add_f32_e32 v16, v159, v168
	v_add_f32_e32 v17, v170, v173
	v_add_f32_e32 v2, v2, v3
	v_add_f32_e32 v4, v4, v5
	v_add_f32_e32 v6, v6, v7
	v_add_f32_e32 v8, v8, v9
	v_add_f32_e32 v10, v10, v11
	v_add_f32_e32 v12, v12, v13
	v_add_f32_e32 v14, v14, v15
	v_add_f32_e32 v16, v16, v17
	v_mov_b32_e32 v3, v2
	v_mov_b32_e32 v5, v4
	v_mov_b32_e32 v7, v6
	v_mov_b32_e32 v9, v8
	v_mov_b32_e32 v11, v10
	v_mov_b32_e32 v13, v12
	v_mov_b32_e32 v15, v14
	v_mov_b32_e32 v17, v16
	v_permlane16_swap_b32_e32 v2, v3
	v_permlane16_swap_b32_e32 v4, v5
	v_permlane16_swap_b32_e32 v6, v7
	v_permlane16_swap_b32_e32 v8, v9
	v_permlane16_swap_b32_e32 v10, v11
	v_permlane16_swap_b32_e32 v12, v13
	v_permlane16_swap_b32_e32 v14, v15
	v_permlane16_swap_b32_e32 v16, v17
	v_add_f32_e32 v2, v2, v3
	v_add_f32_e32 v4, v4, v5
	v_add_f32_e32 v6, v6, v7
	v_add_f32_e32 v8, v8, v9
	v_add_f32_e32 v10, v10, v11
	v_add_f32_e32 v12, v12, v13
	v_add_f32_e32 v14, v14, v15
	v_add_f32_e32 v16, v16, v17
	v_mov_b32_e32 v3, v2
	v_mov_b32_e32 v5, v4
	v_mov_b32_e32 v7, v6
	v_mov_b32_e32 v9, v8
	v_mov_b32_e32 v11, v10
	v_mov_b32_e32 v13, v12
	v_mov_b32_e32 v15, v14
	v_mov_b32_e32 v17, v16
	v_permlane32_swap_b32_e32 v2, v3
	v_permlane32_swap_b32_e32 v4, v5
	v_permlane32_swap_b32_e32 v6, v7
	v_permlane32_swap_b32_e32 v8, v9
	v_permlane32_swap_b32_e32 v10, v11
	v_permlane32_swap_b32_e32 v12, v13
	v_permlane32_swap_b32_e32 v14, v15
	v_permlane32_swap_b32_e32 v16, v17
	s_and_saveexec_b64 s[42:43], s[34:35]
	s_cbranch_execz .LBB0_851
	v_add_f32_e32 v16, v16, v17
	v_mov_b32_e32 v17, 0x358637bd
	v_add_f32_e32 v4, v4, v5
	v_add_f32_e32 v2, v2, v3
	v_add_f32_e32 v8, v8, v9
	v_add_f32_e32 v6, v6, v7
	v_fmamk_f32 v4, v4, 0x3a800000, v17
	v_fmamk_f32 v2, v2, 0x3a800000, v17
	v_add_f32_e32 v12, v12, v13
	v_add_f32_e32 v10, v10, v11
	v_fmamk_f32 v8, v8, 0x3a800000, v17
	v_fmamk_f32 v6, v6, 0x3a800000, v17
	v_rsq_f32_e32 v4, v4
	v_rsq_f32_e32 v2, v2
	v_add_f32_e32 v14, v14, v15
	v_fmamk_f32 v12, v12, 0x3a800000, v17
	v_fmamk_f32 v10, v10, 0x3a800000, v17
	v_rsq_f32_e32 v8, v8
	v_rsq_f32_e32 v6, v6
	v_lshlrev_b32_e32 v3, 10, v157
	v_fmamk_f32 v16, v16, 0x3a800000, v17
	v_fmamk_f32 v14, v14, 0x3a800000, v17
	v_rsq_f32_e32 v12, v12
	v_rsq_f32_e32 v10, v10
	v_xor_b32_e32 v3, 0x400, v3
	v_rsq_f32_e32 v16, v16
	v_rsq_f32_e32 v14, v14
	v_add_u32_e32 v3, v152, v3
	ds_write2_b32 v3, v2, v4 offset1:16
	ds_write2_b32 v3, v6, v8 offset0:32 offset1:48
	ds_write2_b32 v3, v10, v12 offset0:128 offset1:144
	ds_write2_b32 v3, v14, v16 offset0:160 offset1:176

; #define PG8_LAS __attribute__((address_space(3)))
; __device__ __forceinline__ unsigned cvt_pk_bf16(float lo, float hi) { unsigned r; asm volatile("v_cvt_pk_bf16_f32 %0, %1, %2" : "=v"(r) : "v"(lo), "v"(hi)); return r; }
;     __device__ __forceinline__ void operator()(const f32x4 (&acc)[2][2][4][2], const Unit& u, int wr, int wc, int fr, int fq, PG8_LAS unsigned char* stg) const {
;     ...
;         for (int ai = 0; ai < 2; ++ai) {
;         asm volatile("" ::: "memory");
;         u32x4 xin[4][2];
; #pragma unroll
;         for (int m = 0; m < 4; ++m)
; #pragma unroll
;             for (int i = 0; i < 2; ++i) { const int c = lane + 64 * i; xin[m][i] = *(const u32x4*)(xb + (size_t)(rowb + ai * HALF + m * 16 + (c >> 3)) * 1024 + colw + (c & 7) * 8); }
; #pragma unroll
;         for (int m = 0; m < 4; ++m) {
;             const int row = rowb + ai * HALF + m * 16 + fr;
; #pragma unroll
;             for (int i = 0; i < 2; ++i) { const int c = lane + 64 * i; *(PG8_LAS u32x4*)(stg + (c >> 3) * 144 + (c & 7) * 16) = xin[m][i]; }
;             float ss = 0.f;
; #pragma unroll
;             for (int bj = 0; bj < 2; ++bj) {
;                 const u32x4 xo = *(const PG8_LAS u32x4*)(st + bj * 64);
;                 float v[8];
; #pragma unroll
;                 for (int i = 0; i < 4; ++i) { v[2 * i] = __uint_as_float(xo[i] << 16) + acc[ai][bj][m][i >> 1][(2 * i) & 3]; v[2 * i + 1] = __uint_as_float(xo[i] & 0xffff0000u) + acc[ai][bj][m][i >> 1][(2 * i + 1) & 3]; }
;                 u32x4 w; w.x = cvt_pk_bf16(v[0], v[1]); w.y = cvt_pk_bf16(v[2], v[3]); w.z = cvt_pk_bf16(v[4], v[5]); w.w = cvt_pk_bf16(v[6], v[7]);
;                 *(PG8_LAS u32x4*)(st + bj * 64) = w;
;                 ss += ((v[0] * v[0] + v[1] * v[1]) + (v[2] * v[2] + v[3] * v[3])) + ((v[4] * v[4] + v[5] * v[5]) + (v[6] * v[6] + v[7] * v[7]));
;             }
; #pragma unroll
;             for (int i = 0; i < 2; ++i) { const int c = lane + 64 * i; const u32x4 w = *(const PG8_LAS u32x4*)(stg + (c >> 3) * 144 + (c & 7) * 16);
;                 *(u32x4*)(xo_ + (size_t)(row - fr + (c >> 3)) * 1024 + colw + (c & 7) * 8) = w; }
;             ss = sum_x16(ss); ss = sum_x32(ss);
;             if (fq == 0) po_[(size_t)(u.pn * 4 + wc) * 65536 + row] = ss;
.LBB0_926:
	s_ashr_i32 s45, s44, 31
	s_lshl_b32 s14, s14, 8
	s_lshl_b64 s[16:17], s[44:45], 8
	s_add_i32 s42, s14, s10
	s_or_b64 s[16:17], s[16:17], s[74:75]
	v_or_b32_e32 v130, s42, v206
	s_lshl_b64 s[46:47], s[16:17], 1
	v_ashrrev_i32_e32 v131, 31, v130
	v_lshl_add_u64 v[182:183], v[176:177], 0, s[46:47]
	v_lshlrev_b64 v[198:199], 11, v[130:131]
	v_lshl_add_u64 v[130:131], v[182:183], 0, v[198:199]
	global_load_dwordx4 v[154:157], v[130:131], off
	v_or_b32_e32 v130, s42, v207
	v_ashrrev_i32_e32 v131, 31, v130
	v_lshlrev_b64 v[196:197], 11, v[130:131]
	v_lshl_add_u64 v[130:131], v[182:183], 0, v[196:197]
	global_load_dwordx4 v[160:163], v[130:131], off
	s_lshl_b32 s14, s44, 2
	s_or_b32 s14, s14, s9
	s_ashr_i32 s15, s14, 31
	s_lshl_b64 s[44:45], s[14:15], 18
	s_or_b32 s14, s42, 16
	v_or_b32_e32 v130, s14, v206
	v_ashrrev_i32_e32 v131, 31, v130
	v_lshlrev_b64 v[194:195], 11, v[130:131]
	v_lshl_add_u64 v[130:131], v[182:183], 0, v[194:195]
	global_load_dwordx4 v[146:149], v[130:131], off
	v_or_b32_e32 v130, s14, v207
	v_ashrrev_i32_e32 v131, 31, v130
	v_lshlrev_b64 v[192:193], 11, v[130:131]
	v_lshl_add_u64 v[130:131], v[182:183], 0, v[192:193]
	s_or_b32 s14, s42, 32
	global_load_dwordx4 v[150:153], v[130:131], off
	v_or_b32_e32 v130, s14, v206
	v_ashrrev_i32_e32 v131, 31, v130
	v_lshlrev_b64 v[188:189], 11, v[130:131]
	v_lshl_add_u64 v[130:131], v[182:183], 0, v[188:189]
	global_load_dwordx4 v[134:137], v[130:131], off
	v_or_b32_e32 v130, s14, v207
	v_ashrrev_i32_e32 v131, 31, v130
	v_lshlrev_b64 v[186:187], 11, v[130:131]
	v_lshl_add_u64 v[130:131], v[182:183], 0, v[186:187]
	s_or_b32 s14, s42, 48
	global_load_dwordx4 v[138:141], v[130:131], off
	v_or_b32_e32 v130, s14, v206
	v_or_b32_e32 v142, s14, v207
	v_ashrrev_i32_e32 v131, 31, v130
	v_ashrrev_i32_e32 v143, 31, v142
	v_lshlrev_b64 v[184:185], 11, v[130:131]
	v_lshlrev_b64 v[190:191], 11, v[142:143]
	v_lshl_add_u64 v[130:131], v[182:183], 0, v[184:185]
	v_lshl_add_u64 v[142:143], v[182:183], 0, v[190:191]
	global_load_dwordx4 v[130:133], v[130:131], off
	s_nop 0
	global_load_dwordx4 v[142:145], v[142:143], off
	s_waitcnt vmcnt(0)
	ds_write_b128 v209, v[154:157]
	ds_write_b128 v209, v[160:163] offset:1152
	ds_read_b128 v[154:157], v210
	s_waitcnt lgkmcnt(0)
	v_lshlrev_b32_e32 v160, 16, v154
	v_and_b32_e32 v154, 0xffff0000, v154
	v_add_f32_e32 v127, v127, v154
	v_lshlrev_b32_e32 v154, 16, v155
	v_add_f32_e32 v128, v128, v154
	v_and_b32_e32 v154, 0xffff0000, v155
	v_add_f32_e32 v129, v129, v154
	v_lshlrev_b32_e32 v154, 16, v156
	v_add_f32_e32 v154, v122, v154
	v_and_b32_e32 v122, 0xffff0000, v156
	v_add_f32_e32 v155, v123, v122
	v_lshlrev_b32_e32 v122, 16, v157
	v_add_f32_e32 v156, v124, v122
	v_and_b32_e32 v122, 0xffff0000, v157
	v_add_f32_e32 v126, v126, v160
	v_add_f32_e32 v157, v125, v122
	v_cvt_pk_bf16_f32 v122, v126, v127
	v_cvt_pk_bf16_f32 v123, v128, v129
	v_cvt_pk_bf16_f32 v124, v154, v155
	v_cvt_pk_bf16_f32 v125, v156, v157
	ds_write_b128 v210, v[122:125]
	v_mul_f32_e32 v122, v127, v127
	v_mul_f32_e32 v123, v129, v129
	v_fmac_f32_e32 v122, v126, v126
	v_fmac_f32_e32 v123, v128, v128
	v_add_f32_e32 v122, v122, v123
	v_mul_f32_e32 v123, v155, v155
	v_mul_f32_e32 v124, v157, v157
	v_fmac_f32_e32 v123, v154, v154
	v_fmac_f32_e32 v124, v156, v156
	v_add_f32_e32 v123, v123, v124
	v_add_f32_e32 v126, v122, v123
	ds_read_b128 v[122:125], v210 offset:64
	s_waitcnt lgkmcnt(0)
	v_lshlrev_b32_e32 v127, 16, v122
	v_and_b32_e32 v122, 0xffff0000, v122
	v_add_f32_e32 v119, v119, v122
	v_lshlrev_b32_e32 v122, 16, v123
	v_add_f32_e32 v120, v120, v122
	v_and_b32_e32 v122, 0xffff0000, v123
	v_add_f32_e32 v121, v121, v122
	v_lshlrev_b32_e32 v122, 16, v124
	v_add_f32_e32 v122, v114, v122
	v_and_b32_e32 v114, 0xffff0000, v124
	v_add_f32_e32 v123, v115, v114
	v_lshlrev_b32_e32 v114, 16, v125
	v_add_f32_e32 v124, v116, v114
	v_and_b32_e32 v114, 0xffff0000, v125
	v_add_f32_e32 v118, v118, v127
	v_add_f32_e32 v125, v117, v114
	v_cvt_pk_bf16_f32 v114, v118, v119
	v_cvt_pk_bf16_f32 v115, v120, v121
	v_cvt_pk_bf16_f32 v116, v122, v123
	v_cvt_pk_bf16_f32 v117, v124, v125
	ds_write_b128 v210, v[114:117] offset:64
	v_mul_f32_e32 v114, v119, v119
	v_mul_f32_e32 v115, v121, v121
	v_fmac_f32_e32 v114, v118, v118
	v_fmac_f32_e32 v115, v120, v120
	v_add_f32_e32 v114, v114, v115
	v_mul_f32_e32 v115, v123, v123
	v_mul_f32_e32 v116, v125, v125
	v_fmac_f32_e32 v115, v122, v122
	v_fmac_f32_e32 v116, v124, v124
	v_add_f32_e32 v115, v115, v116
	v_add_f32_e32 v114, v114, v115
	v_add_f32_e32 v120, v126, v114
	ds_read_b128 v[114:117], v211
	v_lshl_add_u64 v[118:119], s[76:77], 0, v[198:199]
	v_lshl_add_u64 v[118:119], v[118:119], 0, s[46:47]
	v_lshl_add_u64 v[118:119], v[118:119], 0, v[0:1]
	s_waitcnt lgkmcnt(0)
	global_store_dwordx4 v[118:119], v[114:117], off nt
	ds_read_b128 v[114:117], v211 offset:1152
	v_lshl_add_u64 v[118:119], s[76:77], 0, v[196:197]
	v_lshl_add_u64 v[118:119], v[118:119], 0, s[46:47]
	v_lshl_add_u64 v[118:119], v[118:119], 0, v[0:1]
	s_waitcnt lgkmcnt(0)
	global_store_dwordx4 v[118:119], v[114:117], off nt
	s_nop 1
	v_mov_b32_e32 v114, v120
	s_nop 1
	v_permlane16_swap_b32_e32 v120, v114
	v_add_f32_e32 v114, v120, v114
	v_mov_b32_e32 v115, v114
	s_nop 1
	v_permlane32_swap_b32_e32 v114, v115
	s_and_saveexec_b64 s[48:49], s[34:35]
	s_cbranch_execz .LBB0_928
	s_add_u32 s14, s82, s44
	v_or_b32_e32 v116, s42, v174
	s_addc_u32 s15, s83, s45
	v_ashrrev_i32_e32 v117, 31, v116
	v_lshl_add_u64 v[116:117], v[116:117], 2, s[14:15]
	v_add_f32_e32 v114, v114, v115
	global_store_dword v[116:117], v114, off
; #define PG8_LAS __attribute__((address_space(3)))
; __device__ __forceinline__ unsigned cvt_pk_bf16(float lo, float hi) { unsigned r; asm volatile("v_cvt_pk_bf16_f32 %0, %1, %2" : "=v"(r) : "v"(lo), "v"(hi)); return r; }
; __device__ __forceinline__ float sum_x16(float s) { auto r = __builtin_amdgcn_permlane16_swap(__float_as_uint(s), __float_as_uint(s), false, false); return __uint_as_float(r[0]) + __uint_as_float(r[1]); }
; __device__ __forceinline__ float sum_x32(float s) { auto r = __builtin_amdgcn_permlane32_swap(__float_as_uint(s), __float_as_uint(s), false, false); return __uint_as_float(r[0]) + __uint_as_float(r[1]); }
;     __device__ __forceinline__ void operator()(const f32x4 (&acc)[2][2][4][2], const Unit& u, int wr, int wc, int fr, int fq, PG8_LAS unsigned char* stg) const {
;     ...
;         for (int m = 0; m < 4; ++m) {
;             const int row = rowb + ai * HALF + m * 16 + fr;
; #pragma unroll
;             for (int i = 0; i < 2; ++i) { const int c = lane + 64 * i; *(PG8_LAS u32x4*)(stg + (c >> 3) * 144 + (c & 7) * 16) = xin[m][i]; }
;             float ss = 0.f;
; #pragma unroll
;             for (int bj = 0; bj < 2; ++bj) {
;                 const u32x4 xo = *(const PG8_LAS u32x4*)(st + bj * 64);
;                 float v[8];
; #pragma unroll
;                 for (int i = 0; i < 4; ++i) { v[2 * i] = __uint_as_float(xo[i] << 16) + acc[ai][bj][m][i >> 1][(2 * i) & 3]; v[2 * i + 1] = __uint_as_float(xo[i] & 0xffff0000u) + acc[ai][bj][m][i >> 1][(2 * i + 1) & 3]; }
;                 u32x4 w; w.x = cvt_pk_bf16(v[0], v[1]); w.y = cvt_pk_bf16(v[2], v[3]); w.z = cvt_pk_bf16(v[4], v[5]); w.w = cvt_pk_bf16(v[6], v[7]);
;                 *(PG8_LAS u32x4*)(st + bj * 64) = w;
;                 ss += ((v[0] * v[0] + v[1] * v[1]) + (v[2] * v[2] + v[3] * v[3])) + ((v[4] * v[4] + v[5] * v[5]) + (v[6] * v[6] + v[7] * v[7]));
;             }
; #pragma unroll
;             for (int i = 0; i < 2; ++i) { const int c = lane + 64 * i; const u32x4 w = *(const PG8_LAS u32x4*)(stg + (c >> 3) * 144 + (c & 7) * 16);
;                 *(u32x4*)(xo_ + (size_t)(row - fr + (c >> 3)) * 1024 + colw + (c & 7) * 8) = w; }
;             ss = sum_x16(ss); ss = sum_x32(ss);
;             if (fq == 0) po_[(size_t)(u.pn * 4 + wc) * 65536 + row] = ss;
.LBB0_928:
	s_or_b64 exec, exec, s[48:49]
	ds_write_b128 v209, v[146:149]
	ds_write_b128 v209, v[150:153] offset:1152
	ds_read_b128 v[114:117], v210
	s_waitcnt lgkmcnt(0)
	v_lshlrev_b32_e32 v118, 16, v114
	v_and_b32_e32 v114, 0xffff0000, v114
	v_add_f32_e32 v111, v111, v114
	v_and_b32_e32 v114, 0xffff0000, v115
	v_add_f32_e32 v113, v113, v114
	v_lshlrev_b32_e32 v114, 16, v116
	v_add_f32_e32 v114, v106, v114
	v_and_b32_e32 v106, 0xffff0000, v116
	v_lshlrev_b32_e32 v119, 16, v115
	v_add_f32_e32 v115, v107, v106
	v_lshlrev_b32_e32 v106, 16, v117
	v_add_f32_e32 v116, v108, v106
	v_and_b32_e32 v106, 0xffff0000, v117
	v_add_f32_e32 v110, v110, v118
	v_add_f32_e32 v112, v112, v119
	v_add_f32_e32 v117, v109, v106
	v_cvt_pk_bf16_f32 v106, v110, v111
	v_cvt_pk_bf16_f32 v107, v112, v113
	v_cvt_pk_bf16_f32 v108, v114, v115
	v_cvt_pk_bf16_f32 v109, v116, v117
	ds_write_b128 v210, v[106:109]
	v_mul_f32_e32 v106, v111, v111
	v_mul_f32_e32 v107, v113, v113
	v_fmac_f32_e32 v106, v110, v110
	v_fmac_f32_e32 v107, v112, v112
	v_add_f32_e32 v110, v106, v107
	ds_read_b128 v[106:109], v210 offset:64
	v_mul_f32_e32 v111, v115, v115
	v_mul_f32_e32 v112, v117, v117
	v_fmac_f32_e32 v111, v114, v114
	v_fmac_f32_e32 v112, v116, v116
	v_add_f32_e32 v111, v111, v112
	v_add_f32_e32 v110, v110, v111
	s_waitcnt lgkmcnt(0)
	v_lshlrev_b32_e32 v111, 16, v106
	v_and_b32_e32 v106, 0xffff0000, v106
	v_add_f32_e32 v103, v103, v106
	v_lshlrev_b32_e32 v106, 16, v107
	v_add_f32_e32 v104, v104, v106
	v_and_b32_e32 v106, 0xffff0000, v107
	v_add_f32_e32 v105, v105, v106
	v_lshlrev_b32_e32 v106, 16, v108
	v_add_f32_e32 v106, v98, v106
	v_and_b32_e32 v98, 0xffff0000, v108
	v_add_f32_e32 v107, v99, v98
	v_lshlrev_b32_e32 v98, 16, v109
	v_add_f32_e32 v108, v100, v98
	v_and_b32_e32 v98, 0xffff0000, v109
	v_add_f32_e32 v102, v102, v111
	v_add_f32_e32 v109, v101, v98
	v_cvt_pk_bf16_f32 v98, v102, v103
	v_cvt_pk_bf16_f32 v99, v104, v105
	v_cvt_pk_bf16_f32 v100, v106, v107
	v_cvt_pk_bf16_f32 v101, v108, v109
	ds_write_b128 v210, v[98:101] offset:64
	v_mul_f32_e32 v98, v103, v103
	v_mul_f32_e32 v99, v105, v105
	v_fmac_f32_e32 v98, v102, v102
	v_fmac_f32_e32 v99, v104, v104
	v_add_f32_e32 v98, v98, v99
	v_mul_f32_e32 v99, v107, v107
	v_mul_f32_e32 v100, v109, v109
	v_fmac_f32_e32 v99, v106, v106
	v_fmac_f32_e32 v100, v108, v108
	v_add_f32_e32 v99, v99, v100
	v_add_f32_e32 v98, v98, v99
	v_add_f32_e32 v108, v110, v98
	ds_read_b128 v[98:101], v211
	v_lshl_add_u64 v[102:103], s[76:77], 0, v[194:195]
	v_lshl_add_u64 v[102:103], v[102:103], 0, s[46:47]
	v_lshl_add_u64 v[106:107], v[102:103], 0, v[0:1]
	ds_read_b128 v[102:105], v211 offset:1152
	s_waitcnt lgkmcnt(1)
	global_store_dwordx4 v[106:107], v[98:101], off nt
	s_nop 1
	v_lshl_add_u64 v[98:99], s[76:77], 0, v[192:193]
	v_lshl_add_u64 v[98:99], v[98:99], 0, s[46:47]
	v_lshl_add_u64 v[98:99], v[98:99], 0, v[0:1]
	s_waitcnt lgkmcnt(0)
	global_store_dwordx4 v[98:99], v[102:105], off nt
	v_mov_b32_e32 v98, v108
	s_nop 1
	v_permlane16_swap_b32_e32 v108, v98
	v_add_f32_e32 v98, v108, v98
	v_mov_b32_e32 v99, v98
	s_nop 1
	v_permlane32_swap_b32_e32 v98, v99
	s_and_saveexec_b64 s[48:49], s[34:35]
	s_cbranch_execz .LBB0_930
	s_add_u32 s14, s82, s44
	s_addc_u32 s15, s83, s45
	s_ashr_i32 s43, s42, 31
	v_lshl_add_u64 v[100:101], s[42:43], 0, v[174:175]
	v_lshl_add_u64 v[100:101], v[100:101], 2, s[14:15]
	v_add_f32_e32 v98, v98, v99
	global_store_dword v[100:101], v98, off offset:64
.LBB0_930:
	s_or_b64 exec, exec, s[48:49]
	ds_write_b128 v209, v[134:137]
	ds_write_b128 v209, v[138:141] offset:1152
	ds_read_b128 v[98:101], v210
	s_waitcnt lgkmcnt(0)
	v_lshlrev_b32_e32 v102, 16, v98
	v_and_b32_e32 v98, 0xffff0000, v98
	v_add_f32_e32 v95, v95, v98
	v_and_b32_e32 v98, 0xffff0000, v99
	v_add_f32_e32 v97, v97, v98
	v_lshlrev_b32_e32 v98, 16, v100
	v_add_f32_e32 v98, v90, v98
	v_and_b32_e32 v90, 0xffff0000, v100
	v_lshlrev_b32_e32 v103, 16, v99
	v_add_f32_e32 v99, v91, v90
	v_lshlrev_b32_e32 v90, 16, v101
	v_add_f32_e32 v100, v92, v90
	v_and_b32_e32 v90, 0xffff0000, v101
	v_add_f32_e32 v94, v94, v102
	v_add_f32_e32 v96, v96, v103
	v_add_f32_e32 v101, v93, v90
	v_cvt_pk_bf16_f32 v90, v94, v95
	v_cvt_pk_bf16_f32 v91, v96, v97
	v_cvt_pk_bf16_f32 v92, v98, v99
	v_cvt_pk_bf16_f32 v93, v100, v101
	ds_write_b128 v210, v[90:93]
	v_mul_f32_e32 v90, v95, v95
	v_mul_f32_e32 v91, v97, v97
	v_fmac_f32_e32 v90, v94, v94
	v_fmac_f32_e32 v91, v96, v96
	v_add_f32_e32 v94, v90, v91
	ds_read_b128 v[90:93], v210 offset:64
	v_mul_f32_e32 v95, v99, v99
	v_mul_f32_e32 v96, v101, v101
	v_fmac_f32_e32 v95, v98, v98
	v_fmac_f32_e32 v96, v100, v100
	v_add_f32_e32 v95, v95, v96
	v_add_f32_e32 v94, v94, v95
	s_waitcnt lgkmcnt(0)
	v_lshlrev_b32_e32 v95, 16, v90
	v_and_b32_e32 v90, 0xffff0000, v90
	v_add_f32_e32 v87, v87, v90
	v_lshlrev_b32_e32 v90, 16, v91
	v_add_f32_e32 v88, v88, v90
	v_and_b32_e32 v90, 0xffff0000, v91
	v_add_f32_e32 v89, v89, v90
	v_lshlrev_b32_e32 v90, 16, v92
	v_add_f32_e32 v90, v82, v90
	v_and_b32_e32 v82, 0xffff0000, v92
	v_add_f32_e32 v91, v83, v82
	v_lshlrev_b32_e32 v82, 16, v93
	v_add_f32_e32 v92, v84, v82
	v_and_b32_e32 v82, 0xffff0000, v93
	v_add_f32_e32 v86, v86, v95
	v_add_f32_e32 v93, v85, v82
	v_cvt_pk_bf16_f32 v82, v86, v87
	v_cvt_pk_bf16_f32 v83, v88, v89
	v_cvt_pk_bf16_f32 v84, v90, v91
	v_cvt_pk_bf16_f32 v85, v92, v93
	ds_write_b128 v210, v[82:85] offset:64
	v_mul_f32_e32 v82, v87, v87
	v_mul_f32_e32 v83, v89, v89
	v_fmac_f32_e32 v82, v86, v86
	v_fmac_f32_e32 v83, v88, v88
	v_add_f32_e32 v82, v82, v83
	v_mul_f32_e32 v83, v91, v91
	v_mul_f32_e32 v84, v93, v93
	v_fmac_f32_e32 v83, v90, v90
	v_fmac_f32_e32 v84, v92, v92
	v_add_f32_e32 v83, v83, v84
	v_add_f32_e32 v82, v82, v83
	v_add_f32_e32 v92, v94, v82
	ds_read_b128 v[82:85], v211
	v_lshl_add_u64 v[86:87], s[76:77], 0, v[188:189]
	v_lshl_add_u64 v[86:87], v[86:87], 0, s[46:47]
	v_lshl_add_u64 v[90:91], v[86:87], 0, v[0:1]
	ds_read_b128 v[86:89], v211 offset:1152
	s_waitcnt lgkmcnt(1)
	global_store_dwordx4 v[90:91], v[82:85], off nt
	s_nop 1
	v_lshl_add_u64 v[82:83], s[76:77], 0, v[186:187]
	v_lshl_add_u64 v[82:83], v[82:83], 0, s[46:47]
	v_lshl_add_u64 v[82:83], v[82:83], 0, v[0:1]
	s_waitcnt lgkmcnt(0)
	global_store_dwordx4 v[82:83], v[86:89], off nt
	v_mov_b32_e32 v82, v92
	s_nop 1
	v_permlane16_swap_b32_e32 v92, v82
	v_add_f32_e32 v82, v92, v82
	v_mov_b32_e32 v83, v82
	s_nop 1
	v_permlane32_swap_b32_e32 v82, v83
	s_and_saveexec_b64 s[48:49], s[34:35]
	s_cbranch_execz .LBB0_932
	s_add_u32 s14, s82, s44
	s_addc_u32 s15, s83, s45
	s_ashr_i32 s43, s42, 31
	v_lshl_add_u64 v[84:85], s[42:43], 0, v[174:175]
	v_lshl_add_u64 v[84:85], v[84:85], 2, s[14:15]
	v_add_f32_e32 v82, v82, v83
	global_store_dword v[84:85], v82, off offset:128
; #define PG8_LAS __attribute__((address_space(3)))
; __device__ __forceinline__ unsigned cvt_pk_bf16(float lo, float hi) { unsigned r; asm volatile("v_cvt_pk_bf16_f32 %0, %1, %2" : "=v"(r) : "v"(lo), "v"(hi)); return r; }
; __device__ __forceinline__ float sum_x16(float s) { auto r = __builtin_amdgcn_permlane16_swap(__float_as_uint(s), __float_as_uint(s), false, false); return __uint_as_float(r[0]) + __uint_as_float(r[1]); }
;     __device__ __forceinline__ void operator()(const f32x4 (&acc)[2][2][4][2], const Unit& u, int wr, int wc, int fr, int fq, PG8_LAS unsigned char* stg) const {
;     ...
;         for (int m = 0; m < 4; ++m)
; #pragma unroll
;             for (int i = 0; i < 2; ++i) { const int c = lane + 64 * i; xin[m][i] = *(const u32x4*)(xb + (size_t)(rowb + ai * HALF + m * 16 + (c >> 3)) * 1024 + colw + (c & 7) * 8); }
; #pragma unroll
;         for (int m = 0; m < 4; ++m) {
;             const int row = rowb + ai * HALF + m * 16 + fr;
; #pragma unroll
;             for (int i = 0; i < 2; ++i) { const int c = lane + 64 * i; *(PG8_LAS u32x4*)(stg + (c >> 3) * 144 + (c & 7) * 16) = xin[m][i]; }
;             float ss = 0.f;
; #pragma unroll
;             for (int bj = 0; bj < 2; ++bj) {
;                 const u32x4 xo = *(const PG8_LAS u32x4*)(st + bj * 64);
;                 float v[8];
; #pragma unroll
;                 for (int i = 0; i < 4; ++i) { v[2 * i] = __uint_as_float(xo[i] << 16) + acc[ai][bj][m][i >> 1][(2 * i) & 3]; v[2 * i + 1] = __uint_as_float(xo[i] & 0xffff0000u) + acc[ai][bj][m][i >> 1][(2 * i + 1) & 3]; }
;                 u32x4 w; w.x = cvt_pk_bf16(v[0], v[1]); w.y = cvt_pk_bf16(v[2], v[3]); w.z = cvt_pk_bf16(v[4], v[5]); w.w = cvt_pk_bf16(v[6], v[7]);
;                 *(PG8_LAS u32x4*)(st + bj * 64) = w;
;                 ss += ((v[0] * v[0] + v[1] * v[1]) + (v[2] * v[2] + v[3] * v[3])) + ((v[4] * v[4] + v[5] * v[5]) + (v[6] * v[6] + v[7] * v[7]));
;             }
; #pragma unroll
;             for (int i = 0; i < 2; ++i) { const int c = lane + 64 * i; const u32x4 w = *(const PG8_LAS u32x4*)(stg + (c >> 3) * 144 + (c & 7) * 16);
;                 *(u32x4*)(xo_ + (size_t)(row - fr + (c >> 3)) * 1024 + colw + (c & 7) * 8) = w; }
;             ss = sum_x16(ss); ss = sum_x32(ss);
;             if (fq == 0) po_[(size_t)(u.pn * 4 + wc) * 65536 + row] = ss;
.LBB0_932:
	s_or_b64 exec, exec, s[48:49]
	ds_write_b128 v209, v[130:133]
	ds_write_b128 v209, v[142:145] offset:1152
	ds_read_b128 v[82:85], v210
	s_waitcnt lgkmcnt(0)
	v_lshlrev_b32_e32 v86, 16, v82
	v_and_b32_e32 v82, 0xffff0000, v82
	v_add_f32_e32 v79, v79, v82
	v_and_b32_e32 v82, 0xffff0000, v83
	v_add_f32_e32 v81, v81, v82
	v_lshlrev_b32_e32 v82, 16, v84
	v_add_f32_e32 v82, v74, v82
	v_and_b32_e32 v74, 0xffff0000, v84
	v_lshlrev_b32_e32 v87, 16, v83
	v_add_f32_e32 v83, v75, v74
	v_lshlrev_b32_e32 v74, 16, v85
	v_add_f32_e32 v84, v76, v74
	v_and_b32_e32 v74, 0xffff0000, v85
	v_add_f32_e32 v78, v78, v86
	v_add_f32_e32 v80, v80, v87
	v_add_f32_e32 v85, v77, v74
	v_cvt_pk_bf16_f32 v74, v78, v79
	v_cvt_pk_bf16_f32 v75, v80, v81
	v_cvt_pk_bf16_f32 v76, v82, v83
	v_cvt_pk_bf16_f32 v77, v84, v85
	ds_write_b128 v210, v[74:77]
	v_mul_f32_e32 v74, v79, v79
	v_mul_f32_e32 v75, v81, v81
	v_fmac_f32_e32 v74, v78, v78
	v_fmac_f32_e32 v75, v80, v80
	v_add_f32_e32 v78, v74, v75
	ds_read_b128 v[74:77], v210 offset:64
	v_mul_f32_e32 v79, v83, v83
	v_mul_f32_e32 v80, v85, v85
	v_fmac_f32_e32 v79, v82, v82
	v_fmac_f32_e32 v80, v84, v84
	v_add_f32_e32 v79, v79, v80
	v_add_f32_e32 v78, v78, v79
	s_waitcnt lgkmcnt(0)
	v_lshlrev_b32_e32 v79, 16, v74
	v_and_b32_e32 v74, 0xffff0000, v74
	v_add_f32_e32 v71, v71, v74
	v_lshlrev_b32_e32 v74, 16, v75
	v_add_f32_e32 v72, v72, v74
	v_and_b32_e32 v74, 0xffff0000, v75
	v_add_f32_e32 v73, v73, v74
	v_lshlrev_b32_e32 v74, 16, v76
	v_add_f32_e32 v74, v66, v74
	v_and_b32_e32 v66, 0xffff0000, v76
	v_add_f32_e32 v75, v67, v66
	v_lshlrev_b32_e32 v66, 16, v77
	v_add_f32_e32 v76, v68, v66
	v_and_b32_e32 v66, 0xffff0000, v77
	v_add_f32_e32 v70, v70, v79
	v_add_f32_e32 v77, v69, v66
	v_cvt_pk_bf16_f32 v66, v70, v71
	v_cvt_pk_bf16_f32 v67, v72, v73
	v_cvt_pk_bf16_f32 v68, v74, v75
	v_cvt_pk_bf16_f32 v69, v76, v77
	ds_write_b128 v210, v[66:69] offset:64
	v_mul_f32_e32 v66, v71, v71
	v_mul_f32_e32 v67, v73, v73
	v_fmac_f32_e32 v66, v70, v70
	v_fmac_f32_e32 v67, v72, v72
	v_add_f32_e32 v66, v66, v67
	v_mul_f32_e32 v67, v75, v75
	v_mul_f32_e32 v68, v77, v77
	v_fmac_f32_e32 v67, v74, v74
	v_fmac_f32_e32 v68, v76, v76
	v_add_f32_e32 v67, v67, v68
	v_add_f32_e32 v66, v66, v67
	v_add_f32_e32 v76, v78, v66
	ds_read_b128 v[66:69], v211
	v_lshl_add_u64 v[70:71], s[76:77], 0, v[184:185]
	v_lshl_add_u64 v[70:71], v[70:71], 0, s[46:47]
	v_lshl_add_u64 v[74:75], v[70:71], 0, v[0:1]
	ds_read_b128 v[70:73], v211 offset:1152
	s_waitcnt lgkmcnt(1)
	global_store_dwordx4 v[74:75], v[66:69], off nt
	s_nop 1
	v_lshl_add_u64 v[66:67], s[76:77], 0, v[190:191]
	v_lshl_add_u64 v[66:67], v[66:67], 0, s[46:47]
	v_lshl_add_u64 v[66:67], v[66:67], 0, v[0:1]
	s_waitcnt lgkmcnt(0)
	global_store_dwordx4 v[66:67], v[70:73], off nt
	v_mov_b32_e32 v66, v76
	s_nop 1
	v_permlane16_swap_b32_e32 v76, v66
	v_add_f32_e32 v66, v76, v66
	v_mov_b32_e32 v67, v66
	s_nop 1
	v_permlane32_swap_b32_e32 v66, v67
	s_and_saveexec_b64 s[48:49], s[34:35]
	s_cbranch_execz .LBB0_934
	s_add_u32 s14, s82, s44
	s_addc_u32 s15, s83, s45
	s_ashr_i32 s43, s42, 31
	v_lshl_add_u64 v[68:69], s[42:43], 0, v[174:175]
	v_lshl_add_u64 v[68:69], v[68:69], 2, s[14:15]
	v_add_f32_e32 v66, v66, v67
	global_store_dword v[68:69], v66, off offset:192
.LBB0_934:
	s_or_b64 exec, exec, s[48:49]
	s_add_i32 s14, s42, 0x80
	v_or_b32_e32 v66, s14, v206
	v_ashrrev_i32_e32 v67, 31, v66
	v_lshlrev_b64 v[104:105], 11, v[66:67]
	v_lshl_add_u64 v[66:67], v[182:183], 0, v[104:105]
	global_load_dwordx4 v[106:109], v[66:67], off
	v_or_b32_e32 v66, s14, v207
	v_ashrrev_i32_e32 v67, 31, v66
	v_lshlrev_b64 v[102:103], 11, v[66:67]
	v_lshl_add_u64 v[66:67], v[182:183], 0, v[102:103]
	global_load_dwordx4 v[110:113], v[66:67], off
	s_add_i32 s14, s42, 0x90
	v_or_b32_e32 v66, s14, v206
	v_ashrrev_i32_e32 v67, 31, v66
	v_lshlrev_b64 v[100:101], 11, v[66:67]
	v_lshl_add_u64 v[66:67], v[182:183], 0, v[100:101]
	global_load_dwordx4 v[82:85], v[66:67], off
	v_or_b32_e32 v66, s14, v207
	v_ashrrev_i32_e32 v67, 31, v66
	v_lshlrev_b64 v[98:99], 11, v[66:67]
	v_lshl_add_u64 v[66:67], v[182:183], 0, v[98:99]
	s_add_i32 s14, s42, 0xa0
	global_load_dwordx4 v[86:89], v[66:67], off
	v_or_b32_e32 v66, s14, v206
	v_ashrrev_i32_e32 v67, 31, v66
	v_lshlrev_b64 v[94:95], 11, v[66:67]
	v_lshl_add_u64 v[66:67], v[182:183], 0, v[94:95]
	global_load_dwordx4 v[70:73], v[66:67], off
	v_or_b32_e32 v66, s14, v207
	v_ashrrev_i32_e32 v67, 31, v66
	v_lshlrev_b64 v[92:93], 11, v[66:67]
	v_lshl_add_u64 v[66:67], v[182:183], 0, v[92:93]
	s_add_i32 s14, s42, 0xb0
	global_load_dwordx4 v[74:77], v[66:67], off
	v_or_b32_e32 v66, s14, v206
	v_or_b32_e32 v78, s14, v207
	v_ashrrev_i32_e32 v67, 31, v66
	v_ashrrev_i32_e32 v79, 31, v78
	v_lshlrev_b64 v[90:91], 11, v[66:67]
	v_lshlrev_b64 v[96:97], 11, v[78:79]
	v_lshl_add_u64 v[66:67], v[182:183], 0, v[90:91]
	v_lshl_add_u64 v[78:79], v[182:183], 0, v[96:97]
	global_load_dwordx4 v[66:69], v[66:67], off
	s_nop 0
	global_load_dwordx4 v[78:81], v[78:79], off
	s_waitcnt vmcnt(7)
	ds_write_b128 v209, v[106:109]
	s_waitcnt vmcnt(6)
	ds_write_b128 v209, v[110:113] offset:1152
	ds_read_b128 v[106:109], v210
	s_waitcnt lgkmcnt(0)
; #define PG8_LAS __attribute__((address_space(3)))
; __device__ __forceinline__ unsigned cvt_pk_bf16(float lo, float hi) { unsigned r; asm volatile("v_cvt_pk_bf16_f32 %0, %1, %2" : "=v"(r) : "v"(lo), "v"(hi)); return r; }
; __device__ __forceinline__ float sum_x16(float s) { auto r = __builtin_amdgcn_permlane16_swap(__float_as_uint(s), __float_as_uint(s), false, false); return __uint_as_float(r[0]) + __uint_as_float(r[1]); }
; __device__ __forceinline__ float sum_x32(float s) { auto r = __builtin_amdgcn_permlane32_swap(__float_as_uint(s), __float_as_uint(s), false, false); return __uint_as_float(r[0]) + __uint_as_float(r[1]); }
;     __device__ __forceinline__ void operator()(const f32x4 (&acc)[2][2][4][2], const Unit& u, int wr, int wc, int fr, int fq, PG8_LAS unsigned char* stg) const {
;     ...
;         for (int m = 0; m < 4; ++m) {
;             const int row = rowb + ai * HALF + m * 16 + fr;
; #pragma unroll
;             for (int i = 0; i < 2; ++i) { const int c = lane + 64 * i; *(PG8_LAS u32x4*)(stg + (c >> 3) * 144 + (c & 7) * 16) = xin[m][i]; }
;             float ss = 0.f;
; #pragma unroll
;             for (int bj = 0; bj < 2; ++bj) {
;                 const u32x4 xo = *(const PG8_LAS u32x4*)(st + bj * 64);
;                 float v[8];
; #pragma unroll
;                 for (int i = 0; i < 4; ++i) { v[2 * i] = __uint_as_float(xo[i] << 16) + acc[ai][bj][m][i >> 1][(2 * i) & 3]; v[2 * i + 1] = __uint_as_float(xo[i] & 0xffff0000u) + acc[ai][bj][m][i >> 1][(2 * i + 1) & 3]; }
;                 u32x4 w; w.x = cvt_pk_bf16(v[0], v[1]); w.y = cvt_pk_bf16(v[2], v[3]); w.z = cvt_pk_bf16(v[4], v[5]); w.w = cvt_pk_bf16(v[6], v[7]);
;                 *(PG8_LAS u32x4*)(st + bj * 64) = w;
;                 ss += ((v[0] * v[0] + v[1] * v[1]) + (v[2] * v[2] + v[3] * v[3])) + ((v[4] * v[4] + v[5] * v[5]) + (v[6] * v[6] + v[7] * v[7]));
;             }
; #pragma unroll
;             for (int i = 0; i < 2; ++i) { const int c = lane + 64 * i; const u32x4 w = *(const PG8_LAS u32x4*)(stg + (c >> 3) * 144 + (c & 7) * 16);
;                 *(u32x4*)(xo_ + (size_t)(row - fr + (c >> 3)) * 1024 + colw + (c & 7) * 8) = w; }
;             ss = sum_x16(ss); ss = sum_x32(ss);
;             if (fq == 0) po_[(size_t)(u.pn * 4 + wc) * 65536 + row] = ss;
	v_lshlrev_b32_e32 v110, 16, v106
	v_and_b32_e32 v106, 0xffff0000, v106
	v_add_f32_e32 v63, v63, v106
	v_lshlrev_b32_e32 v106, 16, v107
	v_add_f32_e32 v64, v64, v106
	v_and_b32_e32 v106, 0xffff0000, v107
	v_add_f32_e32 v65, v65, v106
	v_lshlrev_b32_e32 v106, 16, v108
	v_add_f32_e32 v106, v58, v106
	v_and_b32_e32 v58, 0xffff0000, v108
	v_add_f32_e32 v107, v59, v58
	v_lshlrev_b32_e32 v58, 16, v109
	v_add_f32_e32 v108, v60, v58
	v_and_b32_e32 v58, 0xffff0000, v109
	v_add_f32_e32 v62, v62, v110
	v_add_f32_e32 v109, v61, v58
	v_cvt_pk_bf16_f32 v58, v62, v63
	v_cvt_pk_bf16_f32 v59, v64, v65
	v_cvt_pk_bf16_f32 v60, v106, v107
	v_cvt_pk_bf16_f32 v61, v108, v109
	ds_write_b128 v210, v[58:61]
	v_mul_f32_e32 v58, v63, v63
	v_mul_f32_e32 v59, v65, v65
	v_fmac_f32_e32 v58, v62, v62
	v_fmac_f32_e32 v59, v64, v64
	v_add_f32_e32 v58, v58, v59
	v_mul_f32_e32 v59, v107, v107
	v_mul_f32_e32 v60, v109, v109
	v_fmac_f32_e32 v59, v106, v106
	v_fmac_f32_e32 v60, v108, v108
	v_add_f32_e32 v59, v59, v60
	v_add_f32_e32 v62, v58, v59
	ds_read_b128 v[58:61], v210 offset:64
	s_waitcnt lgkmcnt(0)
	v_lshlrev_b32_e32 v63, 16, v58
	v_and_b32_e32 v58, 0xffff0000, v58
	v_add_f32_e32 v55, v55, v58
	v_lshlrev_b32_e32 v58, 16, v59
	v_add_f32_e32 v56, v56, v58
	v_and_b32_e32 v58, 0xffff0000, v59
	v_add_f32_e32 v57, v57, v58
	v_lshlrev_b32_e32 v58, 16, v60
	v_add_f32_e32 v58, v50, v58
	v_and_b32_e32 v50, 0xffff0000, v60
	v_add_f32_e32 v59, v51, v50
	v_lshlrev_b32_e32 v50, 16, v61
	v_add_f32_e32 v60, v52, v50
	v_and_b32_e32 v50, 0xffff0000, v61
	v_add_f32_e32 v54, v54, v63
	v_add_f32_e32 v61, v53, v50
	v_cvt_pk_bf16_f32 v50, v54, v55
	v_cvt_pk_bf16_f32 v51, v56, v57
	v_cvt_pk_bf16_f32 v52, v58, v59
	v_cvt_pk_bf16_f32 v53, v60, v61
	ds_write_b128 v210, v[50:53] offset:64
	v_mul_f32_e32 v50, v55, v55
	v_mul_f32_e32 v51, v57, v57
	v_fmac_f32_e32 v50, v54, v54
	v_fmac_f32_e32 v51, v56, v56
	v_add_f32_e32 v50, v50, v51
	v_mul_f32_e32 v51, v59, v59
	v_mul_f32_e32 v52, v61, v61
	v_fmac_f32_e32 v51, v58, v58
	v_fmac_f32_e32 v52, v60, v60
	v_add_f32_e32 v51, v51, v52
	v_add_f32_e32 v50, v50, v51
	v_add_f32_e32 v56, v62, v50
	ds_read_b128 v[50:53], v211
	v_lshl_add_u64 v[54:55], s[76:77], 0, v[104:105]
	v_lshl_add_u64 v[54:55], v[54:55], 0, s[46:47]
	v_lshl_add_u64 v[54:55], v[54:55], 0, v[0:1]
	s_waitcnt lgkmcnt(0)
	global_store_dwordx4 v[54:55], v[50:53], off nt
	ds_read_b128 v[50:53], v211 offset:1152
	v_lshl_add_u64 v[54:55], s[76:77], 0, v[102:103]
	v_lshl_add_u64 v[54:55], v[54:55], 0, s[46:47]
	v_lshl_add_u64 v[54:55], v[54:55], 0, v[0:1]
	s_waitcnt lgkmcnt(0)
	global_store_dwordx4 v[54:55], v[50:53], off nt
	s_nop 1
	v_mov_b32_e32 v50, v56
	s_nop 1
	v_permlane16_swap_b32_e32 v56, v50
	v_add_f32_e32 v50, v56, v50
	v_mov_b32_e32 v51, v50
	s_nop 1
	v_permlane32_swap_b32_e32 v50, v51
	s_and_saveexec_b64 s[48:49], s[34:35]
	s_cbranch_execz .LBB0_936
	s_add_u32 s14, s82, s44
	s_addc_u32 s15, s83, s45
	s_ashr_i32 s43, s42, 31
	v_lshl_add_u64 v[52:53], s[42:43], 0, v[174:175]
	v_lshl_add_u64 v[52:53], v[52:53], 2, s[14:15]
	v_add_f32_e32 v50, v50, v51
	global_store_dword v[52:53], v50, off offset:512
.LBB0_936:
	s_or_b64 exec, exec, s[48:49]
	s_waitcnt vmcnt(7)
	ds_write_b128 v209, v[82:85]
	s_waitcnt vmcnt(6)
	ds_write_b128 v209, v[86:89] offset:1152
	ds_read_b128 v[50:53], v210
	s_waitcnt lgkmcnt(0)
	v_lshlrev_b32_e32 v54, 16, v50
	v_and_b32_e32 v50, 0xffff0000, v50
	v_add_f32_e32 v47, v47, v50
	v_and_b32_e32 v50, 0xffff0000, v51
	v_add_f32_e32 v49, v49, v50
	v_lshlrev_b32_e32 v50, 16, v52
	v_add_f32_e32 v50, v42, v50
	v_and_b32_e32 v42, 0xffff0000, v52
	v_lshlrev_b32_e32 v55, 16, v51
	v_add_f32_e32 v51, v43, v42
	v_lshlrev_b32_e32 v42, 16, v53
	v_add_f32_e32 v52, v44, v42
	v_and_b32_e32 v42, 0xffff0000, v53
	v_add_f32_e32 v46, v46, v54
	v_add_f32_e32 v48, v48, v55
	v_add_f32_e32 v53, v45, v42
	v_cvt_pk_bf16_f32 v42, v46, v47
	v_cvt_pk_bf16_f32 v43, v48, v49
	v_cvt_pk_bf16_f32 v44, v50, v51
	v_cvt_pk_bf16_f32 v45, v52, v53
	ds_write_b128 v210, v[42:45]
	v_mul_f32_e32 v42, v47, v47
	v_mul_f32_e32 v43, v49, v49
	v_fmac_f32_e32 v42, v46, v46
	v_fmac_f32_e32 v43, v48, v48
	v_add_f32_e32 v46, v42, v43
	ds_read_b128 v[42:45], v210 offset:64
	v_mul_f32_e32 v47, v51, v51
	v_mul_f32_e32 v48, v53, v53
	v_fmac_f32_e32 v47, v50, v50
	v_fmac_f32_e32 v48, v52, v52
	v_add_f32_e32 v47, v47, v48
	v_add_f32_e32 v46, v46, v47
	s_waitcnt lgkmcnt(0)
	v_lshlrev_b32_e32 v47, 16, v42
	v_and_b32_e32 v42, 0xffff0000, v42
	v_add_f32_e32 v39, v39, v42
	v_lshlrev_b32_e32 v42, 16, v43
	v_add_f32_e32 v40, v40, v42
	v_and_b32_e32 v42, 0xffff0000, v43
	v_add_f32_e32 v41, v41, v42
	v_lshlrev_b32_e32 v42, 16, v44
	v_add_f32_e32 v42, v34, v42
	v_and_b32_e32 v34, 0xffff0000, v44
	v_add_f32_e32 v43, v35, v34
	v_lshlrev_b32_e32 v34, 16, v45
	v_add_f32_e32 v44, v36, v34
	v_and_b32_e32 v34, 0xffff0000, v45
	v_add_f32_e32 v38, v38, v47
	v_add_f32_e32 v45, v37, v34
	v_cvt_pk_bf16_f32 v34, v38, v39
	v_cvt_pk_bf16_f32 v35, v40, v41
	v_cvt_pk_bf16_f32 v36, v42, v43
	v_cvt_pk_bf16_f32 v37, v44, v45
	ds_write_b128 v210, v[34:37] offset:64
	v_mul_f32_e32 v34, v39, v39
	v_mul_f32_e32 v35, v41, v41
	v_fmac_f32_e32 v34, v38, v38
	v_fmac_f32_e32 v35, v40, v40
	v_add_f32_e32 v34, v34, v35
	v_mul_f32_e32 v35, v43, v43
	v_mul_f32_e32 v36, v45, v45
	v_fmac_f32_e32 v35, v42, v42
	v_fmac_f32_e32 v36, v44, v44
	v_add_f32_e32 v35, v35, v36
	v_add_f32_e32 v34, v34, v35
	v_add_f32_e32 v44, v46, v34
	ds_read_b128 v[34:37], v211
	v_lshl_add_u64 v[38:39], s[76:77], 0, v[100:101]
	v_lshl_add_u64 v[38:39], v[38:39], 0, s[46:47]
	v_lshl_add_u64 v[42:43], v[38:39], 0, v[0:1]
	ds_read_b128 v[38:41], v211 offset:1152
	s_waitcnt lgkmcnt(1)
	global_store_dwordx4 v[42:43], v[34:37], off nt
	s_nop 1
	v_lshl_add_u64 v[34:35], s[76:77], 0, v[98:99]
	v_lshl_add_u64 v[34:35], v[34:35], 0, s[46:47]
	v_lshl_add_u64 v[34:35], v[34:35], 0, v[0:1]
	s_waitcnt lgkmcnt(0)
	global_store_dwordx4 v[34:35], v[38:41], off nt
	v_mov_b32_e32 v34, v44
	s_nop 1
	v_permlane16_swap_b32_e32 v44, v34
	v_add_f32_e32 v34, v44, v34
	v_mov_b32_e32 v35, v34
	s_nop 1
	v_permlane32_swap_b32_e32 v34, v35
	s_and_saveexec_b64 s[48:49], s[34:35]
	s_cbranch_execz .LBB0_938
	s_add_u32 s14, s82, s44
	s_addc_u32 s15, s83, s45
	s_ashr_i32 s43, s42, 31
	v_lshl_add_u64 v[36:37], s[42:43], 0, v[174:175]
	v_lshl_add_u64 v[36:37], v[36:37], 2, s[14:15]
	v_add_f32_e32 v34, v34, v35
	global_store_dword v[36:37], v34, off offset:576
; #define PG8_LAS __attribute__((address_space(3)))
; __device__ __forceinline__ unsigned cvt_pk_bf16(float lo, float hi) { unsigned r; asm volatile("v_cvt_pk_bf16_f32 %0, %1, %2" : "=v"(r) : "v"(lo), "v"(hi)); return r; }
; __device__ __forceinline__ float sum_x16(float s) { auto r = __builtin_amdgcn_permlane16_swap(__float_as_uint(s), __float_as_uint(s), false, false); return __uint_as_float(r[0]) + __uint_as_float(r[1]); }
; __device__ __forceinline__ float sum_x32(float s) { auto r = __builtin_amdgcn_permlane32_swap(__float_as_uint(s), __float_as_uint(s), false, false); return __uint_as_float(r[0]) + __uint_as_float(r[1]); }
;     __device__ __forceinline__ void operator()(const f32x4 (&acc)[2][2][4][2], const Unit& u, int wr, int wc, int fr, int fq, PG8_LAS unsigned char* stg) const {
;     ...
;         for (int m = 0; m < 4; ++m) {
;             const int row = rowb + ai * HALF + m * 16 + fr;
; #pragma unroll
;             for (int i = 0; i < 2; ++i) { const int c = lane + 64 * i; *(PG8_LAS u32x4*)(stg + (c >> 3) * 144 + (c & 7) * 16) = xin[m][i]; }
;             float ss = 0.f;
; #pragma unroll
;             for (int bj = 0; bj < 2; ++bj) {
;                 const u32x4 xo = *(const PG8_LAS u32x4*)(st + bj * 64);
;                 float v[8];
; #pragma unroll
;                 for (int i = 0; i < 4; ++i) { v[2 * i] = __uint_as_float(xo[i] << 16) + acc[ai][bj][m][i >> 1][(2 * i) & 3]; v[2 * i + 1] = __uint_as_float(xo[i] & 0xffff0000u) + acc[ai][bj][m][i >> 1][(2 * i + 1) & 3]; }
;                 u32x4 w; w.x = cvt_pk_bf16(v[0], v[1]); w.y = cvt_pk_bf16(v[2], v[3]); w.z = cvt_pk_bf16(v[4], v[5]); w.w = cvt_pk_bf16(v[6], v[7]);
;                 *(PG8_LAS u32x4*)(st + bj * 64) = w;
;                 ss += ((v[0] * v[0] + v[1] * v[1]) + (v[2] * v[2] + v[3] * v[3])) + ((v[4] * v[4] + v[5] * v[5]) + (v[6] * v[6] + v[7] * v[7]));
;             }
; #pragma unroll
;             for (int i = 0; i < 2; ++i) { const int c = lane + 64 * i; const u32x4 w = *(const PG8_LAS u32x4*)(stg + (c >> 3) * 144 + (c & 7) * 16);
;                 *(u32x4*)(xo_ + (size_t)(row - fr + (c >> 3)) * 1024 + colw + (c & 7) * 8) = w; }
;             ss = sum_x16(ss); ss = sum_x32(ss);
;             if (fq == 0) po_[(size_t)(u.pn * 4 + wc) * 65536 + row] = ss;
.LBB0_938:
	s_or_b64 exec, exec, s[48:49]
	s_waitcnt vmcnt(7)
	ds_write_b128 v209, v[70:73]
	s_waitcnt vmcnt(6)
	ds_write_b128 v209, v[74:77] offset:1152
	ds_read_b128 v[34:37], v210
	s_waitcnt lgkmcnt(0)
	v_lshlrev_b32_e32 v38, 16, v34
	v_and_b32_e32 v34, 0xffff0000, v34
	v_add_f32_e32 v31, v31, v34
	v_and_b32_e32 v34, 0xffff0000, v35
	v_add_f32_e32 v33, v33, v34
	v_lshlrev_b32_e32 v34, 16, v36
	v_add_f32_e32 v34, v26, v34
	v_and_b32_e32 v26, 0xffff0000, v36
	v_lshlrev_b32_e32 v39, 16, v35
	v_add_f32_e32 v35, v27, v26
	v_lshlrev_b32_e32 v26, 16, v37
	v_add_f32_e32 v36, v28, v26
	v_and_b32_e32 v26, 0xffff0000, v37
	v_add_f32_e32 v30, v30, v38
	v_add_f32_e32 v32, v32, v39
	v_add_f32_e32 v37, v29, v26
	v_cvt_pk_bf16_f32 v26, v30, v31
	v_cvt_pk_bf16_f32 v27, v32, v33
	v_cvt_pk_bf16_f32 v28, v34, v35
	v_cvt_pk_bf16_f32 v29, v36, v37
	ds_write_b128 v210, v[26:29]
	v_mul_f32_e32 v26, v31, v31
	v_mul_f32_e32 v27, v33, v33
	v_fmac_f32_e32 v26, v30, v30
	v_fmac_f32_e32 v27, v32, v32
	v_add_f32_e32 v30, v26, v27
	ds_read_b128 v[26:29], v210 offset:64
	v_mul_f32_e32 v31, v35, v35
	v_mul_f32_e32 v32, v37, v37
	v_fmac_f32_e32 v31, v34, v34
	v_fmac_f32_e32 v32, v36, v36
	v_add_f32_e32 v31, v31, v32
	v_add_f32_e32 v30, v30, v31
	s_waitcnt lgkmcnt(0)
	v_lshlrev_b32_e32 v31, 16, v26
	v_and_b32_e32 v26, 0xffff0000, v26
	v_add_f32_e32 v23, v23, v26
	v_lshlrev_b32_e32 v26, 16, v27
	v_add_f32_e32 v24, v24, v26
	v_and_b32_e32 v26, 0xffff0000, v27
	v_add_f32_e32 v25, v25, v26
	v_lshlrev_b32_e32 v26, 16, v28
	v_add_f32_e32 v26, v18, v26
	v_and_b32_e32 v18, 0xffff0000, v28
	v_add_f32_e32 v27, v19, v18
	v_lshlrev_b32_e32 v18, 16, v29
	v_add_f32_e32 v28, v20, v18
	v_and_b32_e32 v18, 0xffff0000, v29
	v_add_f32_e32 v22, v22, v31
	v_add_f32_e32 v29, v21, v18
	v_cvt_pk_bf16_f32 v18, v22, v23
	v_cvt_pk_bf16_f32 v19, v24, v25
	v_cvt_pk_bf16_f32 v20, v26, v27
	v_cvt_pk_bf16_f32 v21, v28, v29
	ds_write_b128 v210, v[18:21] offset:64
	v_mul_f32_e32 v18, v23, v23
	v_mul_f32_e32 v19, v25, v25
	v_fmac_f32_e32 v18, v22, v22
	v_fmac_f32_e32 v19, v24, v24
	v_add_f32_e32 v18, v18, v19
	v_mul_f32_e32 v19, v27, v27
	v_mul_f32_e32 v20, v29, v29
	v_fmac_f32_e32 v19, v26, v26
	v_fmac_f32_e32 v20, v28, v28
	v_add_f32_e32 v19, v19, v20
	v_add_f32_e32 v18, v18, v19
	v_add_f32_e32 v28, v30, v18
	ds_read_b128 v[18:21], v211
	v_lshl_add_u64 v[22:23], s[76:77], 0, v[94:95]
	v_lshl_add_u64 v[22:23], v[22:23], 0, s[46:47]
	v_lshl_add_u64 v[26:27], v[22:23], 0, v[0:1]
	ds_read_b128 v[22:25], v211 offset:1152
	s_waitcnt lgkmcnt(1)
	global_store_dwordx4 v[26:27], v[18:21], off nt
	s_nop 1
	v_lshl_add_u64 v[18:19], s[76:77], 0, v[92:93]
	v_lshl_add_u64 v[18:19], v[18:19], 0, s[46:47]
	v_lshl_add_u64 v[18:19], v[18:19], 0, v[0:1]
	s_waitcnt lgkmcnt(0)
	global_store_dwordx4 v[18:19], v[22:25], off nt
	v_mov_b32_e32 v18, v28
	s_nop 1
	v_permlane16_swap_b32_e32 v28, v18
	v_add_f32_e32 v18, v28, v18
	v_mov_b32_e32 v19, v18
	s_nop 1
	v_permlane32_swap_b32_e32 v18, v19
	s_and_saveexec_b64 s[48:49], s[34:35]
	s_cbranch_execz .LBB0_940
	s_add_u32 s14, s82, s44
	s_addc_u32 s15, s83, s45
	s_ashr_i32 s43, s42, 31
	v_lshl_add_u64 v[20:21], s[42:43], 0, v[174:175]
	v_lshl_add_u64 v[20:21], v[20:21], 2, s[14:15]
	v_add_f32_e32 v18, v18, v19
	global_store_dword v[20:21], v18, off offset:640
.LBB0_940:
	s_or_b64 exec, exec, s[48:49]
	s_waitcnt vmcnt(7)
	ds_write_b128 v209, v[66:69]
	s_waitcnt vmcnt(6)
	ds_write_b128 v209, v[78:81] offset:1152
	ds_read_b128 v[18:21], v210
	s_waitcnt lgkmcnt(0)
	v_lshlrev_b32_e32 v22, 16, v18
	v_and_b32_e32 v18, 0xffff0000, v18
	v_add_f32_e32 v15, v15, v18
	v_and_b32_e32 v18, 0xffff0000, v19
	v_add_f32_e32 v17, v17, v18
	v_lshlrev_b32_e32 v18, 16, v20
	v_add_f32_e32 v18, v10, v18
	v_and_b32_e32 v10, 0xffff0000, v20
	v_lshlrev_b32_e32 v23, 16, v19
	v_add_f32_e32 v19, v11, v10
	v_lshlrev_b32_e32 v10, 16, v21
	v_add_f32_e32 v20, v12, v10
	v_and_b32_e32 v10, 0xffff0000, v21
	v_add_f32_e32 v14, v14, v22
	v_add_f32_e32 v16, v16, v23
	v_add_f32_e32 v21, v13, v10
	v_cvt_pk_bf16_f32 v10, v14, v15
	v_cvt_pk_bf16_f32 v11, v16, v17
	v_cvt_pk_bf16_f32 v12, v18, v19
	v_cvt_pk_bf16_f32 v13, v20, v21
	ds_write_b128 v210, v[10:13]
	v_mul_f32_e32 v10, v15, v15
	v_mul_f32_e32 v11, v17, v17
	v_fmac_f32_e32 v10, v14, v14
	v_fmac_f32_e32 v11, v16, v16
	v_add_f32_e32 v14, v10, v11
	ds_read_b128 v[10:13], v210 offset:64
	v_mul_f32_e32 v15, v19, v19
	v_mul_f32_e32 v16, v21, v21
	v_fmac_f32_e32 v15, v18, v18
	v_fmac_f32_e32 v16, v20, v20
	v_add_f32_e32 v15, v15, v16
	v_add_f32_e32 v14, v14, v15
	s_waitcnt lgkmcnt(0)
	v_lshlrev_b32_e32 v15, 16, v10
	v_and_b32_e32 v10, 0xffff0000, v10
	v_add_f32_e32 v7, v7, v10
	v_lshlrev_b32_e32 v10, 16, v11
	v_add_f32_e32 v8, v8, v10
	v_and_b32_e32 v10, 0xffff0000, v11
	v_add_f32_e32 v9, v9, v10
	v_lshlrev_b32_e32 v10, 16, v12
	v_add_f32_e32 v10, v2, v10
	v_and_b32_e32 v2, 0xffff0000, v12
	v_add_f32_e32 v11, v3, v2
	v_lshlrev_b32_e32 v2, 16, v13
	v_add_f32_e32 v12, v4, v2
	v_and_b32_e32 v2, 0xffff0000, v13
	v_add_f32_e32 v6, v6, v15
	v_add_f32_e32 v13, v5, v2
	v_cvt_pk_bf16_f32 v2, v6, v7
	v_cvt_pk_bf16_f32 v3, v8, v9
	v_cvt_pk_bf16_f32 v4, v10, v11
	v_cvt_pk_bf16_f32 v5, v12, v13
	ds_write_b128 v210, v[2:5] offset:64
	v_mul_f32_e32 v2, v7, v7
	v_mul_f32_e32 v3, v9, v9
	v_fmac_f32_e32 v2, v6, v6
	v_fmac_f32_e32 v3, v8, v8
	v_add_f32_e32 v2, v2, v3
	v_mul_f32_e32 v3, v11, v11
	v_mul_f32_e32 v4, v13, v13
	v_fmac_f32_e32 v3, v10, v10
	v_fmac_f32_e32 v4, v12, v12
	v_add_f32_e32 v3, v3, v4
	v_add_f32_e32 v2, v2, v3
	v_add_f32_e32 v12, v14, v2
	ds_read_b128 v[2:5], v211
	v_lshl_add_u64 v[6:7], s[76:77], 0, v[90:91]
	v_lshl_add_u64 v[6:7], v[6:7], 0, s[46:47]
	v_lshl_add_u64 v[10:11], v[6:7], 0, v[0:1]
	ds_read_b128 v[6:9], v211 offset:1152
	s_waitcnt lgkmcnt(1)
	global_store_dwordx4 v[10:11], v[2:5], off nt
	s_nop 1
	v_lshl_add_u64 v[2:3], s[76:77], 0, v[96:97]
	v_lshl_add_u64 v[2:3], v[2:3], 0, s[46:47]
	v_lshl_add_u64 v[2:3], v[2:3], 0, v[0:1]
	s_waitcnt lgkmcnt(0)
	global_store_dwordx4 v[2:3], v[6:9], off nt
	v_mov_b32_e32 v2, v12
	s_nop 1
	v_permlane16_swap_b32_e32 v12, v2
	v_add_f32_e32 v2, v12, v2
	v_mov_b32_e32 v3, v2
	s_nop 1
	v_permlane32_swap_b32_e32 v2, v3
	s_and_saveexec_b64 s[46:47], s[34:35]
	s_cbranch_execz .LBB0_942
	s_add_u32 s14, s82, s44
	s_addc_u32 s15, s83, s45
	s_ashr_i32 s43, s42, 31
	v_lshl_add_u64 v[4:5], s[42:43], 0, v[174:175]
	v_lshl_add_u64 v[4:5], v[4:5], 2, s[14:15]
	v_add_f32_e32 v2, v2, v3
	global_store_dword v[4:5], v2, off offset:704

; __global__ void __launch_bounds__(NTHREADS, 2) fwd_megakernel(Params p) {
;     extern __shared__ __attribute__((aligned(16))) unsigned char lds_raw[];
	.amdhsa_kernel _Z14fwd_megakernel6Params
		.amdhsa_group_segment_fixed_size 0
		.amdhsa_private_segment_fixed_size 0
		.amdhsa_kernarg_size 376
		.amdhsa_user_sgpr_count 2
		.amdhsa_user_sgpr_dispatch_ptr 0
		.amdhsa_user_sgpr_queue_ptr 0
		.amdhsa_user_sgpr_kernarg_segment_ptr 1
		.amdhsa_user_sgpr_dispatch_id 0
		.amdhsa_user_sgpr_kernarg_preload_length 0
		.amdhsa_user_sgpr_kernarg_preload_offset 0
		.amdhsa_user_sgpr_private_segment_size 0
		.amdhsa_uses_dynamic_stack 0
		.amdhsa_enable_private_segment 0
		.amdhsa_system_sgpr_workgroup_id_x 1
		.amdhsa_system_sgpr_workgroup_id_y 0
		.amdhsa_system_sgpr_workgroup_id_z 0
		.amdhsa_system_sgpr_workgroup_info 0
		.amdhsa_system_vgpr_workitem_id 2
		.amdhsa_next_free_vgpr 256
		.amdhsa_next_free_sgpr 102
		.amdhsa_accum_offset 256
		.amdhsa_reserve_vcc 1
		.amdhsa_float_round_mode_32 0
		.amdhsa_float_round_mode_16_64 0
		.amdhsa_float_denorm_mode_32 3
		.amdhsa_float_denorm_mode_16_64 3
		.amdhsa_dx10_clamp 1
		.amdhsa_ieee_mode 1
		.amdhsa_fp16_overflow 0
		.amdhsa_tg_split 0
		.amdhsa_exception_fp_ieee_invalid_op 0
		.amdhsa_exception_fp_denorm_src 0
		.amdhsa_exception_fp_ieee_div_zero 0
		.amdhsa_exception_fp_ieee_overflow 0
		.amdhsa_exception_fp_ieee_underflow 0
		.amdhsa_exception_fp_ieee_inexact 0
		.amdhsa_exception_int_div_zero 0
	.end_amdhsa_kernel

; __global__ void __launch_bounds__(NTHREADS, 2) fwd_megakernel(Params p) {
;     extern __shared__ __attribute__((aligned(16))) unsigned char lds_raw[];
amdhsa.kernels:
  - .agpr_count:     0
    .args:
      - .offset:         0
        .size:           120
        .value_kind:     by_value
      - .offset:         120
        .size:           4
        .value_kind:     hidden_block_count_x
      - .offset:         124
        .size:           4
        .value_kind:     hidden_block_count_y
      - .offset:         128
        .size:           4
        .value_kind:     hidden_block_count_z
      - .offset:         132
        .size:           2
        .value_kind:     hidden_group_size_x
      - .offset:         134
        .size:           2
        .value_kind:     hidden_group_size_y
      - .offset:         136
        .size:           2
        .value_kind:     hidden_group_size_z
      - .offset:         138
        .size:           2
        .value_kind:     hidden_remainder_x
      - .offset:         140
        .size:           2
        .value_kind:     hidden_remainder_y
      - .offset:         142
        .size:           2
        .value_kind:     hidden_remainder_z
      - .offset:         160
        .size:           8
        .value_kind:     hidden_global_offset_x
      - .offset:         168
        .size:           8
        .value_kind:     hidden_global_offset_y
      - .offset:         176
        .size:           8
        .value_kind:     hidden_global_offset_z
      - .offset:         184
        .size:           2
        .value_kind:     hidden_grid_dims
      - .offset:         208
        .size:           8
        .value_kind:     hidden_multigrid_sync_arg
      - .offset:         240
        .size:           4
        .value_kind:     hidden_dynamic_lds_size
    .group_segment_fixed_size: 0
    .kernarg_segment_align: 8
    .kernarg_segment_size: 376
    .language:       OpenCL C
    .language_version:
      - 2
      - 0
    .max_flat_workgroup_size: 512
    .name:           _Z14fwd_megakernel6Params
    .private_segment_fixed_size: 0
    .sgpr_count:     108
    .sgpr_spill_count: 176
    .symbol:         _Z14fwd_megakernel6Params.kd
    .uniform_work_group_size: 1
    .uses_dynamic_stack: false
    .vgpr_count:     256
    .vgpr_spill_count: 0
    .wavefront_size: 64
